# p3/p4/p6 epilogue loops: both iterations' loads issued before iteration 1 (iteration 2 needs no wait, no store drain)
# speedup vs baseline: 1.0038x; 1.0038x over previous
; DEVI float sigmoidf_(float x) { return 1.f / (1.f + __expf(-x)); }
; DEVI void gate_tile(const Params& P, int l, int pm, int q, char* smem, int tid) {
;     ...
; #pragma unroll 4
;   for (int q = 0; q < 8; ++q) {
;     const int id = tid + 256 * q, row = id >> 4, g4 = id & 15;
;     const int cl = g4 * 4, wcc = cl >> 5, c32 = cl & 31;
;     const long grow = (long)pm * 128 + row;
;     const int col = nb * 128 + hb * 64 + cl;
;     float4 rp = *reinterpret_cast<const float4*>(T + row * 128 + wcc * 64 + c32);
;     float4 gp = *reinterpret_cast<const float4*>(T + row * 128 + wcc * 64 + 32 + c32);
;     float xv[4], bav[4], bxv[4], lmv[4];
;     load4bf(cb + grow * 1024 + col, xv);
;     ld4f(ba + col, bav); ld4f(bx + col, bxv); ld4f(lam + col, lmv);
;     const float rpa[4] = {rp.x, rp.y, rp.z, rp.w}, gpa[4] = {gp.x, gp.y, gp.z, gp.w};
;     float av[4], uv[4];
; #pragma unroll
;     for (int i = 0; i < 4; ++i) {
;       float r = sigmoidf_(rpa[i] + bav[i]);
;       float gi = sigmoidf_(gpa[i] + bxv[i]);
;       float a = __expf(-8.f * log1pf(__expf(-lmv[i])) * r);
;       av[i] = a;
;       uv[i] = sqrtf(fmaxf(1.f - a * a, 0.f)) * gi * xv[i];
.LBB0_459:
	s_cmp_lg_u32 s61, 0
	s_cbranch_scc1 .Leh2LBB0459b
	v_add_u32_e32 v173, s61, v20
	v_ashrrev_i32_e32 v170, 4, v173
	v_ashrrev_i32_e32 v171, 31, v170
	v_lshlrev_b64 v[170:171], 10, v[170:171]
	v_lshl_add_u64 v[174:175], v[170:171], 0, s[54:55]
	v_lshl_add_u64 v[170:171], v[174:175], 1, v[48:49]
	global_load_dwordx2 v[208:209], v[170:171], off
	global_load_dwordx4 v[212:215], v[50:51], off
	global_load_dwordx4 v[216:219], v[52:53], off
	global_load_dwordx4 v[220:223], v[54:55], off
	v_add_u32_e32 v175, s61, v20
	v_add_u32_e32 v170, 0x100, v175
	v_ashrrev_i32_e32 v172, 4, v170
	v_ashrrev_i32_e32 v173, 31, v172
	v_lshlrev_b64 v[172:173], 10, v[172:173]
	v_lshl_add_u64 v[176:177], v[172:173], 0, s[54:55]
	v_lshl_add_u64 v[172:173], v[176:177], 1, v[48:49]
	global_load_dwordx2 v[210:211], v[172:173], off
	v_add_u32_e32 v175, s61, v20
	v_add_u32_e32 v170, 0x200, v175
	v_ashrrev_i32_e32 v172, 4, v170
	v_ashrrev_i32_e32 v173, 31, v172
	v_lshlrev_b64 v[172:173], 10, v[172:173]
	v_lshl_add_u64 v[176:177], v[172:173], 0, s[54:55]
	v_lshl_add_u64 v[172:173], v[176:177], 1, v[48:49]
	global_load_dwordx2 v[224:225], v[172:173], off
	v_add_u32_e32 v175, s61, v20
	v_add_u32_e32 v170, 0x300, v175
	v_ashrrev_i32_e32 v172, 4, v170
	v_ashrrev_i32_e32 v173, 31, v172
	v_lshlrev_b64 v[172:173], 10, v[172:173]
	v_lshl_add_u64 v[176:177], v[172:173], 0, s[54:55]
	v_lshl_add_u64 v[172:173], v[176:177], 1, v[48:49]
	global_load_dwordx2 v[226:227], v[172:173], off
	v_add_u32_e32 v173, s61, v20
	v_add_u32_e32 v173, 0x400, v173
	v_ashrrev_i32_e32 v170, 4, v173
	v_ashrrev_i32_e32 v171, 31, v170
	v_lshlrev_b64 v[170:171], 10, v[170:171]
	v_lshl_add_u64 v[174:175], v[170:171], 0, s[54:55]
	v_lshl_add_u64 v[170:171], v[174:175], 1, v[48:49]
	global_load_dwordx2 v[228:229], v[170:171], off
	v_add_u32_e32 v175, s61, v20
	v_add_u32_e32 v175, 0x400, v175
	v_add_u32_e32 v170, 0x100, v175
	v_ashrrev_i32_e32 v172, 4, v170
	v_ashrrev_i32_e32 v173, 31, v172
	v_lshlrev_b64 v[172:173], 10, v[172:173]
	v_lshl_add_u64 v[176:177], v[172:173], 0, s[54:55]
	v_lshl_add_u64 v[172:173], v[176:177], 1, v[48:49]
	global_load_dwordx2 v[230:231], v[172:173], off
	v_add_u32_e32 v175, s61, v20
	v_add_u32_e32 v175, 0x400, v175
	v_add_u32_e32 v170, 0x200, v175
	v_ashrrev_i32_e32 v172, 4, v170
	v_ashrrev_i32_e32 v173, 31, v172
	v_lshlrev_b64 v[172:173], 10, v[172:173]
	v_lshl_add_u64 v[176:177], v[172:173], 0, s[54:55]
	v_lshl_add_u64 v[172:173], v[176:177], 1, v[48:49]
	global_load_dwordx2 v[232:233], v[172:173], off
	v_add_u32_e32 v175, s61, v20
	v_add_u32_e32 v175, 0x400, v175
	v_add_u32_e32 v170, 0x300, v175
	v_ashrrev_i32_e32 v172, 4, v170
	v_ashrrev_i32_e32 v173, 31, v172
	v_lshlrev_b64 v[172:173], 10, v[172:173]
	v_lshl_add_u64 v[176:177], v[172:173], 0, s[54:55]
	v_lshl_add_u64 v[172:173], v[176:177], 1, v[48:49]
	global_load_dwordx2 v[234:235], v[172:173], off
	s_waitcnt vmcnt(0)
	s_branch .Leh2LBB0459c
.Leh2LBB0459b:
	v_mov_b32_e32 v208, v228
	v_mov_b32_e32 v209, v229
	v_mov_b32_e32 v210, v230
	v_mov_b32_e32 v211, v231
	v_mov_b32_e32 v224, v232
	v_mov_b32_e32 v225, v233
	v_mov_b32_e32 v226, v234
	v_mov_b32_e32 v227, v235
.Leh2LBB0459c:
	v_add_u32_e32 v41, s61, v20
	v_ashrrev_i32_e32 v8, 4, v41
	v_ashrrev_i32_e32 v9, 31, v8
	v_lshl_or_b32 v43, v8, 9, v112
	v_lshlrev_b64 v[8:9], 10, v[8:9]
	v_lshl_add_u64 v[100:101], v[8:9], 0, s[54:55]
	v_lshl_add_u64 v[8:9], v[100:101], 1, v[48:49]
	ds_read_b128 v[4:7], v43
	ds_read_b128 v[0:3], v43 offset:128
	v_mov_b32_e32 v8, v208
	v_mov_b32_e32 v9, v209
	s_addk_i32 s61, 0x400
	s_cmpk_eq_i32 s61, 0x800
	v_lshlrev_b32_e32 v62, 16, v8
	v_and_b32_e32 v63, 0xffff0000, v8
	v_lshlrev_b32_e32 v60, 16, v9
	v_and_b32_e32 v61, 0xffff0000, v9
	v_mov_b32_e32 v16, v212
	v_mov_b32_e32 v17, v213
	v_mov_b32_e32 v18, v214
	v_mov_b32_e32 v19, v215
	v_mov_b32_e32 v12, v216
	v_mov_b32_e32 v13, v217
	v_mov_b32_e32 v14, v218
	v_mov_b32_e32 v15, v219
	v_mov_b32_e32 v8, v220
	v_mov_b32_e32 v9, v221
	v_mov_b32_e32 v10, v222
	v_mov_b32_e32 v11, v223
	s_waitcnt lgkmcnt(1)
	v_add_f32_e32 v4, v4, v16
	v_mul_f32_e32 v4, 0xbfb8aa3b, v4
	v_exp_f32_e32 v4, v4
	s_waitcnt lgkmcnt(0)
	v_add_f32_e32 v0, v0, v12
	v_mul_f32_e32 v0, 0xbfb8aa3b, v0
	v_add_f32_e32 v5, v5, v17
	v_add_f32_e32 v4, 1.0, v4
	v_div_scale_f32 v16, s[46:47], v4, v4, 1.0
	v_rcp_f32_e32 v45, v16
	v_mul_f32_e32 v5, 0xbfb8aa3b, v5
	v_exp_f32_e32 v5, v5
	v_add_f32_e32 v1, v1, v13
	v_fma_f32 v47, -v16, v45, 1.0
	v_fmac_f32_e32 v45, v47, v45
	v_div_scale_f32 v47, vcc, 1.0, v4, 1.0
	v_mul_f32_e32 v113, v47, v45
	v_fma_f32 v114, -v16, v113, v47
	v_fmac_f32_e32 v113, v114, v45
	v_fma_f32 v16, -v16, v113, v47
	v_div_fmas_f32 v16, v16, v45, v113
	v_div_fixup_f32 v16, v16, v4, 1.0
	v_exp_f32_e32 v4, v0
	v_add_f32_e32 v5, 1.0, v5
	v_mul_f32_e32 v1, 0xbfb8aa3b, v1
	v_add_f32_e32 v6, v6, v18
	v_mul_f32_e32 v6, 0xbfb8aa3b, v6
	v_exp_f32_e32 v6, v6
	s_nop 0
	v_add_f32_e32 v6, 1.0, v6
	v_add_f32_e32 v2, v2, v14
	v_mul_f32_e32 v2, 0xbfb8aa3b, v2
	v_add_f32_e32 v7, v7, v19
	v_mul_f32_e32 v7, 0xbfb8aa3b, v7
	v_exp_f32_e32 v7, v7
	v_mov_b32_e32 v0, v240
	v_mul_f32_e32 v0, v16, v0
	v_mul_f32_e32 v0, 0x3fb8aa3b, v0
	v_exp_f32_e32 v0, v0
	v_add_f32_e32 v7, 1.0, v7
	v_add_f32_e32 v3, v3, v15
	v_mul_f32_e32 v3, 0xbfb8aa3b, v3
	v_fma_f32 v8, -v0, v0, 1.0
	v_max_f32_e32 v8, 0, v8
	v_cmp_gt_f32_e32 vcc, s69, v8
	v_mul_f32_e32 v12, 0x4f800000, v8
	s_nop 0
	v_cndmask_b32_e32 v8, v8, v12, vcc
	v_sqrt_f32_e32 v12, v8
	s_nop 0
	v_add_u32_e32 v16, -1, v12
	v_fma_f32 v45, -v16, v12, v8
	v_cmp_ge_f32_e64 s[46:47], 0, v45
	v_add_u32_e32 v45, 1, v12
	s_nop 0
	v_cndmask_b32_e64 v16, v12, v16, s[46:47]
	v_fma_f32 v12, -v45, v12, v8
; DEVI float sigmoidf_(float x) { return 1.f / (1.f + __expf(-x)); }
; DEVI void gate_tile(const Params& P, int l, int pm, int q, char* smem, int tid) {
;     ...
; #pragma unroll
;     for (int i = 0; i < 4; ++i) {
;       float r = sigmoidf_(rpa[i] + bav[i]);
;       float gi = sigmoidf_(gpa[i] + bxv[i]);
;       float a = __expf(-8.f * log1pf(__expf(-lmv[i])) * r);
;       av[i] = a;
;       uv[i] = sqrtf(fmaxf(1.f - a * a, 0.f)) * gi * xv[i];
;     }
;     *reinterpret_cast<float4*>(au0 + grow * 1024 + col) = make_float4(av[0], av[1], av[2], av[3]);
;     *reinterpret_cast<float4*>(au1 + grow * 1024 + col) = make_float4(uv[0], uv[1], uv[2], uv[3]);
;     *reinterpret_cast<float4*>(Tw + row * 128 + wcc * 64 + c32) = make_float4(av[0], av[1], av[2], av[3]);
;     *reinterpret_cast<float4*>(Tw + row * 128 + wcc * 64 + 32 + c32) = make_float4(uv[0], uv[1], uv[2], uv[3]);
	v_cmp_lt_f32_e64 s[46:47], 0, v12
	s_nop 1
	v_cndmask_b32_e64 v12, v16, v45, s[46:47]
	v_mul_f32_e32 v16, 0x37800000, v12
	v_cndmask_b32_e32 v12, v12, v16, vcc
	v_cmp_class_f32_e32 vcc, v8, v186
	s_nop 1
	v_cndmask_b32_e32 v8, v12, v8, vcc
	v_div_scale_f32 v12, s[46:47], v5, v5, 1.0
	v_rcp_f32_e32 v16, v12
	s_nop 0
	v_fma_f32 v17, -v12, v16, 1.0
	v_fmac_f32_e32 v16, v17, v16
	v_div_scale_f32 v17, vcc, 1.0, v5, 1.0
	v_mul_f32_e32 v45, v17, v16
	v_fma_f32 v47, -v12, v45, v17
	v_fmac_f32_e32 v45, v47, v16
	v_fma_f32 v12, -v12, v45, v17
	v_div_fmas_f32 v12, v12, v16, v45
	v_div_fixup_f32 v16, v12, v5, 1.0
	v_exp_f32_e32 v5, v1
	s_nop 0
	v_pk_add_f32 v[4:5], v[4:5], 1.0 op_sel_hi:[1,0]
	s_nop 1
	s_nop 1
	s_nop 1
	v_mov_b32_e32 v1, v241
	v_mul_f32_e32 v1, v16, v1
	v_mul_f32_e32 v1, 0x3fb8aa3b, v1
	v_exp_f32_e32 v1, v1
	s_nop 0
	v_fma_f32 v9, -v1, v1, 1.0
	v_max_f32_e32 v9, 0, v9
	v_cmp_gt_f32_e32 vcc, s69, v9
	v_mul_f32_e32 v12, 0x4f800000, v9
	s_nop 0
	v_cndmask_b32_e32 v9, v9, v12, vcc
	v_sqrt_f32_e32 v12, v9
	s_nop 0
	v_add_u32_e32 v13, -1, v12
	v_fma_f32 v16, -v13, v12, v9
	v_cmp_ge_f32_e64 s[46:47], 0, v16
	v_add_u32_e32 v16, 1, v12
	s_nop 0
	v_cndmask_b32_e64 v13, v12, v13, s[46:47]
	v_fma_f32 v12, -v16, v12, v9
	v_cmp_lt_f32_e64 s[46:47], 0, v12
	s_nop 1
	v_cndmask_b32_e64 v12, v13, v16, s[46:47]
	v_mul_f32_e32 v13, 0x37800000, v12
	v_cndmask_b32_e32 v12, v12, v13, vcc
	v_cmp_class_f32_e32 vcc, v9, v186
	s_nop 1
	v_cndmask_b32_e32 v9, v12, v9, vcc
	v_div_scale_f32 v12, s[46:47], v6, v6, 1.0
	v_rcp_f32_e32 v13, v12
	s_nop 0
	v_fma_f32 v16, -v12, v13, 1.0
	v_fmac_f32_e32 v13, v16, v13
	v_div_scale_f32 v16, vcc, 1.0, v6, 1.0
	v_mul_f32_e32 v17, v16, v13
	v_fma_f32 v18, -v12, v17, v16
	v_fmac_f32_e32 v17, v18, v13
	v_fma_f32 v12, -v12, v17, v16
	v_div_fmas_f32 v12, v12, v13, v17
	v_div_fixup_f32 v16, v12, v6, 1.0
	v_exp_f32_e32 v6, v2
	s_nop 0
	s_nop 1
	s_nop 1
	s_nop 1
	v_mov_b32_e32 v2, v242
	v_mul_f32_e32 v2, v16, v2
	v_mul_f32_e32 v2, 0x3fb8aa3b, v2
	v_exp_f32_e32 v2, v2
	s_nop 0
	v_fma_f32 v10, -v2, v2, 1.0
	v_max_f32_e32 v10, 0, v10
	v_cmp_gt_f32_e32 vcc, s69, v10
	v_mul_f32_e32 v12, 0x4f800000, v10
	s_nop 0
	v_cndmask_b32_e32 v10, v10, v12, vcc
	v_sqrt_f32_e32 v12, v10
	s_nop 0
	v_add_u32_e32 v13, -1, v12
	v_fma_f32 v14, -v13, v12, v10
	v_cmp_ge_f32_e64 s[46:47], 0, v14
	v_add_u32_e32 v14, 1, v12
	s_nop 0
	v_cndmask_b32_e64 v13, v12, v13, s[46:47]
	v_fma_f32 v12, -v14, v12, v10
	v_cmp_lt_f32_e64 s[46:47], 0, v12
	s_nop 1
	v_cndmask_b32_e64 v12, v13, v14, s[46:47]
	v_mul_f32_e32 v13, 0x37800000, v12
	v_cndmask_b32_e32 v12, v12, v13, vcc
	v_cmp_class_f32_e32 vcc, v10, v186
	s_nop 1
	v_cndmask_b32_e32 v10, v12, v10, vcc
	v_div_scale_f32 v12, s[46:47], v7, v7, 1.0
	v_rcp_f32_e32 v13, v12
	s_nop 0
	v_fma_f32 v14, -v12, v13, 1.0
	v_fmac_f32_e32 v13, v14, v13
	v_div_scale_f32 v14, vcc, 1.0, v7, 1.0
	v_mul_f32_e32 v16, v14, v13
	v_fma_f32 v17, -v12, v16, v14
	v_fmac_f32_e32 v16, v17, v13
	v_fma_f32 v12, -v12, v16, v14
	v_div_fmas_f32 v12, v12, v13, v16
	v_div_fixup_f32 v14, v12, v7, 1.0
	v_exp_f32_e32 v7, v3
	s_nop 0
	v_pk_add_f32 v[6:7], v[6:7], 1.0 op_sel_hi:[1,0]
	s_nop 1
	s_nop 1
	s_nop 1
	v_mov_b32_e32 v3, v243
	v_mul_f32_e32 v3, v14, v3
	v_mul_f32_e32 v3, 0x3fb8aa3b, v3
	v_exp_f32_e32 v3, v3
	s_nop 0
	v_fma_f32 v11, -v3, v3, 1.0
	v_max_f32_e32 v11, 0, v11
	v_cmp_gt_f32_e32 vcc, s69, v11
	v_mul_f32_e32 v12, 0x4f800000, v11
	s_nop 0
	v_cndmask_b32_e32 v11, v11, v12, vcc
	v_sqrt_f32_e32 v12, v11
	s_nop 0
	v_add_u32_e32 v13, -1, v12
	v_fma_f32 v14, -v13, v12, v11
	v_cmp_ge_f32_e64 s[46:47], 0, v14
	v_add_u32_e32 v14, 1, v12
	s_nop 0
	v_cndmask_b32_e64 v13, v12, v13, s[46:47]
	v_fma_f32 v12, -v14, v12, v11
	v_cmp_lt_f32_e64 s[46:47], 0, v12
	s_nop 1
	v_cndmask_b32_e64 v12, v13, v14, s[46:47]
	v_mul_f32_e32 v13, 0x37800000, v12
	v_cndmask_b32_e32 v12, v12, v13, vcc
	v_cmp_class_f32_e32 vcc, v11, v186
	s_nop 1
	v_cndmask_b32_e32 v11, v12, v11, vcc
	v_lshlrev_b64 v[12:13], 2, v[100:101]
	v_lshl_add_u64 v[14:15], v[56:57], 0, v[12:13]
	global_store_dwordx4 v[14:15], v[0:3], off
	v_div_scale_f32 v14, s[46:47], v5, v5, 1.0
	v_rcp_f32_e32 v15, v14
	v_lshl_add_u64 v[12:13], v[58:59], 0, v[12:13]
	v_fma_f32 v16, -v14, v15, 1.0
	v_fmac_f32_e32 v15, v16, v15
	v_div_scale_f32 v16, vcc, 1.0, v5, 1.0
	v_mul_f32_e32 v17, v16, v15
	v_fma_f32 v18, -v14, v17, v16
	v_fmac_f32_e32 v17, v18, v15
	v_fma_f32 v14, -v14, v17, v16
	v_div_fmas_f32 v14, v14, v15, v17
	v_div_fixup_f32 v5, v14, v5, 1.0
	v_div_scale_f32 v14, s[46:47], v4, v4, 1.0
	v_rcp_f32_e32 v15, v14
	s_nop 0
	v_fma_f32 v16, -v14, v15, 1.0
	v_fmac_f32_e32 v15, v16, v15
	v_div_scale_f32 v16, vcc, 1.0, v4, 1.0
	v_mul_f32_e32 v17, v16, v15
	v_fma_f32 v18, -v14, v17, v16
	v_fmac_f32_e32 v17, v18, v15
	v_fma_f32 v14, -v14, v17, v16
	v_div_fmas_f32 v14, v14, v15, v17
	v_div_fixup_f32 v4, v14, v4, 1.0
	v_pk_mul_f32 v[4:5], v[4:5], v[8:9]
	v_div_scale_f32 v8, s[46:47], v7, v7, 1.0
	v_rcp_f32_e32 v9, v8
	v_pk_mul_f32 v[4:5], v[4:5], v[62:63]
	v_fma_f32 v14, -v8, v9, 1.0
	v_fmac_f32_e32 v9, v14, v9
	v_div_scale_f32 v14, vcc, 1.0, v7, 1.0
	v_mul_f32_e32 v15, v14, v9
	v_fma_f32 v16, -v8, v15, v14
	v_fmac_f32_e32 v15, v16, v9
	v_fma_f32 v8, -v8, v15, v14
	v_div_fmas_f32 v8, v8, v9, v15
	v_div_fixup_f32 v7, v8, v7, 1.0
	v_div_scale_f32 v8, s[46:47], v6, v6, 1.0
	v_rcp_f32_e32 v9, v8
	s_nop 0
	v_fma_f32 v14, -v8, v9, 1.0
	v_fmac_f32_e32 v9, v14, v9
	v_div_scale_f32 v14, vcc, 1.0, v6, 1.0
	v_mul_f32_e32 v15, v14, v9
	v_fma_f32 v16, -v8, v15, v14
	v_fmac_f32_e32 v15, v16, v9
	v_fma_f32 v8, -v8, v15, v14
	v_div_fmas_f32 v8, v8, v9, v15
	v_div_fixup_f32 v6, v8, v6, 1.0
	v_pk_mul_f32 v[6:7], v[6:7], v[10:11]
	s_nop 0
	v_pk_mul_f32 v[6:7], v[6:7], v[60:61]
	global_store_dwordx4 v[12:13], v[4:7], off
	ds_write_b128 v43, v[0:3]
	ds_write_b128 v43, v[4:7] offset:128
	v_add_u32_e32 v0, 0x100, v41
	v_ashrrev_i32_e32 v4, 4, v0
	v_ashrrev_i32_e32 v5, 31, v4
	v_lshl_or_b32 v43, v4, 9, v112
	v_lshlrev_b64 v[4:5], 10, v[4:5]
	v_lshl_add_u64 v[100:101], v[4:5], 0, s[54:55]
	v_lshl_add_u64 v[4:5], v[100:101], 1, v[48:49]
	ds_read_b128 v[12:15], v43
	ds_read_b128 v[0:3], v43 offset:128
	v_mov_b32_e32 v4, v210
	v_mov_b32_e32 v5, v211
	v_lshlrev_b32_e32 v62, 16, v4
	v_and_b32_e32 v63, 0xffff0000, v4
	v_lshlrev_b32_e32 v60, 16, v5
	v_and_b32_e32 v61, 0xffff0000, v5
	v_mov_b32_e32 v16, v212
	v_mov_b32_e32 v17, v213
	v_mov_b32_e32 v18, v214
	v_mov_b32_e32 v19, v215
	v_mov_b32_e32 v8, v216
	v_mov_b32_e32 v9, v217
	v_mov_b32_e32 v10, v218
	v_mov_b32_e32 v11, v219
	v_mov_b32_e32 v4, v220
	v_mov_b32_e32 v5, v221
	v_mov_b32_e32 v6, v222
	v_mov_b32_e32 v7, v223
	s_waitcnt lgkmcnt(1)
; DEVI float sigmoidf_(float x) { return 1.f / (1.f + __expf(-x)); }
; DEVI void gate_tile(const Params& P, int l, int pm, int q, char* smem, int tid) {
;     ...
; #pragma unroll
;     for (int i = 0; i < 4; ++i) {
;       float r = sigmoidf_(rpa[i] + bav[i]);
;       float gi = sigmoidf_(gpa[i] + bxv[i]);
;       float a = __expf(-8.f * log1pf(__expf(-lmv[i])) * r);
;       av[i] = a;
;       uv[i] = sqrtf(fmaxf(1.f - a * a, 0.f)) * gi * xv[i];
;     }
;     *reinterpret_cast<float4*>(au0 + grow * 1024 + col) = make_float4(av[0], av[1], av[2], av[3]);
;     *reinterpret_cast<float4*>(au1 + grow * 1024 + col) = make_float4(uv[0], uv[1], uv[2], uv[3]);
	v_add_f32_e32 v12, v12, v16
	v_mul_f32_e32 v12, 0xbfb8aa3b, v12
	v_exp_f32_e32 v12, v12
	s_waitcnt lgkmcnt(0)
	v_add_f32_e32 v0, v0, v8
	v_mul_f32_e32 v0, 0xbfb8aa3b, v0
	v_exp_f32_e32 v8, v0
	v_add_f32_e32 v12, 1.0, v12
	v_div_scale_f32 v16, s[46:47], v12, v12, 1.0
	v_rcp_f32_e32 v45, v16
	v_add_f32_e32 v1, v1, v9
	v_fma_f32 v47, -v16, v45, 1.0
	v_fmac_f32_e32 v45, v47, v45
	v_div_scale_f32 v47, vcc, 1.0, v12, 1.0
	v_mul_f32_e32 v113, v47, v45
	v_fma_f32 v114, -v16, v113, v47
	v_fmac_f32_e32 v113, v114, v45
	v_fma_f32 v16, -v16, v113, v47
	v_div_fmas_f32 v16, v16, v45, v113
	v_div_fixup_f32 v12, v16, v12, 1.0
	v_mul_f32_e32 v1, 0xbfb8aa3b, v1
	v_exp_f32_e32 v9, v1
	v_add_f32_e32 v2, v2, v10
	v_mul_f32_e32 v2, 0xbfb8aa3b, v2
	v_exp_f32_e32 v10, v2
	v_mov_b32_e32 v0, v240
	v_mul_f32_e32 v0, v12, v0
	v_mul_f32_e32 v0, 0x3fb8aa3b, v0
	v_exp_f32_e32 v0, v0
	v_add_f32_e32 v3, v3, v11
	v_fma_f32 v4, -v0, v0, 1.0
	v_max_f32_e32 v4, 0, v4
	v_cmp_gt_f32_e32 vcc, s69, v4
	v_mul_f32_e32 v12, 0x4f800000, v4
	s_nop 0
	v_cndmask_b32_e32 v4, v4, v12, vcc
	v_sqrt_f32_e32 v12, v4
	v_mul_f32_e32 v3, 0xbfb8aa3b, v3
	v_exp_f32_e32 v11, v3
	v_add_u32_e32 v16, -1, v12
	v_fma_f32 v45, -v16, v12, v4
	v_cmp_ge_f32_e64 s[46:47], 0, v45
	v_add_u32_e32 v45, 1, v12
	s_nop 0
	v_cndmask_b32_e64 v16, v12, v16, s[46:47]
	v_fma_f32 v12, -v45, v12, v4
	v_cmp_lt_f32_e64 s[46:47], 0, v12
	v_pk_add_f32 v[8:9], v[8:9], 1.0 op_sel_hi:[1,0]
	s_nop 0
	v_cndmask_b32_e64 v12, v16, v45, s[46:47]
	v_mul_f32_e32 v16, 0x37800000, v12
	v_cndmask_b32_e32 v12, v12, v16, vcc
	v_cmp_class_f32_e32 vcc, v4, v186
	s_nop 1
	v_cndmask_b32_e32 v4, v12, v4, vcc
	v_add_f32_e32 v12, v13, v17
	v_mul_f32_e32 v12, 0xbfb8aa3b, v12
	v_exp_f32_e32 v12, v12
	s_nop 0
	v_add_f32_e32 v12, 1.0, v12
	v_div_scale_f32 v13, s[46:47], v12, v12, 1.0
	v_rcp_f32_e32 v16, v13
	s_nop 0
	v_fma_f32 v17, -v13, v16, 1.0
	v_fmac_f32_e32 v16, v17, v16
	v_div_scale_f32 v17, vcc, 1.0, v12, 1.0
	v_mul_f32_e32 v45, v17, v16
	v_fma_f32 v47, -v13, v45, v17
	v_fmac_f32_e32 v45, v47, v16
	v_fma_f32 v13, -v13, v45, v17
	v_div_fmas_f32 v13, v13, v16, v45
	v_div_fixup_f32 v16, v13, v12, 1.0
	s_nop 1
	s_nop 1
	s_nop 1
	v_mov_b32_e32 v1, v241
	v_mul_f32_e32 v1, v16, v1
	v_mul_f32_e32 v1, 0x3fb8aa3b, v1
	v_exp_f32_e32 v1, v1
	s_nop 0
	v_fma_f32 v5, -v1, v1, 1.0
	v_max_f32_e32 v5, 0, v5
	v_cmp_gt_f32_e32 vcc, s69, v5
	v_mul_f32_e32 v12, 0x4f800000, v5
	s_nop 0
	v_cndmask_b32_e32 v5, v5, v12, vcc
	v_sqrt_f32_e32 v12, v5
	s_nop 0
	v_add_u32_e32 v13, -1, v12
	v_fma_f32 v16, -v13, v12, v5
	v_cmp_ge_f32_e64 s[46:47], 0, v16
	v_add_u32_e32 v16, 1, v12
	s_nop 0
	v_cndmask_b32_e64 v13, v12, v13, s[46:47]
	v_fma_f32 v12, -v16, v12, v5
	v_cmp_lt_f32_e64 s[46:47], 0, v12
	s_nop 1
	v_cndmask_b32_e64 v12, v13, v16, s[46:47]
	v_mul_f32_e32 v13, 0x37800000, v12
	v_cndmask_b32_e32 v12, v12, v13, vcc
	v_cmp_class_f32_e32 vcc, v5, v186
	s_nop 1
	v_cndmask_b32_e32 v5, v12, v5, vcc
	v_add_f32_e32 v12, v14, v18
	v_mul_f32_e32 v12, 0xbfb8aa3b, v12
	v_exp_f32_e32 v12, v12
	s_nop 0
	v_add_f32_e32 v12, 1.0, v12
	v_div_scale_f32 v13, s[46:47], v12, v12, 1.0
	v_rcp_f32_e32 v14, v13
	s_nop 0
	v_fma_f32 v16, -v13, v14, 1.0
	v_fmac_f32_e32 v14, v16, v14
	v_div_scale_f32 v16, vcc, 1.0, v12, 1.0
	v_mul_f32_e32 v17, v16, v14
	v_fma_f32 v18, -v13, v17, v16
	v_fmac_f32_e32 v17, v18, v14
	v_fma_f32 v13, -v13, v17, v16
	v_div_fmas_f32 v13, v13, v14, v17
	v_div_fixup_f32 v14, v13, v12, 1.0
	s_nop 1
	s_nop 1
	s_nop 1
	v_mov_b32_e32 v2, v242
	v_mul_f32_e32 v2, v14, v2
	v_mul_f32_e32 v2, 0x3fb8aa3b, v2
	v_exp_f32_e32 v2, v2
	s_nop 0
	v_fma_f32 v6, -v2, v2, 1.0
	v_max_f32_e32 v6, 0, v6
	v_cmp_gt_f32_e32 vcc, s69, v6
	v_mul_f32_e32 v12, 0x4f800000, v6
	s_nop 0
	v_cndmask_b32_e32 v6, v6, v12, vcc
	v_sqrt_f32_e32 v12, v6
	s_nop 0
	v_add_u32_e32 v13, -1, v12
	v_fma_f32 v14, -v13, v12, v6
	v_cmp_ge_f32_e64 s[46:47], 0, v14
	v_add_u32_e32 v14, 1, v12
	s_nop 0
	v_cndmask_b32_e64 v13, v12, v13, s[46:47]
	v_fma_f32 v12, -v14, v12, v6
	v_cmp_lt_f32_e64 s[46:47], 0, v12
	s_nop 1
	v_cndmask_b32_e64 v12, v13, v14, s[46:47]
	v_mul_f32_e32 v13, 0x37800000, v12
	v_cndmask_b32_e32 v12, v12, v13, vcc
	v_cmp_class_f32_e32 vcc, v6, v186
	s_nop 1
	v_cndmask_b32_e32 v6, v12, v6, vcc
	v_add_f32_e32 v12, v15, v19
	v_mul_f32_e32 v12, 0xbfb8aa3b, v12
	v_exp_f32_e32 v12, v12
	s_nop 0
	v_add_f32_e32 v12, 1.0, v12
	v_div_scale_f32 v13, s[46:47], v12, v12, 1.0
	v_rcp_f32_e32 v14, v13
	s_nop 0
	v_fma_f32 v15, -v13, v14, 1.0
	v_fmac_f32_e32 v14, v15, v14
	v_div_scale_f32 v15, vcc, 1.0, v12, 1.0
	v_mul_f32_e32 v16, v15, v14
	v_fma_f32 v17, -v13, v16, v15
	v_fmac_f32_e32 v16, v17, v14
	v_fma_f32 v13, -v13, v16, v15
	v_div_fmas_f32 v13, v13, v14, v16
	v_div_fixup_f32 v14, v13, v12, 1.0
	s_nop 1
	s_nop 1
	s_nop 1
	v_mov_b32_e32 v3, v243
	v_mul_f32_e32 v3, v14, v3
	v_mul_f32_e32 v3, 0x3fb8aa3b, v3
	v_exp_f32_e32 v3, v3
	s_nop 0
	v_fma_f32 v7, -v3, v3, 1.0
	v_max_f32_e32 v7, 0, v7
	v_cmp_gt_f32_e32 vcc, s69, v7
	v_mul_f32_e32 v12, 0x4f800000, v7
	s_nop 0
	v_cndmask_b32_e32 v7, v7, v12, vcc
	v_sqrt_f32_e32 v12, v7
	s_nop 0
	v_add_u32_e32 v13, -1, v12
	v_fma_f32 v14, -v13, v12, v7
	v_cmp_ge_f32_e64 s[46:47], 0, v14
	v_add_u32_e32 v14, 1, v12
	s_nop 0
	v_cndmask_b32_e64 v13, v12, v13, s[46:47]
	v_fma_f32 v12, -v14, v12, v7
	v_cmp_lt_f32_e64 s[46:47], 0, v12
	s_nop 1
	v_cndmask_b32_e64 v12, v13, v14, s[46:47]
	v_mul_f32_e32 v13, 0x37800000, v12
	v_cndmask_b32_e32 v12, v12, v13, vcc
	v_cmp_class_f32_e32 vcc, v7, v186
	s_nop 1
	v_cndmask_b32_e32 v7, v12, v7, vcc
	v_lshlrev_b64 v[12:13], 2, v[100:101]
	v_lshl_add_u64 v[14:15], v[56:57], 0, v[12:13]
	global_store_dwordx4 v[14:15], v[0:3], off
	v_div_scale_f32 v14, s[46:47], v9, v9, 1.0
; DEVI float sigmoidf_(float x) { return 1.f / (1.f + __expf(-x)); }
; DEVI void gate_tile(const Params& P, int l, int pm, int q, char* smem, int tid) {
;     ...
; #pragma unroll
;     for (int i = 0; i < 4; ++i) {
;       float r = sigmoidf_(rpa[i] + bav[i]);
;       float gi = sigmoidf_(gpa[i] + bxv[i]);
;       float a = __expf(-8.f * log1pf(__expf(-lmv[i])) * r);
;       av[i] = a;
;       uv[i] = sqrtf(fmaxf(1.f - a * a, 0.f)) * gi * xv[i];
;     }
;     *reinterpret_cast<float4*>(au0 + grow * 1024 + col) = make_float4(av[0], av[1], av[2], av[3]);
;     *reinterpret_cast<float4*>(au1 + grow * 1024 + col) = make_float4(uv[0], uv[1], uv[2], uv[3]);
;     *reinterpret_cast<float4*>(Tw + row * 128 + wcc * 64 + c32) = make_float4(av[0], av[1], av[2], av[3]);
;     *reinterpret_cast<float4*>(Tw + row * 128 + wcc * 64 + 32 + c32) = make_float4(uv[0], uv[1], uv[2], uv[3]);
	v_rcp_f32_e32 v15, v14
	v_lshl_add_u64 v[12:13], v[58:59], 0, v[12:13]
	v_fma_f32 v16, -v14, v15, 1.0
	v_fmac_f32_e32 v15, v16, v15
	v_div_scale_f32 v16, vcc, 1.0, v9, 1.0
	v_mul_f32_e32 v17, v16, v15
	v_fma_f32 v18, -v14, v17, v16
	v_fmac_f32_e32 v17, v18, v15
	v_fma_f32 v14, -v14, v17, v16
	v_div_fmas_f32 v14, v14, v15, v17
	v_div_fixup_f32 v9, v14, v9, 1.0
	v_div_scale_f32 v14, s[46:47], v8, v8, 1.0
	v_rcp_f32_e32 v15, v14
	s_nop 0
	v_fma_f32 v16, -v14, v15, 1.0
	v_fmac_f32_e32 v15, v16, v15
	v_div_scale_f32 v16, vcc, 1.0, v8, 1.0
	v_mul_f32_e32 v17, v16, v15
	v_fma_f32 v18, -v14, v17, v16
	v_fmac_f32_e32 v17, v18, v15
	v_fma_f32 v14, -v14, v17, v16
	v_div_fmas_f32 v14, v14, v15, v17
	v_div_fixup_f32 v8, v14, v8, 1.0
	v_pk_mul_f32 v[4:5], v[8:9], v[4:5]
	v_pk_add_f32 v[8:9], v[10:11], 1.0 op_sel_hi:[1,0]
	v_pk_mul_f32 v[4:5], v[4:5], v[62:63]
	v_div_scale_f32 v10, s[46:47], v9, v9, 1.0
	v_rcp_f32_e32 v11, v10
	s_nop 0
	v_fma_f32 v14, -v10, v11, 1.0
	v_fmac_f32_e32 v11, v14, v11
	v_div_scale_f32 v14, vcc, 1.0, v9, 1.0
	v_mul_f32_e32 v15, v14, v11
	v_fma_f32 v16, -v10, v15, v14
	v_fmac_f32_e32 v15, v16, v11
	v_fma_f32 v10, -v10, v15, v14
	v_div_fmas_f32 v10, v10, v11, v15
	v_div_fixup_f32 v9, v10, v9, 1.0
	v_div_scale_f32 v10, s[46:47], v8, v8, 1.0
	v_rcp_f32_e32 v11, v10
	s_nop 0
	v_fma_f32 v14, -v10, v11, 1.0
	v_fmac_f32_e32 v11, v14, v11
	v_div_scale_f32 v14, vcc, 1.0, v8, 1.0
	v_mul_f32_e32 v15, v14, v11
	v_fma_f32 v16, -v10, v15, v14
	v_fmac_f32_e32 v15, v16, v11
	v_fma_f32 v10, -v10, v15, v14
	v_div_fmas_f32 v10, v10, v11, v15
	v_div_fixup_f32 v8, v10, v8, 1.0
	v_pk_mul_f32 v[6:7], v[8:9], v[6:7]
	s_nop 0
	v_pk_mul_f32 v[6:7], v[6:7], v[60:61]
	global_store_dwordx4 v[12:13], v[4:7], off
	ds_write_b128 v43, v[0:3]
	ds_write_b128 v43, v[4:7] offset:128
	v_add_u32_e32 v0, 0x200, v41
	v_ashrrev_i32_e32 v4, 4, v0
	v_ashrrev_i32_e32 v5, 31, v4
	v_lshl_or_b32 v43, v4, 9, v112
	v_lshlrev_b64 v[4:5], 10, v[4:5]
	v_lshl_add_u64 v[100:101], v[4:5], 0, s[54:55]
	v_lshl_add_u64 v[4:5], v[100:101], 1, v[48:49]
	ds_read_b128 v[12:15], v43
	ds_read_b128 v[0:3], v43 offset:128
	v_mov_b32_e32 v4, v224
	v_mov_b32_e32 v5, v225
	v_lshlrev_b32_e32 v62, 16, v4
	v_and_b32_e32 v63, 0xffff0000, v4
	v_lshlrev_b32_e32 v60, 16, v5
	v_and_b32_e32 v61, 0xffff0000, v5
	v_mov_b32_e32 v16, v212
	v_mov_b32_e32 v17, v213
	v_mov_b32_e32 v18, v214
	v_mov_b32_e32 v19, v215
	v_mov_b32_e32 v8, v216
	v_mov_b32_e32 v9, v217
	v_mov_b32_e32 v10, v218
	v_mov_b32_e32 v11, v219
	v_mov_b32_e32 v4, v220
	v_mov_b32_e32 v5, v221
	v_mov_b32_e32 v6, v222
	v_mov_b32_e32 v7, v223
	s_waitcnt lgkmcnt(1)
	v_add_f32_e32 v12, v12, v16
	v_mul_f32_e32 v12, 0xbfb8aa3b, v12
	v_exp_f32_e32 v12, v12
	s_waitcnt lgkmcnt(0)
	v_add_f32_e32 v0, v0, v8
	v_mul_f32_e32 v0, 0xbfb8aa3b, v0
	v_exp_f32_e32 v8, v0
	v_add_f32_e32 v12, 1.0, v12
	v_div_scale_f32 v16, s[46:47], v12, v12, 1.0
	v_rcp_f32_e32 v45, v16
	v_add_f32_e32 v1, v1, v9
	v_fma_f32 v47, -v16, v45, 1.0
	v_fmac_f32_e32 v45, v47, v45
	v_div_scale_f32 v47, vcc, 1.0, v12, 1.0
	v_mul_f32_e32 v113, v47, v45
	v_fma_f32 v114, -v16, v113, v47
	v_fmac_f32_e32 v113, v114, v45
	v_fma_f32 v16, -v16, v113, v47
	v_div_fmas_f32 v16, v16, v45, v113
	v_div_fixup_f32 v12, v16, v12, 1.0
	v_mul_f32_e32 v1, 0xbfb8aa3b, v1
	v_exp_f32_e32 v9, v1
	v_add_f32_e32 v2, v2, v10
	v_mul_f32_e32 v2, 0xbfb8aa3b, v2
	v_exp_f32_e32 v10, v2
	v_mov_b32_e32 v0, v240
	v_mul_f32_e32 v0, v12, v0
	v_mul_f32_e32 v0, 0x3fb8aa3b, v0
	v_exp_f32_e32 v0, v0
	v_add_f32_e32 v3, v3, v11
	v_fma_f32 v4, -v0, v0, 1.0
	v_max_f32_e32 v4, 0, v4
	v_cmp_gt_f32_e32 vcc, s69, v4
	v_mul_f32_e32 v12, 0x4f800000, v4
	s_nop 0
	v_cndmask_b32_e32 v4, v4, v12, vcc
	v_sqrt_f32_e32 v12, v4
	v_mul_f32_e32 v3, 0xbfb8aa3b, v3
	v_exp_f32_e32 v11, v3
	v_add_u32_e32 v16, -1, v12
	v_fma_f32 v45, -v16, v12, v4
	v_cmp_ge_f32_e64 s[46:47], 0, v45
	v_add_u32_e32 v45, 1, v12
	s_nop 0
	v_cndmask_b32_e64 v16, v12, v16, s[46:47]
	v_fma_f32 v12, -v45, v12, v4
	v_cmp_lt_f32_e64 s[46:47], 0, v12
	v_pk_add_f32 v[8:9], v[8:9], 1.0 op_sel_hi:[1,0]
	s_nop 0
	v_cndmask_b32_e64 v12, v16, v45, s[46:47]
	v_mul_f32_e32 v16, 0x37800000, v12
	v_cndmask_b32_e32 v12, v12, v16, vcc
	v_cmp_class_f32_e32 vcc, v4, v186
	s_nop 1
	v_cndmask_b32_e32 v4, v12, v4, vcc
	v_add_f32_e32 v12, v13, v17
	v_mul_f32_e32 v12, 0xbfb8aa3b, v12
	v_exp_f32_e32 v12, v12
	s_nop 0
	v_add_f32_e32 v12, 1.0, v12
	v_div_scale_f32 v13, s[46:47], v12, v12, 1.0
	v_rcp_f32_e32 v16, v13
	s_nop 0
	v_fma_f32 v17, -v13, v16, 1.0
	v_fmac_f32_e32 v16, v17, v16
	v_div_scale_f32 v17, vcc, 1.0, v12, 1.0
	v_mul_f32_e32 v45, v17, v16
	v_fma_f32 v47, -v13, v45, v17
	v_fmac_f32_e32 v45, v47, v16
	v_fma_f32 v13, -v13, v45, v17
	v_div_fmas_f32 v13, v13, v16, v45
	v_div_fixup_f32 v16, v13, v12, 1.0
	s_nop 1
	s_nop 1
	s_nop 1
	v_mov_b32_e32 v1, v241
	v_mul_f32_e32 v1, v16, v1
	v_mul_f32_e32 v1, 0x3fb8aa3b, v1
	v_exp_f32_e32 v1, v1
	s_nop 0
	v_fma_f32 v5, -v1, v1, 1.0
	v_max_f32_e32 v5, 0, v5
	v_cmp_gt_f32_e32 vcc, s69, v5
	v_mul_f32_e32 v12, 0x4f800000, v5
	s_nop 0
	v_cndmask_b32_e32 v5, v5, v12, vcc
	v_sqrt_f32_e32 v12, v5
	s_nop 0
	v_add_u32_e32 v13, -1, v12
	v_fma_f32 v16, -v13, v12, v5
	v_cmp_ge_f32_e64 s[46:47], 0, v16
	v_add_u32_e32 v16, 1, v12
	s_nop 0
	v_cndmask_b32_e64 v13, v12, v13, s[46:47]
	v_fma_f32 v12, -v16, v12, v5
	v_cmp_lt_f32_e64 s[46:47], 0, v12
	s_nop 1
	v_cndmask_b32_e64 v12, v13, v16, s[46:47]
	v_mul_f32_e32 v13, 0x37800000, v12
	v_cndmask_b32_e32 v12, v12, v13, vcc
	v_cmp_class_f32_e32 vcc, v5, v186
	s_nop 1
	v_cndmask_b32_e32 v5, v12, v5, vcc
	v_add_f32_e32 v12, v14, v18
	v_mul_f32_e32 v12, 0xbfb8aa3b, v12
	v_exp_f32_e32 v12, v12
	s_nop 0
	v_add_f32_e32 v12, 1.0, v12
; DEVI float sigmoidf_(float x) { return 1.f / (1.f + __expf(-x)); }
; DEVI void gate_tile(const Params& P, int l, int pm, int q, char* smem, int tid) {
;     ...
; #pragma unroll
;     for (int i = 0; i < 4; ++i) {
;       float r = sigmoidf_(rpa[i] + bav[i]);
;       float gi = sigmoidf_(gpa[i] + bxv[i]);
;       float a = __expf(-8.f * log1pf(__expf(-lmv[i])) * r);
;       av[i] = a;
;       uv[i] = sqrtf(fmaxf(1.f - a * a, 0.f)) * gi * xv[i];
;     }
;     *reinterpret_cast<float4*>(au0 + grow * 1024 + col) = make_float4(av[0], av[1], av[2], av[3]);
;     *reinterpret_cast<float4*>(au1 + grow * 1024 + col) = make_float4(uv[0], uv[1], uv[2], uv[3]);
;     *reinterpret_cast<float4*>(Tw + row * 128 + wcc * 64 + c32) = make_float4(av[0], av[1], av[2], av[3]);
;     *reinterpret_cast<float4*>(Tw + row * 128 + wcc * 64 + 32 + c32) = make_float4(uv[0], uv[1], uv[2], uv[3]);
	v_div_scale_f32 v13, s[46:47], v12, v12, 1.0
	v_rcp_f32_e32 v14, v13
	s_nop 0
	v_fma_f32 v16, -v13, v14, 1.0
	v_fmac_f32_e32 v14, v16, v14
	v_div_scale_f32 v16, vcc, 1.0, v12, 1.0
	v_mul_f32_e32 v17, v16, v14
	v_fma_f32 v18, -v13, v17, v16
	v_fmac_f32_e32 v17, v18, v14
	v_fma_f32 v13, -v13, v17, v16
	v_div_fmas_f32 v13, v13, v14, v17
	v_div_fixup_f32 v14, v13, v12, 1.0
	s_nop 1
	s_nop 1
	s_nop 1
	v_mov_b32_e32 v2, v242
	v_mul_f32_e32 v2, v14, v2
	v_mul_f32_e32 v2, 0x3fb8aa3b, v2
	v_exp_f32_e32 v2, v2
	s_nop 0
	v_fma_f32 v6, -v2, v2, 1.0
	v_max_f32_e32 v6, 0, v6
	v_cmp_gt_f32_e32 vcc, s69, v6
	v_mul_f32_e32 v12, 0x4f800000, v6
	s_nop 0
	v_cndmask_b32_e32 v6, v6, v12, vcc
	v_sqrt_f32_e32 v12, v6
	s_nop 0
	v_add_u32_e32 v13, -1, v12
	v_fma_f32 v14, -v13, v12, v6
	v_cmp_ge_f32_e64 s[46:47], 0, v14
	v_add_u32_e32 v14, 1, v12
	s_nop 0
	v_cndmask_b32_e64 v13, v12, v13, s[46:47]
	v_fma_f32 v12, -v14, v12, v6
	v_cmp_lt_f32_e64 s[46:47], 0, v12
	s_nop 1
	v_cndmask_b32_e64 v12, v13, v14, s[46:47]
	v_mul_f32_e32 v13, 0x37800000, v12
	v_cndmask_b32_e32 v12, v12, v13, vcc
	v_cmp_class_f32_e32 vcc, v6, v186
	s_nop 1
	v_cndmask_b32_e32 v6, v12, v6, vcc
	v_add_f32_e32 v12, v15, v19
	v_mul_f32_e32 v12, 0xbfb8aa3b, v12
	v_exp_f32_e32 v12, v12
	s_nop 0
	v_add_f32_e32 v12, 1.0, v12
	v_div_scale_f32 v13, s[46:47], v12, v12, 1.0
	v_rcp_f32_e32 v14, v13
	s_nop 0
	v_fma_f32 v15, -v13, v14, 1.0
	v_fmac_f32_e32 v14, v15, v14
	v_div_scale_f32 v15, vcc, 1.0, v12, 1.0
	v_mul_f32_e32 v16, v15, v14
	v_fma_f32 v17, -v13, v16, v15
	v_fmac_f32_e32 v16, v17, v14
	v_fma_f32 v13, -v13, v16, v15
	v_div_fmas_f32 v13, v13, v14, v16
	v_div_fixup_f32 v14, v13, v12, 1.0
	s_nop 1
	s_nop 1
	s_nop 1
	v_mov_b32_e32 v3, v243
	v_mul_f32_e32 v3, v14, v3
	v_mul_f32_e32 v3, 0x3fb8aa3b, v3
	v_exp_f32_e32 v3, v3
	s_nop 0
	v_fma_f32 v7, -v3, v3, 1.0
	v_max_f32_e32 v7, 0, v7
	v_cmp_gt_f32_e32 vcc, s69, v7
	v_mul_f32_e32 v12, 0x4f800000, v7
	s_nop 0
	v_cndmask_b32_e32 v7, v7, v12, vcc
	v_sqrt_f32_e32 v12, v7
	s_nop 0
	v_add_u32_e32 v13, -1, v12
	v_fma_f32 v14, -v13, v12, v7
	v_cmp_ge_f32_e64 s[46:47], 0, v14
	v_add_u32_e32 v14, 1, v12
	s_nop 0
	v_cndmask_b32_e64 v13, v12, v13, s[46:47]
	v_fma_f32 v12, -v14, v12, v7
	v_cmp_lt_f32_e64 s[46:47], 0, v12
	s_nop 1
	v_cndmask_b32_e64 v12, v13, v14, s[46:47]
	v_mul_f32_e32 v13, 0x37800000, v12
	v_cndmask_b32_e32 v12, v12, v13, vcc
	v_cmp_class_f32_e32 vcc, v7, v186
	s_nop 1
	v_cndmask_b32_e32 v7, v12, v7, vcc
	v_lshlrev_b64 v[12:13], 2, v[100:101]
	v_lshl_add_u64 v[14:15], v[56:57], 0, v[12:13]
	global_store_dwordx4 v[14:15], v[0:3], off
	v_div_scale_f32 v14, s[46:47], v9, v9, 1.0
	v_rcp_f32_e32 v15, v14
	v_lshl_add_u64 v[12:13], v[58:59], 0, v[12:13]
	v_fma_f32 v16, -v14, v15, 1.0
	v_fmac_f32_e32 v15, v16, v15
	v_div_scale_f32 v16, vcc, 1.0, v9, 1.0
	v_mul_f32_e32 v17, v16, v15
	v_fma_f32 v18, -v14, v17, v16
	v_fmac_f32_e32 v17, v18, v15
	v_fma_f32 v14, -v14, v17, v16
	v_div_fmas_f32 v14, v14, v15, v17
	v_div_fixup_f32 v9, v14, v9, 1.0
	v_div_scale_f32 v14, s[46:47], v8, v8, 1.0
	v_rcp_f32_e32 v15, v14
	s_nop 0
	v_fma_f32 v16, -v14, v15, 1.0
	v_fmac_f32_e32 v15, v16, v15
	v_div_scale_f32 v16, vcc, 1.0, v8, 1.0
	v_mul_f32_e32 v17, v16, v15
	v_fma_f32 v18, -v14, v17, v16
	v_fmac_f32_e32 v17, v18, v15
	v_fma_f32 v14, -v14, v17, v16
	v_div_fmas_f32 v14, v14, v15, v17
	v_div_fixup_f32 v8, v14, v8, 1.0
	v_pk_mul_f32 v[4:5], v[8:9], v[4:5]
	v_pk_add_f32 v[8:9], v[10:11], 1.0 op_sel_hi:[1,0]
	v_pk_mul_f32 v[4:5], v[4:5], v[62:63]
	v_div_scale_f32 v10, s[46:47], v9, v9, 1.0
	v_rcp_f32_e32 v11, v10
	s_nop 0
	v_fma_f32 v14, -v10, v11, 1.0
	v_fmac_f32_e32 v11, v14, v11
	v_div_scale_f32 v14, vcc, 1.0, v9, 1.0
	v_mul_f32_e32 v15, v14, v11
	v_fma_f32 v16, -v10, v15, v14
	v_fmac_f32_e32 v15, v16, v11
	v_fma_f32 v10, -v10, v15, v14
	v_div_fmas_f32 v10, v10, v11, v15
	v_div_fixup_f32 v9, v10, v9, 1.0
	v_div_scale_f32 v10, s[46:47], v8, v8, 1.0
	v_rcp_f32_e32 v11, v10
	s_nop 0
	v_fma_f32 v14, -v10, v11, 1.0
	v_fmac_f32_e32 v11, v14, v11
	v_div_scale_f32 v14, vcc, 1.0, v8, 1.0
	v_mul_f32_e32 v15, v14, v11
	v_fma_f32 v16, -v10, v15, v14
	v_fmac_f32_e32 v15, v16, v11
	v_fma_f32 v10, -v10, v15, v14
	v_div_fmas_f32 v10, v10, v11, v15
	v_div_fixup_f32 v8, v10, v8, 1.0
	v_pk_mul_f32 v[6:7], v[8:9], v[6:7]
	s_nop 0
	v_pk_mul_f32 v[6:7], v[6:7], v[60:61]
	global_store_dwordx4 v[12:13], v[4:7], off
	ds_write_b128 v43, v[0:3]
	ds_write_b128 v43, v[4:7] offset:128
	v_add_u32_e32 v0, 0x300, v41
	v_ashrrev_i32_e32 v4, 4, v0
	v_ashrrev_i32_e32 v5, 31, v4
	v_lshl_or_b32 v41, v4, 9, v112
	v_lshlrev_b64 v[4:5], 10, v[4:5]
	v_lshl_add_u64 v[100:101], v[4:5], 0, s[54:55]
	v_lshl_add_u64 v[4:5], v[100:101], 1, v[48:49]
	ds_read_b128 v[12:15], v41
	ds_read_b128 v[0:3], v41 offset:128
	v_mov_b32_e32 v4, v226
	v_mov_b32_e32 v5, v227
	v_lshlrev_b32_e32 v62, 16, v4
	v_and_b32_e32 v63, 0xffff0000, v4
	v_lshlrev_b32_e32 v60, 16, v5
	v_and_b32_e32 v61, 0xffff0000, v5
	v_mov_b32_e32 v16, v212
	v_mov_b32_e32 v17, v213
	v_mov_b32_e32 v18, v214
	v_mov_b32_e32 v19, v215
	v_mov_b32_e32 v8, v216
	v_mov_b32_e32 v9, v217
	v_mov_b32_e32 v10, v218
	v_mov_b32_e32 v11, v219
	v_mov_b32_e32 v4, v220
	v_mov_b32_e32 v5, v221
	v_mov_b32_e32 v6, v222
	v_mov_b32_e32 v7, v223
	s_waitcnt lgkmcnt(1)
	v_add_f32_e32 v12, v12, v16
	v_mul_f32_e32 v12, 0xbfb8aa3b, v12
	v_exp_f32_e32 v12, v12
	s_waitcnt lgkmcnt(0)
; DEVI float sigmoidf_(float x) { return 1.f / (1.f + __expf(-x)); }
; DEVI void gate_tile(const Params& P, int l, int pm, int q, char* smem, int tid) {
;     ...
; #pragma unroll
;     for (int i = 0; i < 4; ++i) {
;       float r = sigmoidf_(rpa[i] + bav[i]);
;       float gi = sigmoidf_(gpa[i] + bxv[i]);
;       float a = __expf(-8.f * log1pf(__expf(-lmv[i])) * r);
;       av[i] = a;
;       uv[i] = sqrtf(fmaxf(1.f - a * a, 0.f)) * gi * xv[i];
	v_add_f32_e32 v0, v0, v8
	v_mul_f32_e32 v0, 0xbfb8aa3b, v0
	v_exp_f32_e32 v8, v0
	v_add_f32_e32 v12, 1.0, v12
	v_div_scale_f32 v16, s[46:47], v12, v12, 1.0
	v_rcp_f32_e32 v43, v16
	v_add_f32_e32 v1, v1, v9
	v_fma_f32 v45, -v16, v43, 1.0
	v_fmac_f32_e32 v43, v45, v43
	v_div_scale_f32 v45, vcc, 1.0, v12, 1.0
	v_mul_f32_e32 v47, v45, v43
	v_fma_f32 v113, -v16, v47, v45
	v_fmac_f32_e32 v47, v113, v43
	v_fma_f32 v16, -v16, v47, v45
	v_div_fmas_f32 v16, v16, v43, v47
	v_div_fixup_f32 v12, v16, v12, 1.0
	v_mul_f32_e32 v1, 0xbfb8aa3b, v1
	v_exp_f32_e32 v9, v1
	v_add_f32_e32 v2, v2, v10
	v_mul_f32_e32 v2, 0xbfb8aa3b, v2
	v_exp_f32_e32 v10, v2
	v_mov_b32_e32 v0, v240
	v_mul_f32_e32 v0, v12, v0
	v_mul_f32_e32 v0, 0x3fb8aa3b, v0
	v_exp_f32_e32 v0, v0
	v_add_f32_e32 v3, v3, v11
	v_fma_f32 v4, -v0, v0, 1.0
	v_max_f32_e32 v4, 0, v4
	v_cmp_gt_f32_e32 vcc, s69, v4
	v_mul_f32_e32 v12, 0x4f800000, v4
	s_nop 0
	v_cndmask_b32_e32 v4, v4, v12, vcc
	v_sqrt_f32_e32 v12, v4
	v_mul_f32_e32 v3, 0xbfb8aa3b, v3
	v_exp_f32_e32 v11, v3
	v_add_u32_e32 v16, -1, v12
	v_fma_f32 v43, -v16, v12, v4
	v_cmp_ge_f32_e64 s[46:47], 0, v43
	v_add_u32_e32 v43, 1, v12
	s_nop 0
	v_cndmask_b32_e64 v16, v12, v16, s[46:47]
	v_fma_f32 v12, -v43, v12, v4
	v_cmp_lt_f32_e64 s[46:47], 0, v12
	v_pk_add_f32 v[8:9], v[8:9], 1.0 op_sel_hi:[1,0]
	s_nop 0
	v_cndmask_b32_e64 v12, v16, v43, s[46:47]
	v_mul_f32_e32 v16, 0x37800000, v12
	v_cndmask_b32_e32 v12, v12, v16, vcc
	v_cmp_class_f32_e32 vcc, v4, v186
	s_nop 1
	v_cndmask_b32_e32 v4, v12, v4, vcc
	v_add_f32_e32 v12, v13, v17
	v_mul_f32_e32 v12, 0xbfb8aa3b, v12
	v_exp_f32_e32 v12, v12
	s_nop 0
	v_add_f32_e32 v12, 1.0, v12
	v_div_scale_f32 v13, s[46:47], v12, v12, 1.0
	v_rcp_f32_e32 v16, v13
	s_nop 0
	v_fma_f32 v17, -v13, v16, 1.0
	v_fmac_f32_e32 v16, v17, v16
	v_div_scale_f32 v17, vcc, 1.0, v12, 1.0
	v_mul_f32_e32 v43, v17, v16
	v_fma_f32 v45, -v13, v43, v17
	v_fmac_f32_e32 v43, v45, v16
	v_fma_f32 v13, -v13, v43, v17
	v_div_fmas_f32 v13, v13, v16, v43
	v_div_fixup_f32 v16, v13, v12, 1.0
	s_nop 1
	s_nop 1
	s_nop 1
	v_mov_b32_e32 v1, v241
	v_mul_f32_e32 v1, v16, v1
	v_mul_f32_e32 v1, 0x3fb8aa3b, v1
	v_exp_f32_e32 v1, v1
	s_nop 0
	v_fma_f32 v5, -v1, v1, 1.0
	v_max_f32_e32 v5, 0, v5
	v_cmp_gt_f32_e32 vcc, s69, v5
	v_mul_f32_e32 v12, 0x4f800000, v5
	s_nop 0
	v_cndmask_b32_e32 v5, v5, v12, vcc
	v_sqrt_f32_e32 v12, v5
	s_nop 0
	v_add_u32_e32 v13, -1, v12
	v_fma_f32 v16, -v13, v12, v5
	v_cmp_ge_f32_e64 s[46:47], 0, v16
	v_add_u32_e32 v16, 1, v12
	s_nop 0
	v_cndmask_b32_e64 v13, v12, v13, s[46:47]
	v_fma_f32 v12, -v16, v12, v5
	v_cmp_lt_f32_e64 s[46:47], 0, v12
	s_nop 1
	v_cndmask_b32_e64 v12, v13, v16, s[46:47]
	v_mul_f32_e32 v13, 0x37800000, v12
	v_cndmask_b32_e32 v12, v12, v13, vcc
	v_cmp_class_f32_e32 vcc, v5, v186
	s_nop 1
	v_cndmask_b32_e32 v5, v12, v5, vcc
	v_add_f32_e32 v12, v14, v18
	v_mul_f32_e32 v12, 0xbfb8aa3b, v12
	v_exp_f32_e32 v12, v12
	s_nop 0
	v_add_f32_e32 v12, 1.0, v12
	v_div_scale_f32 v13, s[46:47], v12, v12, 1.0
	v_rcp_f32_e32 v14, v13
	s_nop 0
	v_fma_f32 v16, -v13, v14, 1.0
	v_fmac_f32_e32 v14, v16, v14
	v_div_scale_f32 v16, vcc, 1.0, v12, 1.0
	v_mul_f32_e32 v17, v16, v14
	v_fma_f32 v18, -v13, v17, v16
	v_fmac_f32_e32 v17, v18, v14
	v_fma_f32 v13, -v13, v17, v16
	v_div_fmas_f32 v13, v13, v14, v17
	v_div_fixup_f32 v14, v13, v12, 1.0
	s_nop 1
	s_nop 1
	s_nop 1
	v_mov_b32_e32 v2, v242
	v_mul_f32_e32 v2, v14, v2
	v_mul_f32_e32 v2, 0x3fb8aa3b, v2
	v_exp_f32_e32 v2, v2
	s_nop 0
	v_fma_f32 v6, -v2, v2, 1.0
	v_max_f32_e32 v6, 0, v6
	v_cmp_gt_f32_e32 vcc, s69, v6
	v_mul_f32_e32 v12, 0x4f800000, v6
	s_nop 0
	v_cndmask_b32_e32 v6, v6, v12, vcc
	v_sqrt_f32_e32 v12, v6
	s_nop 0
	v_add_u32_e32 v13, -1, v12
	v_fma_f32 v14, -v13, v12, v6
	v_cmp_ge_f32_e64 s[46:47], 0, v14
	v_add_u32_e32 v14, 1, v12
	s_nop 0
; DEVI float sigmoidf_(float x) { return 1.f / (1.f + __expf(-x)); }
; DEVI char* wsp(const Params& P, size_t off) { asm volatile("" : "+s"(off)); return P.ws + off; }
; DEVI void gate_tile(const Params& P, int l, int pm, int q, char* smem, int tid) {
;     ...
; #pragma unroll
;     for (int i = 0; i < 4; ++i) {
;       float r = sigmoidf_(rpa[i] + bav[i]);
;       float gi = sigmoidf_(gpa[i] + bxv[i]);
;       float a = __expf(-8.f * log1pf(__expf(-lmv[i])) * r);
;       av[i] = a;
;       uv[i] = sqrtf(fmaxf(1.f - a * a, 0.f)) * gi * xv[i];
;     }
;     *reinterpret_cast<float4*>(au0 + grow * 1024 + col) = make_float4(av[0], av[1], av[2], av[3]);
;     *reinterpret_cast<float4*>(au1 + grow * 1024 + col) = make_float4(uv[0], uv[1], uv[2], uv[3]);
;     *reinterpret_cast<float4*>(Tw + row * 128 + wcc * 64 + c32) = make_float4(av[0], av[1], av[2], av[3]);
;     *reinterpret_cast<float4*>(Tw + row * 128 + wcc * 64 + 32 + c32) = make_float4(uv[0], uv[1], uv[2], uv[3]);
;   }
;   __syncthreads();
;   if (tid < 64) {
;     const int wcc = tid >> 5, c32 = tid & 31;
;     const float* ta = T + wcc * 64 + c32;
;     float Ap = 1.f, Hp = 0.f;
; #pragma unroll 1
;     for (int r0 = 0; r0 < 128; r0 += 16) {
;       float av[16], uv[16];
; #pragma unroll
;       for (int i = 0; i < 16; ++i) { av[i] = ta[(r0 + i) * 128]; uv[i] = ta[(r0 + i) * 128 + 32]; }
; #pragma unroll
;       for (int i = 0; i < 16; ++i) { Hp = av[i] * Hp + uv[i]; Ap *= av[i]; }
;     }
;     float* ls = (float*)wsp(P, O_LSUM) + (long)pm * 2048 + nb * 128 + hb * 64 + tid;
;     ls[0] = Ap; ls[1024] = Hp;
;   }
	v_cndmask_b32_e64 v13, v12, v13, s[46:47]
	v_fma_f32 v12, -v14, v12, v6
	v_cmp_lt_f32_e64 s[46:47], 0, v12
	s_nop 1
	v_cndmask_b32_e64 v12, v13, v14, s[46:47]
	v_mul_f32_e32 v13, 0x37800000, v12
	v_cndmask_b32_e32 v12, v12, v13, vcc
	v_cmp_class_f32_e32 vcc, v6, v186
	s_nop 1
	v_cndmask_b32_e32 v6, v12, v6, vcc
	v_add_f32_e32 v12, v15, v19
	v_mul_f32_e32 v12, 0xbfb8aa3b, v12
	v_exp_f32_e32 v12, v12
	s_nop 0
	v_add_f32_e32 v12, 1.0, v12
	v_div_scale_f32 v13, s[46:47], v12, v12, 1.0
	v_rcp_f32_e32 v14, v13
	s_nop 0
	v_fma_f32 v15, -v13, v14, 1.0
	v_fmac_f32_e32 v14, v15, v14
	v_div_scale_f32 v15, vcc, 1.0, v12, 1.0
	v_mul_f32_e32 v16, v15, v14
	v_fma_f32 v17, -v13, v16, v15
	v_fmac_f32_e32 v16, v17, v14
	v_fma_f32 v13, -v13, v16, v15
	v_div_fmas_f32 v13, v13, v14, v16
	v_div_fixup_f32 v14, v13, v12, 1.0
	s_nop 1
	s_nop 1
	s_nop 1
	v_mov_b32_e32 v3, v243
	v_mul_f32_e32 v3, v14, v3
	v_mul_f32_e32 v3, 0x3fb8aa3b, v3
	v_exp_f32_e32 v3, v3
	s_nop 0
	v_fma_f32 v7, -v3, v3, 1.0
	v_max_f32_e32 v7, 0, v7
	v_cmp_gt_f32_e32 vcc, s69, v7
	v_mul_f32_e32 v12, 0x4f800000, v7
	s_nop 0
	v_cndmask_b32_e32 v7, v7, v12, vcc
	v_sqrt_f32_e32 v12, v7
	s_nop 0
	v_add_u32_e32 v13, -1, v12
	v_fma_f32 v14, -v13, v12, v7
	v_cmp_ge_f32_e64 s[46:47], 0, v14
	v_add_u32_e32 v14, 1, v12
	s_nop 0
	v_cndmask_b32_e64 v13, v12, v13, s[46:47]
	v_fma_f32 v12, -v14, v12, v7
	v_cmp_lt_f32_e64 s[46:47], 0, v12
	s_nop 1
	v_cndmask_b32_e64 v12, v13, v14, s[46:47]
	v_mul_f32_e32 v13, 0x37800000, v12
	v_cndmask_b32_e32 v12, v12, v13, vcc
	v_cmp_class_f32_e32 vcc, v7, v186
	s_nop 1
	v_cndmask_b32_e32 v7, v12, v7, vcc
	v_lshlrev_b64 v[12:13], 2, v[100:101]
	v_lshl_add_u64 v[14:15], v[56:57], 0, v[12:13]
	global_store_dwordx4 v[14:15], v[0:3], off
	v_div_scale_f32 v14, s[46:47], v9, v9, 1.0
	v_rcp_f32_e32 v15, v14
	v_lshl_add_u64 v[12:13], v[58:59], 0, v[12:13]
	v_fma_f32 v16, -v14, v15, 1.0
	v_fmac_f32_e32 v15, v16, v15
	v_div_scale_f32 v16, vcc, 1.0, v9, 1.0
	v_mul_f32_e32 v17, v16, v15
	v_fma_f32 v18, -v14, v17, v16
	v_fmac_f32_e32 v17, v18, v15
	v_fma_f32 v14, -v14, v17, v16
	v_div_fmas_f32 v14, v14, v15, v17
	v_div_fixup_f32 v9, v14, v9, 1.0
	v_div_scale_f32 v14, s[46:47], v8, v8, 1.0
	v_rcp_f32_e32 v15, v14
	s_nop 0
	v_fma_f32 v16, -v14, v15, 1.0
	v_fmac_f32_e32 v15, v16, v15
	v_div_scale_f32 v16, vcc, 1.0, v8, 1.0
	v_mul_f32_e32 v17, v16, v15
	v_fma_f32 v18, -v14, v17, v16
	v_fmac_f32_e32 v17, v18, v15
	v_fma_f32 v14, -v14, v17, v16
	v_div_fmas_f32 v14, v14, v15, v17
	v_div_fixup_f32 v8, v14, v8, 1.0
	v_pk_mul_f32 v[4:5], v[8:9], v[4:5]
	v_pk_add_f32 v[8:9], v[10:11], 1.0 op_sel_hi:[1,0]
	v_pk_mul_f32 v[4:5], v[4:5], v[62:63]
	v_div_scale_f32 v10, s[46:47], v9, v9, 1.0
	v_rcp_f32_e32 v11, v10
	s_nop 0
	v_fma_f32 v14, -v10, v11, 1.0
	v_fmac_f32_e32 v11, v14, v11
	v_div_scale_f32 v14, vcc, 1.0, v9, 1.0
	v_mul_f32_e32 v15, v14, v11
	v_fma_f32 v16, -v10, v15, v14
	v_fmac_f32_e32 v15, v16, v11
	v_fma_f32 v10, -v10, v15, v14
	v_div_fmas_f32 v10, v10, v11, v15
	v_div_fixup_f32 v9, v10, v9, 1.0
	v_div_scale_f32 v10, s[46:47], v8, v8, 1.0
	v_rcp_f32_e32 v11, v10
	s_nop 0
	v_fma_f32 v14, -v10, v11, 1.0
	v_fmac_f32_e32 v11, v14, v11
	v_div_scale_f32 v14, vcc, 1.0, v8, 1.0
	v_mul_f32_e32 v15, v14, v11
	v_fma_f32 v16, -v10, v15, v14
	v_fmac_f32_e32 v15, v16, v11
	v_fma_f32 v10, -v10, v15, v14
	v_div_fmas_f32 v10, v10, v11, v15
	v_div_fixup_f32 v8, v10, v8, 1.0
	v_pk_mul_f32 v[6:7], v[8:9], v[6:7]
	s_nop 0
	v_pk_mul_f32 v[6:7], v[6:7], v[60:61]
	global_store_dwordx4 v[12:13], v[4:7], off
	ds_write_b128 v41, v[0:3]
	ds_write_b128 v41, v[4:7] offset:128
	s_cbranch_scc0 .LBB0_459
	s_waitcnt lgkmcnt(0)
	s_barrier
	s_and_saveexec_b64 s[46:47], s[44:45]
	s_cbranch_execz .LBB0_451
	v_mov_b32_e32 v1, 1.0
	v_mov_b32_e32 v2, 0
	s_mov_b32 s54, -16
	v_mov_b32_e32 v4, v111

; DEVI float sigmoidf_(float x) { return 1.f / (1.f + __expf(-x)); }
; DEVI void load4bf(const bfu* p, float (&o)[4]) {
;   uint2 v = *reinterpret_cast<const uint2*>(p);
;   o[0] = __uint_as_float(v.x << 16); o[1] = __uint_as_float(v.x & 0xFFFF0000u);
;   o[2] = __uint_as_float(v.y << 16); o[3] = __uint_as_float(v.y & 0xFFFF0000u);
; }
; template <int BR, int IN, int OUT>
; DEVI void p6_branch(const Params& P, int pm, int pn, float* macc, char* smem, int tid) {
;     ...
; #pragma unroll 8
;   for (int q = 0; q < 16; ++q) {
;     const int id = tid + 256 * q, row = id >> 5, c4 = id & 31;
;     const long grow = (long)pm * 128 + row;
;     const int gcol = pn * 128 + c4 * 4;
;     float4 a = *reinterpret_cast<const float4*>(T + row * 128 + c4 * 4);
;     float g[4];
;     load4bf(Z + grow * NCOL + (9 + BR) * 1024 + gcol, g);
;     float v[4] = {sigmoidf_(g[0]) * a.x, sigmoidf_(g[1]) * a.y, sigmoidf_(g[2]) * a.z, sigmoidf_(g[3]) * a.w};
.LBB0_513:
	s_cmp_lg_u32 s24, 0
	s_cbranch_scc1 .Leh2LBB0513b
	v_add_u32_e32 v238, s24, v91
	v_ashrrev_i32_e32 v236, 5, v238
	v_ashrrev_i32_e32 v237, 31, v236
	v_lshl_add_u64 v[240:241], s[74:75], 0, v[236:237]
	v_mov_b64_e32 v[236:237], s[26:27]
	v_mad_u64_u32 v[242:243], s[50:51], v240, s22, v[236:237]
	v_mad_i32_i24 v243, v241, s22, v243
	v_lshl_add_u64 v[242:243], v[242:243], 0, v[2:3]
	v_add_co_u32_e32 v242, vcc, 0x4000, v242
	s_nop 1
	v_addc_co_u32_e32 v243, vcc, 0, v243, vcc
	global_load_dwordx2 v[220:221], v[242:243], off offset:2048
	v_add_u32_e32 v238, s24, v91
	v_mov_b64_e32 v[236:237], s[26:27]
	v_add_u32_e32 v239, 0x100, v238
	v_ashrrev_i32_e32 v240, 5, v239
	v_ashrrev_i32_e32 v241, 31, v240
	v_lshl_add_u64 v[242:243], s[74:75], 0, v[240:241]
	v_mad_u64_u32 v[240:241], s[50:51], v242, s22, v[236:237]
	v_mad_i32_i24 v241, v243, s22, v241
	v_lshl_add_u64 v[240:241], v[240:241], 0, v[2:3]
	v_add_co_u32_e32 v240, vcc, s36, v240
	s_nop 1
	v_addc_co_u32_e32 v241, vcc, 0, v241, vcc
	global_load_dwordx2 v[222:223], v[240:241], off offset:2048
	v_add_u32_e32 v238, s24, v91
	v_mov_b64_e32 v[236:237], s[26:27]
	v_add_u32_e32 v239, 0x200, v238
	v_ashrrev_i32_e32 v240, 5, v239
	v_ashrrev_i32_e32 v241, 31, v240
	v_lshl_add_u64 v[242:243], s[74:75], 0, v[240:241]
	v_mad_u64_u32 v[240:241], s[50:51], v242, s22, v[236:237]
	v_mad_i32_i24 v241, v243, s22, v241
	v_lshl_add_u64 v[240:241], v[240:241], 0, v[2:3]
	v_add_co_u32_e32 v240, vcc, s36, v240
	s_nop 1
	v_addc_co_u32_e32 v241, vcc, 0, v241, vcc
	global_load_dwordx2 v[224:225], v[240:241], off offset:2048
	v_add_u32_e32 v238, s24, v91
	v_mov_b64_e32 v[236:237], s[26:27]
	v_add_u32_e32 v239, 0x300, v238
	v_ashrrev_i32_e32 v240, 5, v239
	v_ashrrev_i32_e32 v241, 31, v240
	v_lshl_add_u64 v[242:243], s[74:75], 0, v[240:241]
	v_mad_u64_u32 v[240:241], s[50:51], v242, s22, v[236:237]
	v_mad_i32_i24 v241, v243, s22, v241
	v_lshl_add_u64 v[240:241], v[240:241], 0, v[2:3]
	v_add_co_u32_e32 v240, vcc, s36, v240
	s_nop 1
	v_addc_co_u32_e32 v241, vcc, 0, v241, vcc
	global_load_dwordx2 v[226:227], v[240:241], off offset:2048
	v_add_u32_e32 v238, s24, v91
	v_mov_b64_e32 v[236:237], s[26:27]
	v_add_u32_e32 v239, 0x400, v238
	v_ashrrev_i32_e32 v240, 5, v239
	v_ashrrev_i32_e32 v241, 31, v240
	v_lshl_add_u64 v[242:243], s[74:75], 0, v[240:241]
	v_mad_u64_u32 v[240:241], s[50:51], v242, s22, v[236:237]
	v_mad_i32_i24 v241, v243, s22, v241
	v_lshl_add_u64 v[240:241], v[240:241], 0, v[2:3]
	v_add_co_u32_e32 v240, vcc, s36, v240
	s_nop 1
	v_addc_co_u32_e32 v241, vcc, 0, v241, vcc
	global_load_dwordx2 v[228:229], v[240:241], off offset:2048
	v_add_u32_e32 v238, s24, v91
	v_mov_b64_e32 v[236:237], s[26:27]
	v_add_u32_e32 v239, 0x500, v238
	v_ashrrev_i32_e32 v240, 5, v239
	v_ashrrev_i32_e32 v241, 31, v240
	v_lshl_add_u64 v[242:243], s[74:75], 0, v[240:241]
	v_mad_u64_u32 v[240:241], s[50:51], v242, s22, v[236:237]
	v_mad_i32_i24 v241, v243, s22, v241
	v_lshl_add_u64 v[240:241], v[240:241], 0, v[2:3]
	v_add_co_u32_e32 v240, vcc, s36, v240
	s_nop 1
	v_addc_co_u32_e32 v241, vcc, 0, v241, vcc
	global_load_dwordx2 v[230:231], v[240:241], off offset:2048
	v_add_u32_e32 v238, s24, v91
	v_mov_b64_e32 v[236:237], s[26:27]
	v_add_u32_e32 v239, 0x600, v238
	v_ashrrev_i32_e32 v240, 5, v239
	v_ashrrev_i32_e32 v241, 31, v240
	v_lshl_add_u64 v[242:243], s[74:75], 0, v[240:241]
	v_mad_u64_u32 v[240:241], s[50:51], v242, s22, v[236:237]
	v_mad_i32_i24 v241, v243, s22, v241
	v_lshl_add_u64 v[240:241], v[240:241], 0, v[2:3]
	v_add_co_u32_e32 v240, vcc, s36, v240
	s_nop 1
	v_addc_co_u32_e32 v241, vcc, 0, v241, vcc
	global_load_dwordx2 v[232:233], v[240:241], off offset:2048
	v_add_u32_e32 v238, s24, v91
	v_mov_b64_e32 v[236:237], s[26:27]
	v_add_u32_e32 v238, 0x700, v238
	v_ashrrev_i32_e32 v240, 5, v238
	v_ashrrev_i32_e32 v241, 31, v240
	v_lshl_add_u64 v[238:239], s[74:75], 0, v[240:241]
	v_mad_u64_u32 v[236:237], s[50:51], v238, s22, v[236:237]
	v_mad_i32_i24 v237, v239, s22, v237
	v_lshl_add_u64 v[236:237], v[236:237], 0, v[2:3]
	v_add_co_u32_e32 v236, vcc, s36, v236
	s_nop 1
	v_addc_co_u32_e32 v237, vcc, 0, v237, vcc
	global_load_dwordx2 v[234:235], v[236:237], off offset:2048
	v_add_u32_e32 v238, s24, v91
	v_add_u32_e32 v238, 0x800, v238
	v_ashrrev_i32_e32 v236, 5, v238
	v_ashrrev_i32_e32 v237, 31, v236
	v_lshl_add_u64 v[240:241], s[74:75], 0, v[236:237]
	v_mov_b64_e32 v[236:237], s[26:27]
	v_mad_u64_u32 v[242:243], s[50:51], v240, s22, v[236:237]
	v_mad_i32_i24 v243, v241, s22, v243
	v_lshl_add_u64 v[242:243], v[242:243], 0, v[2:3]
	v_add_co_u32_e32 v242, vcc, 0x4000, v242
	s_nop 1
	v_addc_co_u32_e32 v243, vcc, 0, v243, vcc
	global_load_dwordx2 v[28:29], v[242:243], off offset:2048
	v_add_u32_e32 v238, s24, v91
	v_add_u32_e32 v238, 0x800, v238
	v_mov_b64_e32 v[236:237], s[26:27]
	v_add_u32_e32 v239, 0x100, v238
	v_ashrrev_i32_e32 v240, 5, v239
	v_ashrrev_i32_e32 v241, 31, v240
	v_lshl_add_u64 v[242:243], s[74:75], 0, v[240:241]
	v_mad_u64_u32 v[240:241], s[50:51], v242, s22, v[236:237]
	v_mad_i32_i24 v241, v243, s22, v241
	v_lshl_add_u64 v[240:241], v[240:241], 0, v[2:3]
	v_add_co_u32_e32 v240, vcc, s36, v240
	s_nop 1
	v_addc_co_u32_e32 v241, vcc, 0, v241, vcc
	global_load_dwordx2 v[30:31], v[240:241], off offset:2048
	v_add_u32_e32 v238, s24, v91
	v_add_u32_e32 v238, 0x800, v238
	v_mov_b64_e32 v[236:237], s[26:27]
	v_add_u32_e32 v239, 0x200, v238
	v_ashrrev_i32_e32 v240, 5, v239
	v_ashrrev_i32_e32 v241, 31, v240
	v_lshl_add_u64 v[242:243], s[74:75], 0, v[240:241]
	v_mad_u64_u32 v[240:241], s[50:51], v242, s22, v[236:237]
	v_mad_i32_i24 v241, v243, s22, v241
	v_lshl_add_u64 v[240:241], v[240:241], 0, v[2:3]
; DEVI float sigmoidf_(float x) { return 1.f / (1.f + __expf(-x)); }
; template <int BR, int IN, int OUT>
; DEVI void p6_branch(const Params& P, int pm, int pn, float* macc, char* smem, int tid) {
;     ...
; #pragma unroll 8
;   for (int q = 0; q < 16; ++q) {
;     const int id = tid + 256 * q, row = id >> 5, c4 = id & 31;
;     const long grow = (long)pm * 128 + row;
;     const int gcol = pn * 128 + c4 * 4;
;     float4 a = *reinterpret_cast<const float4*>(T + row * 128 + c4 * 4);
;     float g[4];
;     load4bf(Z + grow * NCOL + (9 + BR) * 1024 + gcol, g);
;     float v[4] = {sigmoidf_(g[0]) * a.x, sigmoidf_(g[1]) * a.y, sigmoidf_(g[2]) * a.z, sigmoidf_(g[3]) * a.w};
	v_add_co_u32_e32 v240, vcc, s36, v240
	s_nop 1
	v_addc_co_u32_e32 v241, vcc, 0, v241, vcc
	global_load_dwordx2 v[32:33], v[240:241], off offset:2048
	v_add_u32_e32 v238, s24, v91
	v_add_u32_e32 v238, 0x800, v238
	v_mov_b64_e32 v[236:237], s[26:27]
	v_add_u32_e32 v239, 0x300, v238
	v_ashrrev_i32_e32 v240, 5, v239
	v_ashrrev_i32_e32 v241, 31, v240
	v_lshl_add_u64 v[242:243], s[74:75], 0, v[240:241]
	v_mad_u64_u32 v[240:241], s[50:51], v242, s22, v[236:237]
	v_mad_i32_i24 v241, v243, s22, v241
	v_lshl_add_u64 v[240:241], v[240:241], 0, v[2:3]
	v_add_co_u32_e32 v240, vcc, s36, v240
	s_nop 1
	v_addc_co_u32_e32 v241, vcc, 0, v241, vcc
	global_load_dwordx2 v[34:35], v[240:241], off offset:2048
	v_add_u32_e32 v238, s24, v91
	v_add_u32_e32 v238, 0x800, v238
	v_mov_b64_e32 v[236:237], s[26:27]
	v_add_u32_e32 v239, 0x400, v238
	v_ashrrev_i32_e32 v240, 5, v239
	v_ashrrev_i32_e32 v241, 31, v240
	v_lshl_add_u64 v[242:243], s[74:75], 0, v[240:241]
	v_mad_u64_u32 v[240:241], s[50:51], v242, s22, v[236:237]
	v_mad_i32_i24 v241, v243, s22, v241
	v_lshl_add_u64 v[240:241], v[240:241], 0, v[2:3]
	v_add_co_u32_e32 v240, vcc, s36, v240
	s_nop 1
	v_addc_co_u32_e32 v241, vcc, 0, v241, vcc
	global_load_dwordx2 v[36:37], v[240:241], off offset:2048
	v_add_u32_e32 v238, s24, v91
	v_add_u32_e32 v238, 0x800, v238
	v_mov_b64_e32 v[236:237], s[26:27]
	v_add_u32_e32 v239, 0x500, v238
	v_ashrrev_i32_e32 v240, 5, v239
	v_ashrrev_i32_e32 v241, 31, v240
	v_lshl_add_u64 v[242:243], s[74:75], 0, v[240:241]
	v_mad_u64_u32 v[240:241], s[50:51], v242, s22, v[236:237]
	v_mad_i32_i24 v241, v243, s22, v241
	v_lshl_add_u64 v[240:241], v[240:241], 0, v[2:3]
	v_add_co_u32_e32 v240, vcc, s36, v240
	s_nop 1
	v_addc_co_u32_e32 v241, vcc, 0, v241, vcc
	global_load_dwordx2 v[38:39], v[240:241], off offset:2048
	v_add_u32_e32 v238, s24, v91
	v_add_u32_e32 v238, 0x800, v238
	v_mov_b64_e32 v[236:237], s[26:27]
	v_add_u32_e32 v239, 0x600, v238
	v_ashrrev_i32_e32 v240, 5, v239
	v_ashrrev_i32_e32 v241, 31, v240
	v_lshl_add_u64 v[242:243], s[74:75], 0, v[240:241]
	v_mad_u64_u32 v[240:241], s[50:51], v242, s22, v[236:237]
	v_mad_i32_i24 v241, v243, s22, v241
	v_lshl_add_u64 v[240:241], v[240:241], 0, v[2:3]
	v_add_co_u32_e32 v240, vcc, s36, v240
	s_nop 1
	v_addc_co_u32_e32 v241, vcc, 0, v241, vcc
	global_load_dwordx2 v[40:41], v[240:241], off offset:2048
	v_add_u32_e32 v238, s24, v91
	v_add_u32_e32 v238, 0x800, v238
	v_mov_b64_e32 v[236:237], s[26:27]
	v_add_u32_e32 v238, 0x700, v238
	v_ashrrev_i32_e32 v240, 5, v238
	v_ashrrev_i32_e32 v241, 31, v240
	v_lshl_add_u64 v[238:239], s[74:75], 0, v[240:241]
	v_mad_u64_u32 v[236:237], s[50:51], v238, s22, v[236:237]
	v_mad_i32_i24 v237, v239, s22, v237
	v_lshl_add_u64 v[236:237], v[236:237], 0, v[2:3]
	v_add_co_u32_e32 v236, vcc, s36, v236
	s_nop 1
	v_addc_co_u32_e32 v237, vcc, 0, v237, vcc
	global_load_dwordx2 v[42:43], v[236:237], off offset:2048
	s_waitcnt vmcnt(0)
	s_branch .Leh2LBB0513c
.Leh2LBB0513b:
	v_mov_b32_e32 v220, v28
	v_mov_b32_e32 v221, v29
	v_mov_b32_e32 v222, v30
	v_mov_b32_e32 v223, v31
	v_mov_b32_e32 v224, v32
	v_mov_b32_e32 v225, v33
	v_mov_b32_e32 v226, v34
	v_mov_b32_e32 v227, v35
	v_mov_b32_e32 v228, v36
	v_mov_b32_e32 v229, v37
	v_mov_b32_e32 v230, v38
	v_mov_b32_e32 v231, v39
	v_mov_b32_e32 v232, v40
	v_mov_b32_e32 v233, v41
	v_mov_b32_e32 v234, v42
	v_mov_b32_e32 v235, v43
.Leh2LBB0513c:
	v_add_u32_e32 v6, s24, v91
	v_ashrrev_i32_e32 v4, 5, v6
	v_ashrrev_i32_e32 v5, 31, v4
	v_lshl_add_u64 v[8:9], s[74:75], 0, v[4:5]
	v_lshl_or_b32 v7, v4, 9, v169
	v_mov_b64_e32 v[4:5], s[26:27]
	v_mad_u64_u32 v[10:11], s[50:51], v8, s22, v[4:5]
	v_mad_i32_i24 v11, v9, s22, v11
	v_lshl_add_u64 v[10:11], v[10:11], 0, v[2:3]
	v_add_co_u32_e32 v10, vcc, 0x4000, v10
	v_lshlrev_b64 v[8:9], 11, v[8:9]
	s_nop 0
	v_addc_co_u32_e32 v11, vcc, 0, v11, vcc
	v_mov_b32_e32 v10, v220
	v_mov_b32_e32 v11, v221
	v_lshl_add_u64 v[16:17], v[0:1], 0, v[8:9]
	s_addk_i32 s24, 0x800
	s_cmpk_lg_i32 s24, 0x1000
	v_lshlrev_b32_e32 v12, 16, v10
	v_and_b32_e32 v10, 0xffff0000, v10
	v_lshlrev_b32_e32 v13, 16, v11
	v_mul_f32_e32 v10, 0xbfb8aa3b, v10
	v_mul_f32_e32 v12, 0xbfb8aa3b, v12
	v_exp_f32_e32 v14, v10
	v_mul_f32_e32 v10, 0xbfb8aa3b, v13
	v_exp_f32_e32 v12, v12
	v_exp_f32_e32 v13, v10
	v_and_b32_e32 v11, 0xffff0000, v11
	v_mul_f32_e32 v10, 0xbfb8aa3b, v11
	v_exp_f32_e32 v15, v10
	v_pk_add_f32 v[12:13], v[12:13], 1.0 op_sel_hi:[1,0]
	ds_read_b128 v[8:11], v7
	v_div_scale_f32 v7, s[50:51], v13, v13, 1.0
	v_rcp_f32_e32 v18, v7
	v_pk_add_f32 v[14:15], v[14:15], 1.0 op_sel_hi:[1,0]
	v_fma_f32 v19, -v7, v18, 1.0
	v_fmac_f32_e32 v18, v19, v18
	v_div_scale_f32 v19, vcc, 1.0, v13, 1.0
	v_mul_f32_e32 v20, v19, v18
	v_fma_f32 v21, -v7, v20, v19
	v_fmac_f32_e32 v20, v21, v18
	v_fma_f32 v7, -v7, v20, v19
	v_div_fmas_f32 v7, v7, v18, v20
	v_div_fixup_f32 v13, v7, v13, 1.0
	v_div_scale_f32 v7, s[50:51], v12, v12, 1.0
	v_rcp_f32_e32 v18, v7
	s_nop 0
	v_fma_f32 v19, -v7, v18, 1.0
	v_fmac_f32_e32 v18, v19, v18
	v_div_scale_f32 v19, vcc, 1.0, v12, 1.0
	v_mul_f32_e32 v20, v19, v18
	v_fma_f32 v21, -v7, v20, v19
	v_fmac_f32_e32 v20, v21, v18
	v_fma_f32 v7, -v7, v20, v19
	v_div_fmas_f32 v7, v7, v18, v20
	v_div_fixup_f32 v12, v7, v12, 1.0
	v_div_scale_f32 v7, s[50:51], v15, v15, 1.0
	s_waitcnt lgkmcnt(0)
; DEVI float sigmoidf_(float x) { return 1.f / (1.f + __expf(-x)); }
; DEVI void store4bf(bfu* p, const float (&v)[4]) {
;   uint2 r;
;   r.x = f2b(v[0]) | ((unsigned)f2b(v[1]) << 16);
;   r.y = f2b(v[2]) | ((unsigned)f2b(v[3]) << 16);
;   *reinterpret_cast<uint2*>(p) = r;
; }
; template <int BR, int IN, int OUT>
; DEVI void p6_branch(const Params& P, int pm, int pn, float* macc, char* smem, int tid) {
;     ...
; #pragma unroll 8
;   for (int q = 0; q < 16; ++q) {
;     const int id = tid + 256 * q, row = id >> 5, c4 = id & 31;
;     const long grow = (long)pm * 128 + row;
;     const int gcol = pn * 128 + c4 * 4;
;     float4 a = *reinterpret_cast<const float4*>(T + row * 128 + c4 * 4);
;     float g[4];
;     load4bf(Z + grow * NCOL + (9 + BR) * 1024 + gcol, g);
;     float v[4] = {sigmoidf_(g[0]) * a.x, sigmoidf_(g[1]) * a.y, sigmoidf_(g[2]) * a.z, sigmoidf_(g[3]) * a.w};
;     if (IN == 1) {
;       float mo[4]; load4bf(M + grow * 1024 + gcol, mo);
;       v[0] += mo[0]; v[1] += mo[1]; v[2] += mo[2]; v[3] += mo[3];
;     }
;     if (IN == 2) {
;       float4 mo = *reinterpret_cast<const float4*>(macc + grow * 1024 + gcol);
;       v[0] += mo.x; v[1] += mo.y; v[2] += mo.z; v[3] += mo.w;
;     }
;     if (OUT == 1) *reinterpret_cast<float4*>(macc + grow * 1024 + gcol) = make_float4(v[0], v[1], v[2], v[3]);
;     else store4bf(M + grow * 1024 + gcol, v);
	v_mov_b32_e32 v18, v8
	v_rcp_f32_e32 v8, v7
	v_mov_b32_e32 v19, v10
	v_pk_mul_f32 v[12:13], v[18:19], v[12:13]
	v_fma_f32 v10, -v7, v8, 1.0
	v_fmac_f32_e32 v8, v10, v8
	v_div_scale_f32 v10, vcc, 1.0, v15, 1.0
	v_mul_f32_e32 v18, v10, v8
	v_fma_f32 v19, -v7, v18, v10
	v_fmac_f32_e32 v18, v19, v8
	v_fma_f32 v7, -v7, v18, v10
	v_div_fmas_f32 v7, v7, v8, v18
	v_div_fixup_f32 v15, v7, v15, 1.0
	v_div_scale_f32 v7, s[50:51], v14, v14, 1.0
	v_rcp_f32_e32 v8, v7
	s_nop 0
	v_fma_f32 v10, -v7, v8, 1.0
	v_fmac_f32_e32 v8, v10, v8
	v_div_scale_f32 v10, vcc, 1.0, v14, 1.0
	v_mul_f32_e32 v18, v10, v8
	v_fma_f32 v19, -v7, v18, v10
	v_fmac_f32_e32 v18, v19, v8
	v_fma_f32 v7, -v7, v18, v10
	v_div_fmas_f32 v7, v7, v8, v18
	v_div_fixup_f32 v14, v7, v14, 1.0
	v_mov_b32_e32 v10, v9
	v_pk_mul_f32 v[8:9], v[10:11], v[14:15]
	v_and_b32_sdwa v10, v12, v95 dst_sel:DWORD dst_unused:UNUSED_PAD src0_sel:WORD_1 src1_sel:DWORD
	v_add3_u32 v10, v12, v10, s39
	v_and_b32_sdwa v11, v9, v95 dst_sel:DWORD dst_unused:UNUSED_PAD src0_sel:WORD_1 src1_sel:DWORD
	v_and_b32_sdwa v12, v8, v95 dst_sel:DWORD dst_unused:UNUSED_PAD src0_sel:WORD_1 src1_sel:DWORD
	v_and_b32_sdwa v7, v13, v95 dst_sel:DWORD dst_unused:UNUSED_PAD src0_sel:WORD_1 src1_sel:DWORD
	v_add3_u32 v9, v9, v11, s39
	v_add3_u32 v8, v8, v12, s39
	v_add3_u32 v7, v13, v7, s39
	v_and_b32_e32 v9, 0xffff0000, v9
	v_and_b32_e32 v8, 0xffff0000, v8
	v_or_b32_sdwa v9, v9, v7 dst_sel:DWORD dst_unused:UNUSED_PAD src0_sel:DWORD src1_sel:WORD_1
	v_or_b32_sdwa v8, v8, v10 dst_sel:DWORD dst_unused:UNUSED_PAD src0_sel:DWORD src1_sel:WORD_1
	v_add_u32_e32 v7, 0x100, v6
	global_store_dwordx2 v[16:17], v[8:9], off
	v_ashrrev_i32_e32 v8, 5, v7
	v_ashrrev_i32_e32 v9, 31, v8
	v_lshl_add_u64 v[10:11], s[74:75], 0, v[8:9]
	v_lshl_or_b32 v7, v8, 9, v169
	v_mad_u64_u32 v[8:9], s[50:51], v10, s22, v[4:5]
	v_mad_i32_i24 v9, v11, s22, v9
	v_lshl_add_u64 v[8:9], v[8:9], 0, v[2:3]
	v_add_co_u32_e32 v8, vcc, s36, v8
	s_nop 1
	v_addc_co_u32_e32 v9, vcc, 0, v9, vcc
	v_mov_b32_e32 v8, v222
	v_mov_b32_e32 v9, v223
	v_lshlrev_b32_e32 v12, 16, v8
	v_and_b32_e32 v8, 0xffff0000, v8
	v_lshlrev_b32_e32 v13, 16, v9
	v_mul_f32_e32 v8, 0xbfb8aa3b, v8
	v_mul_f32_e32 v12, 0xbfb8aa3b, v12
	v_exp_f32_e32 v14, v8
	v_mul_f32_e32 v8, 0xbfb8aa3b, v13
	v_exp_f32_e32 v12, v12
	v_exp_f32_e32 v13, v8
	v_and_b32_e32 v9, 0xffff0000, v9
	v_mul_f32_e32 v8, 0xbfb8aa3b, v9
	v_exp_f32_e32 v15, v8
	v_lshlrev_b64 v[8:9], 11, v[10:11]
	v_pk_add_f32 v[12:13], v[12:13], 1.0 op_sel_hi:[1,0]
	v_lshl_add_u64 v[16:17], v[0:1], 0, v[8:9]
	ds_read_b128 v[8:11], v7
	v_div_scale_f32 v7, s[50:51], v13, v13, 1.0
	v_rcp_f32_e32 v18, v7
	v_pk_add_f32 v[14:15], v[14:15], 1.0 op_sel_hi:[1,0]
	v_fma_f32 v19, -v7, v18, 1.0
	v_fmac_f32_e32 v18, v19, v18
	v_div_scale_f32 v19, vcc, 1.0, v13, 1.0
	v_mul_f32_e32 v20, v19, v18
	v_fma_f32 v21, -v7, v20, v19
	v_fmac_f32_e32 v20, v21, v18
	v_fma_f32 v7, -v7, v20, v19
	v_div_fmas_f32 v7, v7, v18, v20
	v_div_fixup_f32 v13, v7, v13, 1.0
	v_div_scale_f32 v7, s[50:51], v12, v12, 1.0
	v_rcp_f32_e32 v18, v7
	s_nop 0
	v_fma_f32 v19, -v7, v18, 1.0
	v_fmac_f32_e32 v18, v19, v18
	v_div_scale_f32 v19, vcc, 1.0, v12, 1.0
	v_mul_f32_e32 v20, v19, v18
	v_fma_f32 v21, -v7, v20, v19
	v_fmac_f32_e32 v20, v21, v18
	v_fma_f32 v7, -v7, v20, v19
	v_div_fmas_f32 v7, v7, v18, v20
	v_div_fixup_f32 v12, v7, v12, 1.0
	v_div_scale_f32 v7, s[50:51], v15, v15, 1.0
	s_waitcnt lgkmcnt(0)
	v_mov_b32_e32 v18, v8
	v_rcp_f32_e32 v8, v7
	v_mov_b32_e32 v19, v10
	v_pk_mul_f32 v[12:13], v[18:19], v[12:13]
	v_fma_f32 v10, -v7, v8, 1.0
	v_fmac_f32_e32 v8, v10, v8
	v_div_scale_f32 v10, vcc, 1.0, v15, 1.0
	v_mul_f32_e32 v18, v10, v8
	v_fma_f32 v19, -v7, v18, v10
	v_fmac_f32_e32 v18, v19, v8
	v_fma_f32 v7, -v7, v18, v10
	v_div_fmas_f32 v7, v7, v8, v18
	v_div_fixup_f32 v15, v7, v15, 1.0
	v_div_scale_f32 v7, s[50:51], v14, v14, 1.0
	v_rcp_f32_e32 v8, v7
	s_nop 0
	v_fma_f32 v10, -v7, v8, 1.0
	v_fmac_f32_e32 v8, v10, v8
	v_div_scale_f32 v10, vcc, 1.0, v14, 1.0
	v_mul_f32_e32 v18, v10, v8
	v_fma_f32 v19, -v7, v18, v10
	v_fmac_f32_e32 v18, v19, v8
	v_fma_f32 v7, -v7, v18, v10
	v_div_fmas_f32 v7, v7, v8, v18
	v_div_fixup_f32 v14, v7, v14, 1.0
	v_mov_b32_e32 v10, v9
	v_pk_mul_f32 v[8:9], v[10:11], v[14:15]
	v_and_b32_sdwa v10, v12, v95 dst_sel:DWORD dst_unused:UNUSED_PAD src0_sel:WORD_1 src1_sel:DWORD
	v_add3_u32 v10, v12, v10, s39
	v_and_b32_sdwa v11, v9, v95 dst_sel:DWORD dst_unused:UNUSED_PAD src0_sel:WORD_1 src1_sel:DWORD
	v_and_b32_sdwa v12, v8, v95 dst_sel:DWORD dst_unused:UNUSED_PAD src0_sel:WORD_1 src1_sel:DWORD
	v_and_b32_sdwa v7, v13, v95 dst_sel:DWORD dst_unused:UNUSED_PAD src0_sel:WORD_1 src1_sel:DWORD
	v_add3_u32 v9, v9, v11, s39
	v_add3_u32 v8, v8, v12, s39
	v_add3_u32 v7, v13, v7, s39
	v_and_b32_e32 v9, 0xffff0000, v9
	v_and_b32_e32 v8, 0xffff0000, v8
	v_or_b32_sdwa v9, v9, v7 dst_sel:DWORD dst_unused:UNUSED_PAD src0_sel:DWORD src1_sel:WORD_1
	v_or_b32_sdwa v8, v8, v10 dst_sel:DWORD dst_unused:UNUSED_PAD src0_sel:DWORD src1_sel:WORD_1
	v_add_u32_e32 v7, 0x200, v6
	global_store_dwordx2 v[16:17], v[8:9], off
	v_ashrrev_i32_e32 v8, 5, v7
	v_ashrrev_i32_e32 v9, 31, v8
	v_lshl_add_u64 v[10:11], s[74:75], 0, v[8:9]
	v_lshl_or_b32 v7, v8, 9, v169
	v_mad_u64_u32 v[8:9], s[50:51], v10, s22, v[4:5]
	v_mad_i32_i24 v9, v11, s22, v9
	v_lshl_add_u64 v[8:9], v[8:9], 0, v[2:3]
	v_add_co_u32_e32 v8, vcc, s36, v8
	s_nop 1
	v_addc_co_u32_e32 v9, vcc, 0, v9, vcc
	v_mov_b32_e32 v8, v224
	v_mov_b32_e32 v9, v225
	v_lshlrev_b32_e32 v12, 16, v8
	v_and_b32_e32 v8, 0xffff0000, v8
	v_lshlrev_b32_e32 v13, 16, v9
	v_mul_f32_e32 v8, 0xbfb8aa3b, v8
	v_mul_f32_e32 v12, 0xbfb8aa3b, v12
	v_exp_f32_e32 v14, v8
	v_mul_f32_e32 v8, 0xbfb8aa3b, v13
	v_exp_f32_e32 v12, v12
	v_exp_f32_e32 v13, v8
	v_and_b32_e32 v9, 0xffff0000, v9
	v_mul_f32_e32 v8, 0xbfb8aa3b, v9
	v_exp_f32_e32 v15, v8
	v_lshlrev_b64 v[8:9], 11, v[10:11]
	v_pk_add_f32 v[12:13], v[12:13], 1.0 op_sel_hi:[1,0]
	v_lshl_add_u64 v[16:17], v[0:1], 0, v[8:9]
	ds_read_b128 v[8:11], v7
	v_div_scale_f32 v7, s[50:51], v13, v13, 1.0
	v_rcp_f32_e32 v18, v7
	v_pk_add_f32 v[14:15], v[14:15], 1.0 op_sel_hi:[1,0]
	v_fma_f32 v19, -v7, v18, 1.0
	v_fmac_f32_e32 v18, v19, v18
	v_div_scale_f32 v19, vcc, 1.0, v13, 1.0
	v_mul_f32_e32 v20, v19, v18
	v_fma_f32 v21, -v7, v20, v19
	v_fmac_f32_e32 v20, v21, v18
	v_fma_f32 v7, -v7, v20, v19
	v_div_fmas_f32 v7, v7, v18, v20
	v_div_fixup_f32 v13, v7, v13, 1.0
	v_div_scale_f32 v7, s[50:51], v12, v12, 1.0
	v_rcp_f32_e32 v18, v7
	s_nop 0
	v_fma_f32 v19, -v7, v18, 1.0
	v_fmac_f32_e32 v18, v19, v18
	v_div_scale_f32 v19, vcc, 1.0, v12, 1.0
	v_mul_f32_e32 v20, v19, v18
	v_fma_f32 v21, -v7, v20, v19
	v_fmac_f32_e32 v20, v21, v18
	v_fma_f32 v7, -v7, v20, v19
	v_div_fmas_f32 v7, v7, v18, v20
	v_div_fixup_f32 v12, v7, v12, 1.0
	v_div_scale_f32 v7, s[50:51], v15, v15, 1.0
	s_waitcnt lgkmcnt(0)
; DEVI float sigmoidf_(float x) { return 1.f / (1.f + __expf(-x)); }
; DEVI void store4bf(bfu* p, const float (&v)[4]) {
;   uint2 r;
;   r.x = f2b(v[0]) | ((unsigned)f2b(v[1]) << 16);
;   r.y = f2b(v[2]) | ((unsigned)f2b(v[3]) << 16);
;   *reinterpret_cast<uint2*>(p) = r;
; }
; template <int BR, int IN, int OUT>
; DEVI void p6_branch(const Params& P, int pm, int pn, float* macc, char* smem, int tid) {
;     ...
; #pragma unroll 8
;   for (int q = 0; q < 16; ++q) {
;     const int id = tid + 256 * q, row = id >> 5, c4 = id & 31;
;     const long grow = (long)pm * 128 + row;
;     const int gcol = pn * 128 + c4 * 4;
;     float4 a = *reinterpret_cast<const float4*>(T + row * 128 + c4 * 4);
;     float g[4];
;     load4bf(Z + grow * NCOL + (9 + BR) * 1024 + gcol, g);
;     float v[4] = {sigmoidf_(g[0]) * a.x, sigmoidf_(g[1]) * a.y, sigmoidf_(g[2]) * a.z, sigmoidf_(g[3]) * a.w};
;     if (IN == 1) {
;       float mo[4]; load4bf(M + grow * 1024 + gcol, mo);
;       v[0] += mo[0]; v[1] += mo[1]; v[2] += mo[2]; v[3] += mo[3];
;     }
;     if (IN == 2) {
;       float4 mo = *reinterpret_cast<const float4*>(macc + grow * 1024 + gcol);
;       v[0] += mo.x; v[1] += mo.y; v[2] += mo.z; v[3] += mo.w;
;     }
;     if (OUT == 1) *reinterpret_cast<float4*>(macc + grow * 1024 + gcol) = make_float4(v[0], v[1], v[2], v[3]);
;     else store4bf(M + grow * 1024 + gcol, v);
	v_mov_b32_e32 v18, v8
	v_rcp_f32_e32 v8, v7
	v_mov_b32_e32 v19, v10
	v_pk_mul_f32 v[12:13], v[18:19], v[12:13]
	v_fma_f32 v10, -v7, v8, 1.0
	v_fmac_f32_e32 v8, v10, v8
	v_div_scale_f32 v10, vcc, 1.0, v15, 1.0
	v_mul_f32_e32 v18, v10, v8
	v_fma_f32 v19, -v7, v18, v10
	v_fmac_f32_e32 v18, v19, v8
	v_fma_f32 v7, -v7, v18, v10
	v_div_fmas_f32 v7, v7, v8, v18
	v_div_fixup_f32 v15, v7, v15, 1.0
	v_div_scale_f32 v7, s[50:51], v14, v14, 1.0
	v_rcp_f32_e32 v8, v7
	s_nop 0
	v_fma_f32 v10, -v7, v8, 1.0
	v_fmac_f32_e32 v8, v10, v8
	v_div_scale_f32 v10, vcc, 1.0, v14, 1.0
	v_mul_f32_e32 v18, v10, v8
	v_fma_f32 v19, -v7, v18, v10
	v_fmac_f32_e32 v18, v19, v8
	v_fma_f32 v7, -v7, v18, v10
	v_div_fmas_f32 v7, v7, v8, v18
	v_div_fixup_f32 v14, v7, v14, 1.0
	v_mov_b32_e32 v10, v9
	v_pk_mul_f32 v[8:9], v[10:11], v[14:15]
	v_and_b32_sdwa v10, v12, v95 dst_sel:DWORD dst_unused:UNUSED_PAD src0_sel:WORD_1 src1_sel:DWORD
	v_add3_u32 v10, v12, v10, s39
	v_and_b32_sdwa v11, v9, v95 dst_sel:DWORD dst_unused:UNUSED_PAD src0_sel:WORD_1 src1_sel:DWORD
	v_and_b32_sdwa v12, v8, v95 dst_sel:DWORD dst_unused:UNUSED_PAD src0_sel:WORD_1 src1_sel:DWORD
	v_and_b32_sdwa v7, v13, v95 dst_sel:DWORD dst_unused:UNUSED_PAD src0_sel:WORD_1 src1_sel:DWORD
	v_add3_u32 v9, v9, v11, s39
	v_add3_u32 v8, v8, v12, s39
	v_add3_u32 v7, v13, v7, s39
	v_and_b32_e32 v9, 0xffff0000, v9
	v_and_b32_e32 v8, 0xffff0000, v8
	v_or_b32_sdwa v9, v9, v7 dst_sel:DWORD dst_unused:UNUSED_PAD src0_sel:DWORD src1_sel:WORD_1
	v_or_b32_sdwa v8, v8, v10 dst_sel:DWORD dst_unused:UNUSED_PAD src0_sel:DWORD src1_sel:WORD_1
	v_add_u32_e32 v7, 0x300, v6
	global_store_dwordx2 v[16:17], v[8:9], off
	v_ashrrev_i32_e32 v8, 5, v7
	v_ashrrev_i32_e32 v9, 31, v8
	v_lshl_add_u64 v[10:11], s[74:75], 0, v[8:9]
	v_lshl_or_b32 v7, v8, 9, v169
	v_mad_u64_u32 v[8:9], s[50:51], v10, s22, v[4:5]
	v_mad_i32_i24 v9, v11, s22, v9
	v_lshl_add_u64 v[8:9], v[8:9], 0, v[2:3]
	v_add_co_u32_e32 v8, vcc, s36, v8
	s_nop 1
	v_addc_co_u32_e32 v9, vcc, 0, v9, vcc
	v_mov_b32_e32 v8, v226
	v_mov_b32_e32 v9, v227
	v_lshlrev_b32_e32 v12, 16, v8
	v_and_b32_e32 v8, 0xffff0000, v8
	v_lshlrev_b32_e32 v13, 16, v9
	v_mul_f32_e32 v8, 0xbfb8aa3b, v8
	v_mul_f32_e32 v12, 0xbfb8aa3b, v12
	v_exp_f32_e32 v14, v8
	v_mul_f32_e32 v8, 0xbfb8aa3b, v13
	v_exp_f32_e32 v12, v12
	v_exp_f32_e32 v13, v8
	v_and_b32_e32 v9, 0xffff0000, v9
	v_mul_f32_e32 v8, 0xbfb8aa3b, v9
	v_exp_f32_e32 v15, v8
	v_lshlrev_b64 v[8:9], 11, v[10:11]
	v_pk_add_f32 v[12:13], v[12:13], 1.0 op_sel_hi:[1,0]
	v_lshl_add_u64 v[16:17], v[0:1], 0, v[8:9]
	ds_read_b128 v[8:11], v7
	v_div_scale_f32 v7, s[50:51], v13, v13, 1.0
	v_rcp_f32_e32 v18, v7
	v_pk_add_f32 v[14:15], v[14:15], 1.0 op_sel_hi:[1,0]
	v_fma_f32 v19, -v7, v18, 1.0
	v_fmac_f32_e32 v18, v19, v18
	v_div_scale_f32 v19, vcc, 1.0, v13, 1.0
	v_mul_f32_e32 v20, v19, v18
	v_fma_f32 v21, -v7, v20, v19
	v_fmac_f32_e32 v20, v21, v18
	v_fma_f32 v7, -v7, v20, v19
	v_div_fmas_f32 v7, v7, v18, v20
	v_div_fixup_f32 v13, v7, v13, 1.0
	v_div_scale_f32 v7, s[50:51], v12, v12, 1.0
	v_rcp_f32_e32 v18, v7
	s_nop 0
	v_fma_f32 v19, -v7, v18, 1.0
	v_fmac_f32_e32 v18, v19, v18
	v_div_scale_f32 v19, vcc, 1.0, v12, 1.0
	v_mul_f32_e32 v20, v19, v18
	v_fma_f32 v21, -v7, v20, v19
	v_fmac_f32_e32 v20, v21, v18
	v_fma_f32 v7, -v7, v20, v19
	v_div_fmas_f32 v7, v7, v18, v20
	v_div_fixup_f32 v12, v7, v12, 1.0
	v_div_scale_f32 v7, s[50:51], v15, v15, 1.0
	s_waitcnt lgkmcnt(0)
	v_mov_b32_e32 v18, v8
	v_rcp_f32_e32 v8, v7
	v_mov_b32_e32 v19, v10
	v_pk_mul_f32 v[12:13], v[18:19], v[12:13]
	v_fma_f32 v10, -v7, v8, 1.0
	v_fmac_f32_e32 v8, v10, v8
	v_div_scale_f32 v10, vcc, 1.0, v15, 1.0
	v_mul_f32_e32 v18, v10, v8
	v_fma_f32 v19, -v7, v18, v10
	v_fmac_f32_e32 v18, v19, v8
	v_fma_f32 v7, -v7, v18, v10
	v_div_fmas_f32 v7, v7, v8, v18
	v_div_fixup_f32 v15, v7, v15, 1.0
	v_div_scale_f32 v7, s[50:51], v14, v14, 1.0
	v_rcp_f32_e32 v8, v7
	s_nop 0
	v_fma_f32 v10, -v7, v8, 1.0
	v_fmac_f32_e32 v8, v10, v8
	v_div_scale_f32 v10, vcc, 1.0, v14, 1.0
	v_mul_f32_e32 v18, v10, v8
	v_fma_f32 v19, -v7, v18, v10
	v_fmac_f32_e32 v18, v19, v8
	v_fma_f32 v7, -v7, v18, v10
	v_div_fmas_f32 v7, v7, v8, v18
	v_div_fixup_f32 v14, v7, v14, 1.0
	v_mov_b32_e32 v10, v9
	v_pk_mul_f32 v[8:9], v[10:11], v[14:15]
	v_and_b32_sdwa v10, v12, v95 dst_sel:DWORD dst_unused:UNUSED_PAD src0_sel:WORD_1 src1_sel:DWORD
	v_add3_u32 v10, v12, v10, s39
	v_and_b32_sdwa v11, v9, v95 dst_sel:DWORD dst_unused:UNUSED_PAD src0_sel:WORD_1 src1_sel:DWORD
	v_and_b32_sdwa v12, v8, v95 dst_sel:DWORD dst_unused:UNUSED_PAD src0_sel:WORD_1 src1_sel:DWORD
	v_and_b32_sdwa v7, v13, v95 dst_sel:DWORD dst_unused:UNUSED_PAD src0_sel:WORD_1 src1_sel:DWORD
	v_add3_u32 v9, v9, v11, s39
	v_add3_u32 v8, v8, v12, s39
	v_add3_u32 v7, v13, v7, s39
	v_and_b32_e32 v9, 0xffff0000, v9
	v_and_b32_e32 v8, 0xffff0000, v8
	v_or_b32_sdwa v9, v9, v7 dst_sel:DWORD dst_unused:UNUSED_PAD src0_sel:DWORD src1_sel:WORD_1
	v_or_b32_sdwa v8, v8, v10 dst_sel:DWORD dst_unused:UNUSED_PAD src0_sel:DWORD src1_sel:WORD_1
	v_add_u32_e32 v7, 0x400, v6
	global_store_dwordx2 v[16:17], v[8:9], off
	v_ashrrev_i32_e32 v8, 5, v7
	v_ashrrev_i32_e32 v9, 31, v8
	v_lshl_add_u64 v[10:11], s[74:75], 0, v[8:9]
	v_lshl_or_b32 v7, v8, 9, v169
	v_mad_u64_u32 v[8:9], s[50:51], v10, s22, v[4:5]
	v_mad_i32_i24 v9, v11, s22, v9
	v_lshl_add_u64 v[8:9], v[8:9], 0, v[2:3]
	v_add_co_u32_e32 v8, vcc, s36, v8
	s_nop 1
	v_addc_co_u32_e32 v9, vcc, 0, v9, vcc
	v_mov_b32_e32 v8, v228
	v_mov_b32_e32 v9, v229
	v_lshlrev_b32_e32 v12, 16, v8
	v_and_b32_e32 v8, 0xffff0000, v8
	v_lshlrev_b32_e32 v13, 16, v9
	v_mul_f32_e32 v8, 0xbfb8aa3b, v8
	v_mul_f32_e32 v12, 0xbfb8aa3b, v12
	v_exp_f32_e32 v14, v8
	v_mul_f32_e32 v8, 0xbfb8aa3b, v13
	v_exp_f32_e32 v12, v12
	v_exp_f32_e32 v13, v8
	v_and_b32_e32 v9, 0xffff0000, v9
	v_mul_f32_e32 v8, 0xbfb8aa3b, v9
	v_exp_f32_e32 v15, v8
	v_lshlrev_b64 v[8:9], 11, v[10:11]
	v_pk_add_f32 v[12:13], v[12:13], 1.0 op_sel_hi:[1,0]
	v_lshl_add_u64 v[16:17], v[0:1], 0, v[8:9]
	ds_read_b128 v[8:11], v7
	v_div_scale_f32 v7, s[50:51], v13, v13, 1.0
	v_rcp_f32_e32 v18, v7
	v_pk_add_f32 v[14:15], v[14:15], 1.0 op_sel_hi:[1,0]
	v_fma_f32 v19, -v7, v18, 1.0
	v_fmac_f32_e32 v18, v19, v18
	v_div_scale_f32 v19, vcc, 1.0, v13, 1.0
	v_mul_f32_e32 v20, v19, v18
	v_fma_f32 v21, -v7, v20, v19
	v_fmac_f32_e32 v20, v21, v18
	v_fma_f32 v7, -v7, v20, v19
	v_div_fmas_f32 v7, v7, v18, v20
	v_div_fixup_f32 v13, v7, v13, 1.0
	v_div_scale_f32 v7, s[50:51], v12, v12, 1.0
	v_rcp_f32_e32 v18, v7
	s_nop 0
	v_fma_f32 v19, -v7, v18, 1.0
	v_fmac_f32_e32 v18, v19, v18
	v_div_scale_f32 v19, vcc, 1.0, v12, 1.0
	v_mul_f32_e32 v20, v19, v18
	v_fma_f32 v21, -v7, v20, v19
	v_fmac_f32_e32 v20, v21, v18
	v_fma_f32 v7, -v7, v20, v19
	v_div_fmas_f32 v7, v7, v18, v20
	v_div_fixup_f32 v12, v7, v12, 1.0
	v_div_scale_f32 v7, s[50:51], v15, v15, 1.0
	s_waitcnt lgkmcnt(0)
; DEVI float sigmoidf_(float x) { return 1.f / (1.f + __expf(-x)); }
; DEVI void store4bf(bfu* p, const float (&v)[4]) {
;   uint2 r;
;   r.x = f2b(v[0]) | ((unsigned)f2b(v[1]) << 16);
;   r.y = f2b(v[2]) | ((unsigned)f2b(v[3]) << 16);
;   *reinterpret_cast<uint2*>(p) = r;
; }
; template <int BR, int IN, int OUT>
; DEVI void p6_branch(const Params& P, int pm, int pn, float* macc, char* smem, int tid) {
;     ...
; #pragma unroll 8
;   for (int q = 0; q < 16; ++q) {
;     const int id = tid + 256 * q, row = id >> 5, c4 = id & 31;
;     const long grow = (long)pm * 128 + row;
;     const int gcol = pn * 128 + c4 * 4;
;     float4 a = *reinterpret_cast<const float4*>(T + row * 128 + c4 * 4);
;     float g[4];
;     load4bf(Z + grow * NCOL + (9 + BR) * 1024 + gcol, g);
;     float v[4] = {sigmoidf_(g[0]) * a.x, sigmoidf_(g[1]) * a.y, sigmoidf_(g[2]) * a.z, sigmoidf_(g[3]) * a.w};
;     if (IN == 1) {
;       float mo[4]; load4bf(M + grow * 1024 + gcol, mo);
;       v[0] += mo[0]; v[1] += mo[1]; v[2] += mo[2]; v[3] += mo[3];
;     }
;     if (IN == 2) {
;       float4 mo = *reinterpret_cast<const float4*>(macc + grow * 1024 + gcol);
;       v[0] += mo.x; v[1] += mo.y; v[2] += mo.z; v[3] += mo.w;
;     }
;     if (OUT == 1) *reinterpret_cast<float4*>(macc + grow * 1024 + gcol) = make_float4(v[0], v[1], v[2], v[3]);
;     else store4bf(M + grow * 1024 + gcol, v);
	v_mov_b32_e32 v18, v8
	v_rcp_f32_e32 v8, v7
	v_mov_b32_e32 v19, v10
	v_pk_mul_f32 v[12:13], v[18:19], v[12:13]
	v_fma_f32 v10, -v7, v8, 1.0
	v_fmac_f32_e32 v8, v10, v8
	v_div_scale_f32 v10, vcc, 1.0, v15, 1.0
	v_mul_f32_e32 v18, v10, v8
	v_fma_f32 v19, -v7, v18, v10
	v_fmac_f32_e32 v18, v19, v8
	v_fma_f32 v7, -v7, v18, v10
	v_div_fmas_f32 v7, v7, v8, v18
	v_div_fixup_f32 v15, v7, v15, 1.0
	v_div_scale_f32 v7, s[50:51], v14, v14, 1.0
	v_rcp_f32_e32 v8, v7
	s_nop 0
	v_fma_f32 v10, -v7, v8, 1.0
	v_fmac_f32_e32 v8, v10, v8
	v_div_scale_f32 v10, vcc, 1.0, v14, 1.0
	v_mul_f32_e32 v18, v10, v8
	v_fma_f32 v19, -v7, v18, v10
	v_fmac_f32_e32 v18, v19, v8
	v_fma_f32 v7, -v7, v18, v10
	v_div_fmas_f32 v7, v7, v8, v18
	v_div_fixup_f32 v14, v7, v14, 1.0
	v_mov_b32_e32 v10, v9
	v_pk_mul_f32 v[8:9], v[10:11], v[14:15]
	v_and_b32_sdwa v10, v12, v95 dst_sel:DWORD dst_unused:UNUSED_PAD src0_sel:WORD_1 src1_sel:DWORD
	v_add3_u32 v10, v12, v10, s39
	v_and_b32_sdwa v11, v9, v95 dst_sel:DWORD dst_unused:UNUSED_PAD src0_sel:WORD_1 src1_sel:DWORD
	v_and_b32_sdwa v12, v8, v95 dst_sel:DWORD dst_unused:UNUSED_PAD src0_sel:WORD_1 src1_sel:DWORD
	v_and_b32_sdwa v7, v13, v95 dst_sel:DWORD dst_unused:UNUSED_PAD src0_sel:WORD_1 src1_sel:DWORD
	v_add3_u32 v9, v9, v11, s39
	v_add3_u32 v8, v8, v12, s39
	v_add3_u32 v7, v13, v7, s39
	v_and_b32_e32 v9, 0xffff0000, v9
	v_and_b32_e32 v8, 0xffff0000, v8
	v_or_b32_sdwa v9, v9, v7 dst_sel:DWORD dst_unused:UNUSED_PAD src0_sel:DWORD src1_sel:WORD_1
	v_or_b32_sdwa v8, v8, v10 dst_sel:DWORD dst_unused:UNUSED_PAD src0_sel:DWORD src1_sel:WORD_1
	v_add_u32_e32 v7, 0x500, v6
	global_store_dwordx2 v[16:17], v[8:9], off
	v_ashrrev_i32_e32 v8, 5, v7
	v_ashrrev_i32_e32 v9, 31, v8
	v_lshl_add_u64 v[10:11], s[74:75], 0, v[8:9]
	v_lshl_or_b32 v7, v8, 9, v169
	v_mad_u64_u32 v[8:9], s[50:51], v10, s22, v[4:5]
	v_mad_i32_i24 v9, v11, s22, v9
	v_lshl_add_u64 v[8:9], v[8:9], 0, v[2:3]
	v_add_co_u32_e32 v8, vcc, s36, v8
	s_nop 1
	v_addc_co_u32_e32 v9, vcc, 0, v9, vcc
	v_mov_b32_e32 v8, v230
	v_mov_b32_e32 v9, v231
	v_lshlrev_b32_e32 v12, 16, v8
	v_and_b32_e32 v8, 0xffff0000, v8
	v_lshlrev_b32_e32 v13, 16, v9
	v_mul_f32_e32 v8, 0xbfb8aa3b, v8
	v_mul_f32_e32 v12, 0xbfb8aa3b, v12
	v_exp_f32_e32 v14, v8
	v_mul_f32_e32 v8, 0xbfb8aa3b, v13
	v_exp_f32_e32 v12, v12
	v_exp_f32_e32 v13, v8
	v_and_b32_e32 v9, 0xffff0000, v9
	v_mul_f32_e32 v8, 0xbfb8aa3b, v9
	v_exp_f32_e32 v15, v8
	v_lshlrev_b64 v[8:9], 11, v[10:11]
	v_pk_add_f32 v[12:13], v[12:13], 1.0 op_sel_hi:[1,0]
	v_lshl_add_u64 v[16:17], v[0:1], 0, v[8:9]
	ds_read_b128 v[8:11], v7
	v_div_scale_f32 v7, s[50:51], v13, v13, 1.0
	v_rcp_f32_e32 v18, v7
	v_pk_add_f32 v[14:15], v[14:15], 1.0 op_sel_hi:[1,0]
	v_fma_f32 v19, -v7, v18, 1.0
	v_fmac_f32_e32 v18, v19, v18
	v_div_scale_f32 v19, vcc, 1.0, v13, 1.0
	v_mul_f32_e32 v20, v19, v18
	v_fma_f32 v21, -v7, v20, v19
	v_fmac_f32_e32 v20, v21, v18
	v_fma_f32 v7, -v7, v20, v19
	v_div_fmas_f32 v7, v7, v18, v20
	v_div_fixup_f32 v13, v7, v13, 1.0
	v_div_scale_f32 v7, s[50:51], v12, v12, 1.0
	v_rcp_f32_e32 v18, v7
	s_nop 0
	v_fma_f32 v19, -v7, v18, 1.0
	v_fmac_f32_e32 v18, v19, v18
	v_div_scale_f32 v19, vcc, 1.0, v12, 1.0
	v_mul_f32_e32 v20, v19, v18
	v_fma_f32 v21, -v7, v20, v19
	v_fmac_f32_e32 v20, v21, v18
	v_fma_f32 v7, -v7, v20, v19
	v_div_fmas_f32 v7, v7, v18, v20
	v_div_fixup_f32 v12, v7, v12, 1.0
	v_div_scale_f32 v7, s[50:51], v15, v15, 1.0
	s_waitcnt lgkmcnt(0)
	v_mov_b32_e32 v18, v8
	v_rcp_f32_e32 v8, v7
	v_mov_b32_e32 v19, v10
	v_pk_mul_f32 v[12:13], v[18:19], v[12:13]
	v_fma_f32 v10, -v7, v8, 1.0
	v_fmac_f32_e32 v8, v10, v8
	v_div_scale_f32 v10, vcc, 1.0, v15, 1.0
	v_mul_f32_e32 v18, v10, v8
	v_fma_f32 v19, -v7, v18, v10
	v_fmac_f32_e32 v18, v19, v8
	v_fma_f32 v7, -v7, v18, v10
	v_div_fmas_f32 v7, v7, v8, v18
	v_div_fixup_f32 v15, v7, v15, 1.0
	v_div_scale_f32 v7, s[50:51], v14, v14, 1.0
	v_rcp_f32_e32 v8, v7
	s_nop 0
	v_fma_f32 v10, -v7, v8, 1.0
	v_fmac_f32_e32 v8, v10, v8
	v_div_scale_f32 v10, vcc, 1.0, v14, 1.0
	v_mul_f32_e32 v18, v10, v8
	v_fma_f32 v19, -v7, v18, v10
	v_fmac_f32_e32 v18, v19, v8
	v_fma_f32 v7, -v7, v18, v10
	v_div_fmas_f32 v7, v7, v8, v18
	v_div_fixup_f32 v14, v7, v14, 1.0
	v_mov_b32_e32 v10, v9
	v_pk_mul_f32 v[8:9], v[10:11], v[14:15]
	v_and_b32_sdwa v10, v12, v95 dst_sel:DWORD dst_unused:UNUSED_PAD src0_sel:WORD_1 src1_sel:DWORD
	v_add3_u32 v10, v12, v10, s39
	v_and_b32_sdwa v11, v9, v95 dst_sel:DWORD dst_unused:UNUSED_PAD src0_sel:WORD_1 src1_sel:DWORD
	v_and_b32_sdwa v12, v8, v95 dst_sel:DWORD dst_unused:UNUSED_PAD src0_sel:WORD_1 src1_sel:DWORD
	v_and_b32_sdwa v7, v13, v95 dst_sel:DWORD dst_unused:UNUSED_PAD src0_sel:WORD_1 src1_sel:DWORD
	v_add3_u32 v9, v9, v11, s39
	v_add3_u32 v8, v8, v12, s39
	v_add3_u32 v7, v13, v7, s39
	v_and_b32_e32 v9, 0xffff0000, v9
	v_and_b32_e32 v8, 0xffff0000, v8
	v_or_b32_sdwa v9, v9, v7 dst_sel:DWORD dst_unused:UNUSED_PAD src0_sel:DWORD src1_sel:WORD_1
	v_or_b32_sdwa v8, v8, v10 dst_sel:DWORD dst_unused:UNUSED_PAD src0_sel:DWORD src1_sel:WORD_1
	v_add_u32_e32 v7, 0x600, v6
	global_store_dwordx2 v[16:17], v[8:9], off
	v_ashrrev_i32_e32 v8, 5, v7
	v_ashrrev_i32_e32 v9, 31, v8
	v_lshl_add_u64 v[10:11], s[74:75], 0, v[8:9]
	v_lshl_or_b32 v7, v8, 9, v169
	v_mad_u64_u32 v[8:9], s[50:51], v10, s22, v[4:5]
	v_mad_i32_i24 v9, v11, s22, v9
	v_lshl_add_u64 v[8:9], v[8:9], 0, v[2:3]
	v_add_co_u32_e32 v8, vcc, s36, v8
	v_add_u32_e32 v6, 0x700, v6
	s_nop 0
	v_addc_co_u32_e32 v9, vcc, 0, v9, vcc
	v_mov_b32_e32 v8, v232
	v_mov_b32_e32 v9, v233
	v_lshlrev_b32_e32 v12, 16, v8
	v_and_b32_e32 v8, 0xffff0000, v8
	v_lshlrev_b32_e32 v13, 16, v9
	v_mul_f32_e32 v8, 0xbfb8aa3b, v8
	v_mul_f32_e32 v12, 0xbfb8aa3b, v12
	v_exp_f32_e32 v14, v8
	v_mul_f32_e32 v8, 0xbfb8aa3b, v13
	v_exp_f32_e32 v12, v12
	v_exp_f32_e32 v13, v8
	v_and_b32_e32 v9, 0xffff0000, v9
	v_mul_f32_e32 v8, 0xbfb8aa3b, v9
	v_exp_f32_e32 v15, v8
	v_lshlrev_b64 v[8:9], 11, v[10:11]
	v_pk_add_f32 v[12:13], v[12:13], 1.0 op_sel_hi:[1,0]
	v_lshl_add_u64 v[16:17], v[0:1], 0, v[8:9]
	ds_read_b128 v[8:11], v7
	v_div_scale_f32 v7, s[50:51], v13, v13, 1.0
	v_rcp_f32_e32 v18, v7
	v_pk_add_f32 v[14:15], v[14:15], 1.0 op_sel_hi:[1,0]
	v_fma_f32 v19, -v7, v18, 1.0
	v_fmac_f32_e32 v18, v19, v18
	v_div_scale_f32 v19, vcc, 1.0, v13, 1.0
	v_mul_f32_e32 v20, v19, v18
	v_fma_f32 v21, -v7, v20, v19
	v_fmac_f32_e32 v20, v21, v18
	v_fma_f32 v7, -v7, v20, v19
	v_div_fmas_f32 v7, v7, v18, v20
	v_div_fixup_f32 v13, v7, v13, 1.0
	v_div_scale_f32 v7, s[50:51], v12, v12, 1.0
	v_rcp_f32_e32 v18, v7
	s_nop 0
	v_fma_f32 v19, -v7, v18, 1.0
	v_fmac_f32_e32 v18, v19, v18
	v_div_scale_f32 v19, vcc, 1.0, v12, 1.0
	v_mul_f32_e32 v20, v19, v18
	v_fma_f32 v21, -v7, v20, v19
	v_fmac_f32_e32 v20, v21, v18
	v_fma_f32 v7, -v7, v20, v19
	v_div_fmas_f32 v7, v7, v18, v20
	v_div_fixup_f32 v12, v7, v12, 1.0
	v_div_scale_f32 v7, s[50:51], v15, v15, 1.0
	s_waitcnt lgkmcnt(0)
; DEVI float sigmoidf_(float x) { return 1.f / (1.f + __expf(-x)); }
; template <int BR, int IN, int OUT>
; DEVI void p6_branch(const Params& P, int pm, int pn, float* macc, char* smem, int tid) {
;     ...
; #pragma unroll 8
;   for (int q = 0; q < 16; ++q) {
;     const int id = tid + 256 * q, row = id >> 5, c4 = id & 31;
;     const long grow = (long)pm * 128 + row;
;     const int gcol = pn * 128 + c4 * 4;
;     float4 a = *reinterpret_cast<const float4*>(T + row * 128 + c4 * 4);
;     float g[4];
;     load4bf(Z + grow * NCOL + (9 + BR) * 1024 + gcol, g);
;     float v[4] = {sigmoidf_(g[0]) * a.x, sigmoidf_(g[1]) * a.y, sigmoidf_(g[2]) * a.z, sigmoidf_(g[3]) * a.w};
;     if (IN == 1) {
;       float mo[4]; load4bf(M + grow * 1024 + gcol, mo);
;       v[0] += mo[0]; v[1] += mo[1]; v[2] += mo[2]; v[3] += mo[3];
;     }
;     if (IN == 2) {
;       float4 mo = *reinterpret_cast<const float4*>(macc + grow * 1024 + gcol);
;       v[0] += mo.x; v[1] += mo.y; v[2] += mo.z; v[3] += mo.w;
;     }
;     if (OUT == 1) *reinterpret_cast<float4*>(macc + grow * 1024 + gcol) = make_float4(v[0], v[1], v[2], v[3]);
;     else store4bf(M + grow * 1024 + gcol, v);
	v_mov_b32_e32 v18, v8
	v_rcp_f32_e32 v8, v7
	v_mov_b32_e32 v19, v10
	v_pk_mul_f32 v[12:13], v[18:19], v[12:13]
	v_fma_f32 v10, -v7, v8, 1.0
	v_fmac_f32_e32 v8, v10, v8
	v_div_scale_f32 v10, vcc, 1.0, v15, 1.0
	v_mul_f32_e32 v18, v10, v8
	v_fma_f32 v19, -v7, v18, v10
	v_fmac_f32_e32 v18, v19, v8
	v_fma_f32 v7, -v7, v18, v10
	v_div_fmas_f32 v7, v7, v8, v18
	v_div_fixup_f32 v15, v7, v15, 1.0
	v_div_scale_f32 v7, s[50:51], v14, v14, 1.0
	v_rcp_f32_e32 v8, v7
	s_nop 0
	v_fma_f32 v10, -v7, v8, 1.0
	v_fmac_f32_e32 v8, v10, v8
	v_div_scale_f32 v10, vcc, 1.0, v14, 1.0
	v_mul_f32_e32 v18, v10, v8
	v_fma_f32 v19, -v7, v18, v10
	v_fmac_f32_e32 v18, v19, v8
	v_fma_f32 v7, -v7, v18, v10
	v_div_fmas_f32 v7, v7, v8, v18
	v_div_fixup_f32 v14, v7, v14, 1.0
	v_mov_b32_e32 v10, v9
	v_pk_mul_f32 v[8:9], v[10:11], v[14:15]
	v_and_b32_sdwa v10, v12, v95 dst_sel:DWORD dst_unused:UNUSED_PAD src0_sel:WORD_1 src1_sel:DWORD
	v_add3_u32 v10, v12, v10, s39
	v_and_b32_sdwa v11, v9, v95 dst_sel:DWORD dst_unused:UNUSED_PAD src0_sel:WORD_1 src1_sel:DWORD
	v_and_b32_sdwa v12, v8, v95 dst_sel:DWORD dst_unused:UNUSED_PAD src0_sel:WORD_1 src1_sel:DWORD
	v_and_b32_sdwa v7, v13, v95 dst_sel:DWORD dst_unused:UNUSED_PAD src0_sel:WORD_1 src1_sel:DWORD
	v_add3_u32 v9, v9, v11, s39
	v_add3_u32 v8, v8, v12, s39
	v_add3_u32 v7, v13, v7, s39
	v_and_b32_e32 v9, 0xffff0000, v9
	v_and_b32_e32 v8, 0xffff0000, v8
	v_or_b32_sdwa v9, v9, v7 dst_sel:DWORD dst_unused:UNUSED_PAD src0_sel:DWORD src1_sel:WORD_1
	v_or_b32_sdwa v8, v8, v10 dst_sel:DWORD dst_unused:UNUSED_PAD src0_sel:DWORD src1_sel:WORD_1
	global_store_dwordx2 v[16:17], v[8:9], off
	v_ashrrev_i32_e32 v8, 5, v6
	v_ashrrev_i32_e32 v9, 31, v8
	v_lshl_add_u64 v[6:7], s[74:75], 0, v[8:9]
	v_mad_u64_u32 v[4:5], s[50:51], v6, s22, v[4:5]
	v_mad_i32_i24 v5, v7, s22, v5
	v_lshl_add_u64 v[4:5], v[4:5], 0, v[2:3]
	v_add_co_u32_e32 v4, vcc, s36, v4
	v_lshl_or_b32 v8, v8, 9, v169
	s_nop 0
	v_addc_co_u32_e32 v5, vcc, 0, v5, vcc
	v_mov_b32_e32 v4, v234
	v_mov_b32_e32 v5, v235
	v_lshlrev_b32_e32 v9, 16, v4
	v_and_b32_e32 v4, 0xffff0000, v4
	v_lshlrev_b32_e32 v11, 16, v5
	v_mul_f32_e32 v4, 0xbfb8aa3b, v4
	v_mul_f32_e32 v9, 0xbfb8aa3b, v9
	v_exp_f32_e32 v12, v4
	v_mul_f32_e32 v4, 0xbfb8aa3b, v11
	v_exp_f32_e32 v10, v9
	v_exp_f32_e32 v11, v4
	v_and_b32_e32 v5, 0xffff0000, v5
	v_mul_f32_e32 v4, 0xbfb8aa3b, v5
	v_exp_f32_e32 v13, v4
	v_lshlrev_b64 v[4:5], 11, v[6:7]
	v_lshl_add_u64 v[14:15], v[0:1], 0, v[4:5]
	ds_read_b128 v[4:7], v8
	v_pk_add_f32 v[8:9], v[10:11], 1.0 op_sel_hi:[1,0]
	s_nop 0
	v_div_scale_f32 v10, s[50:51], v9, v9, 1.0
	v_rcp_f32_e32 v11, v10
	s_nop 0
	v_fma_f32 v16, -v10, v11, 1.0
	v_fmac_f32_e32 v11, v16, v11
	v_div_scale_f32 v16, vcc, 1.0, v9, 1.0
	v_mul_f32_e32 v17, v16, v11
	v_fma_f32 v18, -v10, v17, v16
	v_fmac_f32_e32 v17, v18, v11
	v_fma_f32 v10, -v10, v17, v16
	v_div_fmas_f32 v10, v10, v11, v17
	v_div_fixup_f32 v9, v10, v9, 1.0
	v_div_scale_f32 v10, s[50:51], v8, v8, 1.0
	v_rcp_f32_e32 v11, v10
	s_nop 0
	v_fma_f32 v16, -v10, v11, 1.0
	v_fmac_f32_e32 v11, v16, v11
	v_div_scale_f32 v16, vcc, 1.0, v8, 1.0
	v_mul_f32_e32 v17, v16, v11
	v_fma_f32 v18, -v10, v17, v16
	v_fmac_f32_e32 v17, v18, v11
	v_fma_f32 v10, -v10, v17, v16
	v_div_fmas_f32 v10, v10, v11, v17
	v_div_fixup_f32 v8, v10, v8, 1.0
	s_waitcnt lgkmcnt(0)
	v_mov_b32_e32 v10, v4
	v_mov_b32_e32 v11, v6
	v_pk_mul_f32 v[8:9], v[10:11], v[8:9]
	v_pk_add_f32 v[10:11], v[12:13], 1.0 op_sel_hi:[1,0]
	s_nop 0
	v_div_scale_f32 v4, s[50:51], v11, v11, 1.0
	v_rcp_f32_e32 v6, v4
	s_nop 0
	v_fma_f32 v12, -v4, v6, 1.0
	v_fmac_f32_e32 v6, v12, v6
	v_div_scale_f32 v12, vcc, 1.0, v11, 1.0
	v_mul_f32_e32 v13, v12, v6
	v_fma_f32 v16, -v4, v13, v12
	v_fmac_f32_e32 v13, v16, v6
	v_fma_f32 v4, -v4, v13, v12
	v_div_fmas_f32 v4, v4, v6, v13
	v_div_fixup_f32 v11, v4, v11, 1.0
	v_div_scale_f32 v4, s[50:51], v10, v10, 1.0
	v_rcp_f32_e32 v6, v4
	s_nop 0
	v_fma_f32 v12, -v4, v6, 1.0
	v_fmac_f32_e32 v6, v12, v6
	v_div_scale_f32 v12, vcc, 1.0, v10, 1.0
	v_mul_f32_e32 v13, v12, v6
	v_fma_f32 v16, -v4, v13, v12
	v_fmac_f32_e32 v13, v16, v6
	v_fma_f32 v4, -v4, v13, v12
	v_div_fmas_f32 v4, v4, v6, v13
	v_div_fixup_f32 v10, v4, v10, 1.0
	v_mov_b32_e32 v6, v5
	v_pk_mul_f32 v[4:5], v[6:7], v[10:11]
	v_and_b32_sdwa v6, v9, v95 dst_sel:DWORD dst_unused:UNUSED_PAD src0_sel:WORD_1 src1_sel:DWORD
	v_and_b32_sdwa v7, v8, v95 dst_sel:DWORD dst_unused:UNUSED_PAD src0_sel:WORD_1 src1_sel:DWORD
	v_add3_u32 v7, v8, v7, s39
	v_add3_u32 v6, v9, v6, s39
	v_and_b32_sdwa v8, v5, v95 dst_sel:DWORD dst_unused:UNUSED_PAD src0_sel:WORD_1 src1_sel:DWORD
	v_and_b32_sdwa v9, v4, v95 dst_sel:DWORD dst_unused:UNUSED_PAD src0_sel:WORD_1 src1_sel:DWORD
	v_add3_u32 v5, v5, v8, s39
	v_add3_u32 v4, v4, v9, s39
	v_and_b32_e32 v5, 0xffff0000, v5
	v_and_b32_e32 v4, 0xffff0000, v4
	v_or_b32_sdwa v5, v5, v6 dst_sel:DWORD dst_unused:UNUSED_PAD src0_sel:DWORD src1_sel:WORD_1
	v_or_b32_sdwa v4, v4, v7 dst_sel:DWORD dst_unused:UNUSED_PAD src0_sel:DWORD src1_sel:WORD_1
	global_store_dwordx2 v[14:15], v[4:5], off
	s_cbranch_scc1 .LBB0_513
	s_mov_b64 s[26:27], 0

; DEVI float sigmoidf_(float x) { return 1.f / (1.f + __expf(-x)); }
; template <int BR, int IN, int OUT>
; DEVI void p6_branch(const Params& P, int pm, int pn, float* macc, char* smem, int tid) {
;     ...
; #pragma unroll 8
;   for (int q = 0; q < 16; ++q) {
;     const int id = tid + 256 * q, row = id >> 5, c4 = id & 31;
;     const long grow = (long)pm * 128 + row;
;     const int gcol = pn * 128 + c4 * 4;
;     float4 a = *reinterpret_cast<const float4*>(T + row * 128 + c4 * 4);
;     float g[4];
;     load4bf(Z + grow * NCOL + (9 + BR) * 1024 + gcol, g);
;     float v[4] = {sigmoidf_(g[0]) * a.x, sigmoidf_(g[1]) * a.y, sigmoidf_(g[2]) * a.z, sigmoidf_(g[3]) * a.w};
;     if (IN == 1) {
;       float mo[4]; load4bf(M + grow * 1024 + gcol, mo);
;       v[0] += mo[0]; v[1] += mo[1]; v[2] += mo[2]; v[3] += mo[3];
;     }
;     if (IN == 2) {
;       float4 mo = *reinterpret_cast<const float4*>(macc + grow * 1024 + gcol);
.LBB0_737:
	s_cmp_lg_u32 s24, 0
	s_cbranch_scc1 .Leh2LBB0737b
	v_add_u32_e32 v242, s24, v91
	v_ashrrev_i32_e32 v240, 5, v242
	v_ashrrev_i32_e32 v241, 31, v240
	v_lshl_add_u64 v[244:245], s[46:47], 0, v[240:241]
	v_mov_b64_e32 v[240:241], s[44:45]
	v_mad_u64_u32 v[246:247], s[48:49], v244, s22, v[240:241]
	v_mad_i32_i24 v247, v245, s22, v247
	v_lshl_add_u64 v[246:247], v[246:247], 0, v[4:5]
	v_add_co_u32_e32 v246, vcc, 0x5000, v246
	s_nop 1
	v_addc_co_u32_e32 v247, vcc, 0, v247, vcc
	global_load_dwordx2 v[208:209], v[246:247], off offset:2048
	v_add_u32_e32 v242, s24, v91
	v_ashrrev_i32_e32 v240, 5, v242
	v_ashrrev_i32_e32 v241, 31, v240
	v_lshl_add_u64 v[244:245], s[46:47], 0, v[240:241]
	v_lshlrev_b64 v[246:247], 11, v[244:245]
	v_lshl_add_u64 v[246:247], v[0:1], 0, v[246:247]
	global_load_dwordx2 v[210:211], v[246:247], off
	v_add_u32_e32 v242, s24, v91
	v_mov_b64_e32 v[240:241], s[44:45]
	v_add_u32_e32 v243, 0x100, v242
	v_ashrrev_i32_e32 v244, 5, v243
	v_ashrrev_i32_e32 v245, 31, v244
	v_lshl_add_u64 v[246:247], s[46:47], 0, v[244:245]
	v_mad_u64_u32 v[244:245], s[48:49], v246, s22, v[240:241]
	v_mad_i32_i24 v245, v247, s22, v245
	v_lshl_add_u64 v[244:245], v[244:245], 0, v[4:5]
	v_add_co_u32_e32 v244, vcc, s21, v244
	s_nop 1
	v_addc_co_u32_e32 v245, vcc, 0, v245, vcc
	global_load_dwordx2 v[212:213], v[244:245], off offset:2048
	v_add_u32_e32 v240, s24, v91
	v_add_u32_e32 v241, 0x100, v240
	v_ashrrev_i32_e32 v242, 5, v241
	v_ashrrev_i32_e32 v243, 31, v242
	v_lshl_add_u64 v[244:245], s[46:47], 0, v[242:243]
	v_lshlrev_b64 v[242:243], 11, v[244:245]
	v_lshl_add_u64 v[242:243], v[0:1], 0, v[242:243]
	global_load_dwordx2 v[214:215], v[242:243], off
	v_add_u32_e32 v242, s24, v91
	v_mov_b64_e32 v[240:241], s[44:45]
	v_add_u32_e32 v243, 0x200, v242
	v_ashrrev_i32_e32 v244, 5, v243
	v_ashrrev_i32_e32 v245, 31, v244
	v_lshl_add_u64 v[246:247], s[46:47], 0, v[244:245]
	v_mad_u64_u32 v[244:245], s[48:49], v246, s22, v[240:241]
	v_mad_i32_i24 v245, v247, s22, v245
	v_lshl_add_u64 v[244:245], v[244:245], 0, v[4:5]
	v_add_co_u32_e32 v244, vcc, s21, v244
	s_nop 1
	v_addc_co_u32_e32 v245, vcc, 0, v245, vcc
	global_load_dwordx2 v[216:217], v[244:245], off offset:2048
	v_add_u32_e32 v240, s24, v91
	v_add_u32_e32 v241, 0x200, v240
	v_ashrrev_i32_e32 v242, 5, v241
	v_ashrrev_i32_e32 v243, 31, v242
	v_lshl_add_u64 v[244:245], s[46:47], 0, v[242:243]
	v_lshlrev_b64 v[242:243], 11, v[244:245]
	v_lshl_add_u64 v[242:243], v[0:1], 0, v[242:243]
	global_load_dwordx2 v[218:219], v[242:243], off
	v_add_u32_e32 v242, s24, v91
	v_mov_b64_e32 v[240:241], s[44:45]
	v_add_u32_e32 v243, 0x300, v242
	v_ashrrev_i32_e32 v244, 5, v243
	v_ashrrev_i32_e32 v245, 31, v244
	v_lshl_add_u64 v[246:247], s[46:47], 0, v[244:245]
	v_mad_u64_u32 v[244:245], s[48:49], v246, s22, v[240:241]
	v_mad_i32_i24 v245, v247, s22, v245
	v_lshl_add_u64 v[244:245], v[244:245], 0, v[4:5]
	v_add_co_u32_e32 v244, vcc, s21, v244
	s_nop 1
	v_addc_co_u32_e32 v245, vcc, 0, v245, vcc
	global_load_dwordx2 v[220:221], v[244:245], off offset:2048
	v_add_u32_e32 v240, s24, v91
	v_add_u32_e32 v241, 0x300, v240
	v_ashrrev_i32_e32 v242, 5, v241
	v_ashrrev_i32_e32 v243, 31, v242
	v_lshl_add_u64 v[244:245], s[46:47], 0, v[242:243]
	v_lshlrev_b64 v[242:243], 11, v[244:245]
	v_lshl_add_u64 v[242:243], v[0:1], 0, v[242:243]
	global_load_dwordx2 v[222:223], v[242:243], off
	v_add_u32_e32 v242, s24, v91
	v_mov_b64_e32 v[240:241], s[44:45]
	v_add_u32_e32 v243, 0x400, v242
	v_ashrrev_i32_e32 v244, 5, v243
	v_ashrrev_i32_e32 v245, 31, v244
	v_lshl_add_u64 v[246:247], s[46:47], 0, v[244:245]
	v_mad_u64_u32 v[244:245], s[48:49], v246, s22, v[240:241]
	v_mad_i32_i24 v245, v247, s22, v245
	v_lshl_add_u64 v[244:245], v[244:245], 0, v[4:5]
	v_add_co_u32_e32 v244, vcc, s21, v244
	s_nop 1
	v_addc_co_u32_e32 v245, vcc, 0, v245, vcc
	global_load_dwordx2 v[224:225], v[244:245], off offset:2048
	v_add_u32_e32 v240, s24, v91
	v_add_u32_e32 v241, 0x400, v240
	v_ashrrev_i32_e32 v242, 5, v241
	v_ashrrev_i32_e32 v243, 31, v242
	v_lshl_add_u64 v[244:245], s[46:47], 0, v[242:243]
	v_lshlrev_b64 v[242:243], 11, v[244:245]
	v_lshl_add_u64 v[242:243], v[0:1], 0, v[242:243]
	global_load_dwordx2 v[226:227], v[242:243], off
	v_add_u32_e32 v242, s24, v91
	v_mov_b64_e32 v[240:241], s[44:45]
	v_add_u32_e32 v243, 0x500, v242
	v_ashrrev_i32_e32 v244, 5, v243
	v_ashrrev_i32_e32 v245, 31, v244
	v_lshl_add_u64 v[246:247], s[46:47], 0, v[244:245]
	v_mad_u64_u32 v[244:245], s[48:49], v246, s22, v[240:241]
	v_mad_i32_i24 v245, v247, s22, v245
	v_lshl_add_u64 v[244:245], v[244:245], 0, v[4:5]
	v_add_co_u32_e32 v244, vcc, s21, v244
	s_nop 1
	v_addc_co_u32_e32 v245, vcc, 0, v245, vcc
	global_load_dwordx2 v[228:229], v[244:245], off offset:2048
	v_add_u32_e32 v240, s24, v91
	v_add_u32_e32 v241, 0x500, v240
	v_ashrrev_i32_e32 v242, 5, v241
	v_ashrrev_i32_e32 v243, 31, v242
	v_lshl_add_u64 v[244:245], s[46:47], 0, v[242:243]
	v_lshlrev_b64 v[242:243], 11, v[244:245]
	v_lshl_add_u64 v[242:243], v[0:1], 0, v[242:243]
	global_load_dwordx2 v[230:231], v[242:243], off
	v_add_u32_e32 v242, s24, v91
	v_mov_b64_e32 v[240:241], s[44:45]
	v_add_u32_e32 v243, 0x600, v242
	v_ashrrev_i32_e32 v244, 5, v243
	v_ashrrev_i32_e32 v245, 31, v244
	v_lshl_add_u64 v[246:247], s[46:47], 0, v[244:245]
	v_mad_u64_u32 v[244:245], s[48:49], v246, s22, v[240:241]
	v_mad_i32_i24 v245, v247, s22, v245
	v_lshl_add_u64 v[244:245], v[244:245], 0, v[4:5]
	v_add_co_u32_e32 v244, vcc, s21, v244
	s_nop 1
	v_addc_co_u32_e32 v245, vcc, 0, v245, vcc
	global_load_dwordx2 v[232:233], v[244:245], off offset:2048
	v_add_u32_e32 v240, s24, v91
	v_add_u32_e32 v241, 0x600, v240
	v_ashrrev_i32_e32 v242, 5, v241
; DEVI float sigmoidf_(float x) { return 1.f / (1.f + __expf(-x)); }
; template <int BR, int IN, int OUT>
; DEVI void p6_branch(const Params& P, int pm, int pn, float* macc, char* smem, int tid) {
;     ...
; #pragma unroll 8
;   for (int q = 0; q < 16; ++q) {
;     const int id = tid + 256 * q, row = id >> 5, c4 = id & 31;
;     const long grow = (long)pm * 128 + row;
;     const int gcol = pn * 128 + c4 * 4;
;     float4 a = *reinterpret_cast<const float4*>(T + row * 128 + c4 * 4);
;     float g[4];
;     load4bf(Z + grow * NCOL + (9 + BR) * 1024 + gcol, g);
;     float v[4] = {sigmoidf_(g[0]) * a.x, sigmoidf_(g[1]) * a.y, sigmoidf_(g[2]) * a.z, sigmoidf_(g[3]) * a.w};
;     if (IN == 1) {
;       float mo[4]; load4bf(M + grow * 1024 + gcol, mo);
;       v[0] += mo[0]; v[1] += mo[1]; v[2] += mo[2]; v[3] += mo[3];
;     }
;     if (IN == 2) {
;       float4 mo = *reinterpret_cast<const float4*>(macc + grow * 1024 + gcol);
	v_ashrrev_i32_e32 v243, 31, v242
	v_lshl_add_u64 v[244:245], s[46:47], 0, v[242:243]
	v_lshlrev_b64 v[242:243], 11, v[244:245]
	v_lshl_add_u64 v[242:243], v[0:1], 0, v[242:243]
	global_load_dwordx2 v[234:235], v[242:243], off
	v_add_u32_e32 v242, s24, v91
	v_mov_b64_e32 v[240:241], s[44:45]
	v_add_u32_e32 v242, 0x700, v242
	v_ashrrev_i32_e32 v242, 5, v242
	v_ashrrev_i32_e32 v243, 31, v242
	v_lshl_add_u64 v[244:245], s[46:47], 0, v[242:243]
	v_mad_u64_u32 v[240:241], s[48:49], v244, s22, v[240:241]
	v_mad_i32_i24 v241, v245, s22, v241
	v_lshl_add_u64 v[240:241], v[240:241], 0, v[4:5]
	v_add_co_u32_e32 v240, vcc, s21, v240
	s_nop 1
	v_addc_co_u32_e32 v241, vcc, 0, v241, vcc
	global_load_dwordx2 v[236:237], v[240:241], off offset:2048
	v_add_u32_e32 v242, s24, v91
	v_add_u32_e32 v242, 0x700, v242
	v_ashrrev_i32_e32 v242, 5, v242
	v_ashrrev_i32_e32 v243, 31, v242
	v_lshl_add_u64 v[244:245], s[46:47], 0, v[242:243]
	v_lshlrev_b64 v[240:241], 11, v[244:245]
	v_lshl_add_u64 v[240:241], v[0:1], 0, v[240:241]
	global_load_dwordx2 v[238:239], v[240:241], off
	v_add_u32_e32 v242, s24, v91
	v_add_u32_e32 v242, 0x800, v242
	v_ashrrev_i32_e32 v240, 5, v242
	v_ashrrev_i32_e32 v241, 31, v240
	v_lshl_add_u64 v[244:245], s[46:47], 0, v[240:241]
	v_mov_b64_e32 v[240:241], s[44:45]
	v_mad_u64_u32 v[246:247], s[48:49], v244, s22, v[240:241]
	v_mad_i32_i24 v247, v245, s22, v247
	v_lshl_add_u64 v[246:247], v[246:247], 0, v[4:5]
	v_add_co_u32_e32 v246, vcc, 0x5000, v246
	s_nop 1
	v_addc_co_u32_e32 v247, vcc, 0, v247, vcc
	global_load_dwordx2 v[28:29], v[246:247], off offset:2048
	v_add_u32_e32 v242, s24, v91
	v_add_u32_e32 v242, 0x800, v242
	v_ashrrev_i32_e32 v240, 5, v242
	v_ashrrev_i32_e32 v241, 31, v240
	v_lshl_add_u64 v[244:245], s[46:47], 0, v[240:241]
	v_lshlrev_b64 v[246:247], 11, v[244:245]
	v_lshl_add_u64 v[246:247], v[0:1], 0, v[246:247]
	global_load_dwordx2 v[30:31], v[246:247], off
	v_add_u32_e32 v242, s24, v91
	v_add_u32_e32 v242, 0x800, v242
	v_mov_b64_e32 v[240:241], s[44:45]
	v_add_u32_e32 v243, 0x100, v242
	v_ashrrev_i32_e32 v244, 5, v243
	v_ashrrev_i32_e32 v245, 31, v244
	v_lshl_add_u64 v[246:247], s[46:47], 0, v[244:245]
	v_mad_u64_u32 v[244:245], s[48:49], v246, s22, v[240:241]
	v_mad_i32_i24 v245, v247, s22, v245
	v_lshl_add_u64 v[244:245], v[244:245], 0, v[4:5]
	v_add_co_u32_e32 v244, vcc, s21, v244
	s_nop 1
	v_addc_co_u32_e32 v245, vcc, 0, v245, vcc
	global_load_dwordx2 v[32:33], v[244:245], off offset:2048
	v_add_u32_e32 v240, s24, v91
	v_add_u32_e32 v240, 0x800, v240
	v_add_u32_e32 v241, 0x100, v240
	v_ashrrev_i32_e32 v242, 5, v241
	v_ashrrev_i32_e32 v243, 31, v242
	v_lshl_add_u64 v[244:245], s[46:47], 0, v[242:243]
	v_lshlrev_b64 v[242:243], 11, v[244:245]
	v_lshl_add_u64 v[242:243], v[0:1], 0, v[242:243]
	global_load_dwordx2 v[34:35], v[242:243], off
	v_add_u32_e32 v242, s24, v91
	v_add_u32_e32 v242, 0x800, v242
	v_mov_b64_e32 v[240:241], s[44:45]
	v_add_u32_e32 v243, 0x200, v242
	v_ashrrev_i32_e32 v244, 5, v243
	v_ashrrev_i32_e32 v245, 31, v244
	v_lshl_add_u64 v[246:247], s[46:47], 0, v[244:245]
	v_mad_u64_u32 v[244:245], s[48:49], v246, s22, v[240:241]
	v_mad_i32_i24 v245, v247, s22, v245
	v_lshl_add_u64 v[244:245], v[244:245], 0, v[4:5]
	v_add_co_u32_e32 v244, vcc, s21, v244
	s_nop 1
	v_addc_co_u32_e32 v245, vcc, 0, v245, vcc
	global_load_dwordx2 v[36:37], v[244:245], off offset:2048
	v_add_u32_e32 v240, s24, v91
	v_add_u32_e32 v240, 0x800, v240
	v_add_u32_e32 v241, 0x200, v240
	v_ashrrev_i32_e32 v242, 5, v241
	v_ashrrev_i32_e32 v243, 31, v242
	v_lshl_add_u64 v[244:245], s[46:47], 0, v[242:243]
	v_lshlrev_b64 v[242:243], 11, v[244:245]
	v_lshl_add_u64 v[242:243], v[0:1], 0, v[242:243]
	global_load_dwordx2 v[38:39], v[242:243], off
	v_add_u32_e32 v242, s24, v91
	v_add_u32_e32 v242, 0x800, v242
	v_mov_b64_e32 v[240:241], s[44:45]
	v_add_u32_e32 v243, 0x300, v242
	v_ashrrev_i32_e32 v244, 5, v243
	v_ashrrev_i32_e32 v245, 31, v244
	v_lshl_add_u64 v[246:247], s[46:47], 0, v[244:245]
	v_mad_u64_u32 v[244:245], s[48:49], v246, s22, v[240:241]
	v_mad_i32_i24 v245, v247, s22, v245
	v_lshl_add_u64 v[244:245], v[244:245], 0, v[4:5]
	v_add_co_u32_e32 v244, vcc, s21, v244
	s_nop 1
	v_addc_co_u32_e32 v245, vcc, 0, v245, vcc
	global_load_dwordx2 v[40:41], v[244:245], off offset:2048
	v_add_u32_e32 v240, s24, v91
	v_add_u32_e32 v240, 0x800, v240
	v_add_u32_e32 v241, 0x300, v240
	v_ashrrev_i32_e32 v242, 5, v241
	v_ashrrev_i32_e32 v243, 31, v242
	v_lshl_add_u64 v[244:245], s[46:47], 0, v[242:243]
	v_lshlrev_b64 v[242:243], 11, v[244:245]
	v_lshl_add_u64 v[242:243], v[0:1], 0, v[242:243]
	global_load_dwordx2 v[42:43], v[242:243], off
	v_add_u32_e32 v242, s24, v91
	v_add_u32_e32 v242, 0x800, v242
	v_mov_b64_e32 v[240:241], s[44:45]
	v_add_u32_e32 v243, 0x400, v242
	v_ashrrev_i32_e32 v244, 5, v243
	v_ashrrev_i32_e32 v245, 31, v244
	v_lshl_add_u64 v[246:247], s[46:47], 0, v[244:245]
	v_mad_u64_u32 v[244:245], s[48:49], v246, s22, v[240:241]
	v_mad_i32_i24 v245, v247, s22, v245
	v_lshl_add_u64 v[244:245], v[244:245], 0, v[4:5]
	v_add_co_u32_e32 v244, vcc, s21, v244
	s_nop 1
	v_addc_co_u32_e32 v245, vcc, 0, v245, vcc
	global_load_dwordx2 v[44:45], v[244:245], off offset:2048
	v_add_u32_e32 v240, s24, v91
	v_add_u32_e32 v240, 0x800, v240
	v_add_u32_e32 v241, 0x400, v240
	v_ashrrev_i32_e32 v242, 5, v241
	v_ashrrev_i32_e32 v243, 31, v242
	v_lshl_add_u64 v[244:245], s[46:47], 0, v[242:243]
	v_lshlrev_b64 v[242:243], 11, v[244:245]
	v_lshl_add_u64 v[242:243], v[0:1], 0, v[242:243]
	global_load_dwordx2 v[46:47], v[242:243], off
	v_add_u32_e32 v242, s24, v91
	v_add_u32_e32 v242, 0x800, v242
	v_mov_b64_e32 v[240:241], s[44:45]
	v_add_u32_e32 v243, 0x500, v242
; DEVI float sigmoidf_(float x) { return 1.f / (1.f + __expf(-x)); }
; template <int BR, int IN, int OUT>
; DEVI void p6_branch(const Params& P, int pm, int pn, float* macc, char* smem, int tid) {
;     ...
; #pragma unroll 8
;   for (int q = 0; q < 16; ++q) {
;     const int id = tid + 256 * q, row = id >> 5, c4 = id & 31;
;     const long grow = (long)pm * 128 + row;
;     const int gcol = pn * 128 + c4 * 4;
;     float4 a = *reinterpret_cast<const float4*>(T + row * 128 + c4 * 4);
;     float g[4];
;     load4bf(Z + grow * NCOL + (9 + BR) * 1024 + gcol, g);
;     float v[4] = {sigmoidf_(g[0]) * a.x, sigmoidf_(g[1]) * a.y, sigmoidf_(g[2]) * a.z, sigmoidf_(g[3]) * a.w};
;     if (IN == 1) {
;       float mo[4]; load4bf(M + grow * 1024 + gcol, mo);
;       v[0] += mo[0]; v[1] += mo[1]; v[2] += mo[2]; v[3] += mo[3];
	v_ashrrev_i32_e32 v244, 5, v243
	v_ashrrev_i32_e32 v245, 31, v244
	v_lshl_add_u64 v[246:247], s[46:47], 0, v[244:245]
	v_mad_u64_u32 v[244:245], s[48:49], v246, s22, v[240:241]
	v_mad_i32_i24 v245, v247, s22, v245
	v_lshl_add_u64 v[244:245], v[244:245], 0, v[4:5]
	v_add_co_u32_e32 v244, vcc, s21, v244
	s_nop 1
	v_addc_co_u32_e32 v245, vcc, 0, v245, vcc
	global_load_dwordx2 v[48:49], v[244:245], off offset:2048
	v_add_u32_e32 v240, s24, v91
	v_add_u32_e32 v240, 0x800, v240
	v_add_u32_e32 v241, 0x500, v240
	v_ashrrev_i32_e32 v242, 5, v241
	v_ashrrev_i32_e32 v243, 31, v242
	v_lshl_add_u64 v[244:245], s[46:47], 0, v[242:243]
	v_lshlrev_b64 v[242:243], 11, v[244:245]
	v_lshl_add_u64 v[242:243], v[0:1], 0, v[242:243]
	global_load_dwordx2 v[50:51], v[242:243], off
	v_add_u32_e32 v242, s24, v91
	v_add_u32_e32 v242, 0x800, v242
	v_mov_b64_e32 v[240:241], s[44:45]
	v_add_u32_e32 v243, 0x600, v242
	v_ashrrev_i32_e32 v244, 5, v243
	v_ashrrev_i32_e32 v245, 31, v244
	v_lshl_add_u64 v[246:247], s[46:47], 0, v[244:245]
	v_mad_u64_u32 v[244:245], s[48:49], v246, s22, v[240:241]
	v_mad_i32_i24 v245, v247, s22, v245
	v_lshl_add_u64 v[244:245], v[244:245], 0, v[4:5]
	v_add_co_u32_e32 v244, vcc, s21, v244
	s_nop 1
	v_addc_co_u32_e32 v245, vcc, 0, v245, vcc
	global_load_dwordx2 v[52:53], v[244:245], off offset:2048
	v_add_u32_e32 v240, s24, v91
	v_add_u32_e32 v240, 0x800, v240
	v_add_u32_e32 v241, 0x600, v240
	v_ashrrev_i32_e32 v242, 5, v241
	v_ashrrev_i32_e32 v243, 31, v242
	v_lshl_add_u64 v[244:245], s[46:47], 0, v[242:243]
	v_lshlrev_b64 v[242:243], 11, v[244:245]
	v_lshl_add_u64 v[242:243], v[0:1], 0, v[242:243]
	global_load_dwordx2 v[54:55], v[242:243], off
	v_add_u32_e32 v242, s24, v91
	v_add_u32_e32 v242, 0x800, v242
	v_mov_b64_e32 v[240:241], s[44:45]
	v_add_u32_e32 v242, 0x700, v242
	v_ashrrev_i32_e32 v242, 5, v242
	v_ashrrev_i32_e32 v243, 31, v242
	v_lshl_add_u64 v[244:245], s[46:47], 0, v[242:243]
	v_mad_u64_u32 v[240:241], s[48:49], v244, s22, v[240:241]
	v_mad_i32_i24 v241, v245, s22, v241
	v_lshl_add_u64 v[240:241], v[240:241], 0, v[4:5]
	v_add_co_u32_e32 v240, vcc, s21, v240
	s_nop 1
	v_addc_co_u32_e32 v241, vcc, 0, v241, vcc
	global_load_dwordx2 v[56:57], v[240:241], off offset:2048
	v_add_u32_e32 v242, s24, v91
	v_add_u32_e32 v242, 0x800, v242
	v_add_u32_e32 v242, 0x700, v242
	v_ashrrev_i32_e32 v242, 5, v242
	v_ashrrev_i32_e32 v243, 31, v242
	v_lshl_add_u64 v[244:245], s[46:47], 0, v[242:243]
	v_lshlrev_b64 v[240:241], 11, v[244:245]
	v_lshl_add_u64 v[240:241], v[0:1], 0, v[240:241]
	global_load_dwordx2 v[58:59], v[240:241], off
	s_waitcnt vmcnt(0)
	s_branch .Leh2LBB0737c
.Leh2LBB0737b:
	v_mov_b32_e32 v208, v28
	v_mov_b32_e32 v209, v29
	v_mov_b32_e32 v210, v30
	v_mov_b32_e32 v211, v31
	v_mov_b32_e32 v212, v32
	v_mov_b32_e32 v213, v33
	v_mov_b32_e32 v214, v34
	v_mov_b32_e32 v215, v35
	v_mov_b32_e32 v216, v36
	v_mov_b32_e32 v217, v37
	v_mov_b32_e32 v218, v38
	v_mov_b32_e32 v219, v39
	v_mov_b32_e32 v220, v40
	v_mov_b32_e32 v221, v41
	v_mov_b32_e32 v222, v42
	v_mov_b32_e32 v223, v43
	v_mov_b32_e32 v224, v44
	v_mov_b32_e32 v225, v45
	v_mov_b32_e32 v226, v46
	v_mov_b32_e32 v227, v47
	v_mov_b32_e32 v228, v48
	v_mov_b32_e32 v229, v49
	v_mov_b32_e32 v230, v50
	v_mov_b32_e32 v231, v51
	v_mov_b32_e32 v232, v52
	v_mov_b32_e32 v233, v53
	v_mov_b32_e32 v234, v54
	v_mov_b32_e32 v235, v55
	v_mov_b32_e32 v236, v56
	v_mov_b32_e32 v237, v57
	v_mov_b32_e32 v238, v58
	v_mov_b32_e32 v239, v59
.Leh2LBB0737c:
	s_nop 0
	v_add_u32_e32 v8, s24, v91
	v_ashrrev_i32_e32 v6, 5, v8
	v_ashrrev_i32_e32 v7, 31, v6
	v_lshl_add_u64 v[10:11], s[46:47], 0, v[6:7]
	v_lshl_or_b32 v9, v6, 9, v152
	v_mov_b64_e32 v[6:7], s[44:45]
	v_mad_u64_u32 v[12:13], s[48:49], v10, s22, v[6:7]
	v_mad_i32_i24 v13, v11, s22, v13
	v_lshl_add_u64 v[12:13], v[12:13], 0, v[4:5]
	v_add_co_u32_e32 v12, vcc, 0x5000, v12
	s_addk_i32 s24, 0x800
	s_nop 0
	v_addc_co_u32_e32 v13, vcc, 0, v13, vcc
	v_mov_b32_e32 v12, v208
	v_mov_b32_e32 v13, v209
	s_cmpk_lg_i32 s24, 0x1000
	v_lshlrev_b32_e32 v14, 16, v12
	v_and_b32_e32 v12, 0xffff0000, v12
	v_lshlrev_b32_e32 v16, 16, v13
	v_mul_f32_e32 v12, 0xbfb8aa3b, v12
	v_and_b32_e32 v13, 0xffff0000, v13
	v_exp_f32_e32 v15, v12
	v_mul_f32_e32 v12, 0xbfb8aa3b, v16
	v_exp_f32_e32 v16, v12
	v_mul_f32_e32 v12, 0xbfb8aa3b, v13
	v_exp_f32_e32 v17, v12
	v_lshlrev_b64 v[12:13], 11, v[10:11]
	v_lshl_add_u64 v[12:13], v[0:1], 0, v[12:13]
	v_mov_b32_e32 v12, v210
	v_mov_b32_e32 v13, v211
	v_mul_f32_e32 v14, 0xbfb8aa3b, v14
	v_exp_f32_e32 v14, v14
	v_lshlrev_b64 v[10:11], 12, v[10:11]
	v_lshl_add_u64 v[22:23], v[2:3], 0, v[10:11]
	v_pk_add_f32 v[14:15], v[14:15], 1.0 op_sel_hi:[1,0]
	v_lshlrev_b32_e32 v18, 16, v12
	v_and_b32_e32 v19, 0xffff0000, v12
	v_lshlrev_b32_e32 v20, 16, v13
	v_and_b32_e32 v21, 0xffff0000, v13
	ds_read_b128 v[10:13], v9
	v_div_scale_f32 v9, s[48:49], v15, v15, 1.0
	v_rcp_f32_e32 v24, v9
	s_nop 0
	v_fma_f32 v25, -v9, v24, 1.0
	v_fmac_f32_e32 v24, v25, v24
	v_div_scale_f32 v25, vcc, 1.0, v15, 1.0
	v_mul_f32_e32 v26, v25, v24
	v_fma_f32 v27, -v9, v26, v25
	v_fmac_f32_e32 v26, v27, v24
	v_fma_f32 v9, -v9, v26, v25
	v_div_fmas_f32 v9, v9, v24, v26
	v_div_fixup_f32 v15, v9, v15, 1.0
	v_div_scale_f32 v9, s[48:49], v14, v14, 1.0
	v_rcp_f32_e32 v24, v9
	s_nop 0
	v_fma_f32 v25, -v9, v24, 1.0
	v_fmac_f32_e32 v24, v25, v24
	v_div_scale_f32 v25, vcc, 1.0, v14, 1.0
	v_mul_f32_e32 v26, v25, v24
	v_fma_f32 v27, -v9, v26, v25
	v_fmac_f32_e32 v26, v27, v24
	v_fma_f32 v9, -v9, v26, v25
	v_div_fmas_f32 v9, v9, v24, v26
	v_div_fixup_f32 v14, v9, v14, 1.0
	s_waitcnt lgkmcnt(0)
; DEVI float sigmoidf_(float x) { return 1.f / (1.f + __expf(-x)); }
; template <int BR, int IN, int OUT>
; DEVI void p6_branch(const Params& P, int pm, int pn, float* macc, char* smem, int tid) {
;     ...
; #pragma unroll 8
;   for (int q = 0; q < 16; ++q) {
;     const int id = tid + 256 * q, row = id >> 5, c4 = id & 31;
;     const long grow = (long)pm * 128 + row;
;     const int gcol = pn * 128 + c4 * 4;
;     float4 a = *reinterpret_cast<const float4*>(T + row * 128 + c4 * 4);
;     float g[4];
;     load4bf(Z + grow * NCOL + (9 + BR) * 1024 + gcol, g);
;     float v[4] = {sigmoidf_(g[0]) * a.x, sigmoidf_(g[1]) * a.y, sigmoidf_(g[2]) * a.z, sigmoidf_(g[3]) * a.w};
;     if (IN == 1) {
;       float mo[4]; load4bf(M + grow * 1024 + gcol, mo);
;       v[0] += mo[0]; v[1] += mo[1]; v[2] += mo[2]; v[3] += mo[3];
;     }
;     if (IN == 2) {
;       float4 mo = *reinterpret_cast<const float4*>(macc + grow * 1024 + gcol);
;       v[0] += mo.x; v[1] += mo.y; v[2] += mo.z; v[3] += mo.w;
;     }
;     if (OUT == 1) *reinterpret_cast<float4*>(macc + grow * 1024 + gcol) = make_float4(v[0], v[1], v[2], v[3]);
;     else store4bf(M + grow * 1024 + gcol, v);
;   }
	v_pk_fma_f32 v[10:11], v[10:11], v[14:15], v[18:19]
	v_pk_add_f32 v[14:15], v[16:17], 1.0 op_sel_hi:[1,0]
	s_nop 0
	v_div_scale_f32 v9, s[48:49], v15, v15, 1.0
	v_rcp_f32_e32 v16, v9
	s_nop 0
	v_fma_f32 v17, -v9, v16, 1.0
	v_fmac_f32_e32 v16, v17, v16
	v_div_scale_f32 v17, vcc, 1.0, v15, 1.0
	v_mul_f32_e32 v18, v17, v16
	v_fma_f32 v19, -v9, v18, v17
	v_fmac_f32_e32 v18, v19, v16
	v_fma_f32 v9, -v9, v18, v17
	v_div_fmas_f32 v9, v9, v16, v18
	v_div_fixup_f32 v15, v9, v15, 1.0
	v_div_scale_f32 v9, s[48:49], v14, v14, 1.0
	v_rcp_f32_e32 v16, v9
	s_nop 0
	v_fma_f32 v17, -v9, v16, 1.0
	v_fmac_f32_e32 v16, v17, v16
	v_div_scale_f32 v17, vcc, 1.0, v14, 1.0
	v_mul_f32_e32 v18, v17, v16
	v_fma_f32 v19, -v9, v18, v17
	v_fmac_f32_e32 v18, v19, v16
	v_fma_f32 v9, -v9, v18, v17
	v_div_fmas_f32 v9, v9, v16, v18
	v_div_fixup_f32 v14, v9, v14, 1.0
	v_pk_fma_f32 v[12:13], v[12:13], v[14:15], v[20:21]
	v_add_u32_e32 v9, 0x100, v8
	global_store_dwordx4 v[22:23], v[10:13], off
	s_nop 1
	v_ashrrev_i32_e32 v10, 5, v9
	v_ashrrev_i32_e32 v11, 31, v10
	v_lshl_add_u64 v[12:13], s[46:47], 0, v[10:11]
	v_lshl_or_b32 v9, v10, 9, v152
	v_mad_u64_u32 v[10:11], s[48:49], v12, s22, v[6:7]
	v_mad_i32_i24 v11, v13, s22, v11
	v_lshl_add_u64 v[10:11], v[10:11], 0, v[4:5]
	v_add_co_u32_e32 v10, vcc, s21, v10
	s_nop 1
	v_addc_co_u32_e32 v11, vcc, 0, v11, vcc
	v_mov_b32_e32 v10, v212
	v_mov_b32_e32 v11, v213
	v_lshlrev_b32_e32 v14, 16, v10
	v_and_b32_e32 v10, 0xffff0000, v10
	v_lshlrev_b32_e32 v16, 16, v11
	v_mul_f32_e32 v10, 0xbfb8aa3b, v10
	v_and_b32_e32 v11, 0xffff0000, v11
	v_exp_f32_e32 v15, v10
	v_mul_f32_e32 v10, 0xbfb8aa3b, v16
	v_exp_f32_e32 v16, v10
	v_mul_f32_e32 v10, 0xbfb8aa3b, v11
	v_exp_f32_e32 v17, v10
	v_lshlrev_b64 v[10:11], 11, v[12:13]
	v_lshl_add_u64 v[10:11], v[0:1], 0, v[10:11]
	v_mov_b32_e32 v10, v214
	v_mov_b32_e32 v11, v215
	v_mul_f32_e32 v14, 0xbfb8aa3b, v14
	v_exp_f32_e32 v14, v14
	v_lshlrev_b32_e32 v18, 16, v10
	v_and_b32_e32 v19, 0xffff0000, v10
	v_lshlrev_b32_e32 v20, 16, v11
	v_and_b32_e32 v21, 0xffff0000, v11
	v_lshlrev_b64 v[10:11], 12, v[12:13]
	v_pk_add_f32 v[14:15], v[14:15], 1.0 op_sel_hi:[1,0]
	v_lshl_add_u64 v[22:23], v[2:3], 0, v[10:11]
	ds_read_b128 v[10:13], v9
	v_div_scale_f32 v9, s[48:49], v15, v15, 1.0
	v_rcp_f32_e32 v24, v9
	s_nop 0
	v_fma_f32 v25, -v9, v24, 1.0
	v_fmac_f32_e32 v24, v25, v24
	v_div_scale_f32 v25, vcc, 1.0, v15, 1.0
	v_mul_f32_e32 v26, v25, v24
	v_fma_f32 v27, -v9, v26, v25
	v_fmac_f32_e32 v26, v27, v24
	v_fma_f32 v9, -v9, v26, v25
	v_div_fmas_f32 v9, v9, v24, v26
	v_div_fixup_f32 v15, v9, v15, 1.0
	v_div_scale_f32 v9, s[48:49], v14, v14, 1.0
	v_rcp_f32_e32 v24, v9
	s_nop 0
	v_fma_f32 v25, -v9, v24, 1.0
	v_fmac_f32_e32 v24, v25, v24
	v_div_scale_f32 v25, vcc, 1.0, v14, 1.0
	v_mul_f32_e32 v26, v25, v24
	v_fma_f32 v27, -v9, v26, v25
	v_fmac_f32_e32 v26, v27, v24
	v_fma_f32 v9, -v9, v26, v25
	v_div_fmas_f32 v9, v9, v24, v26
	v_div_fixup_f32 v14, v9, v14, 1.0
	s_waitcnt lgkmcnt(0)
	v_pk_fma_f32 v[10:11], v[10:11], v[14:15], v[18:19]
	v_pk_add_f32 v[14:15], v[16:17], 1.0 op_sel_hi:[1,0]
	s_nop 0
	v_div_scale_f32 v9, s[48:49], v15, v15, 1.0
	v_rcp_f32_e32 v16, v9
	s_nop 0
	v_fma_f32 v17, -v9, v16, 1.0
	v_fmac_f32_e32 v16, v17, v16
	v_div_scale_f32 v17, vcc, 1.0, v15, 1.0
	v_mul_f32_e32 v18, v17, v16
	v_fma_f32 v19, -v9, v18, v17
	v_fmac_f32_e32 v18, v19, v16
	v_fma_f32 v9, -v9, v18, v17
	v_div_fmas_f32 v9, v9, v16, v18
	v_div_fixup_f32 v15, v9, v15, 1.0
	v_div_scale_f32 v9, s[48:49], v14, v14, 1.0
	v_rcp_f32_e32 v16, v9
	s_nop 0
	v_fma_f32 v17, -v9, v16, 1.0
	v_fmac_f32_e32 v16, v17, v16
	v_div_scale_f32 v17, vcc, 1.0, v14, 1.0
	v_mul_f32_e32 v18, v17, v16
	v_fma_f32 v19, -v9, v18, v17
	v_fmac_f32_e32 v18, v19, v16
	v_fma_f32 v9, -v9, v18, v17
	v_div_fmas_f32 v9, v9, v16, v18
	v_div_fixup_f32 v14, v9, v14, 1.0
	v_pk_fma_f32 v[12:13], v[12:13], v[14:15], v[20:21]
	v_add_u32_e32 v9, 0x200, v8
	global_store_dwordx4 v[22:23], v[10:13], off
	s_nop 1
	v_ashrrev_i32_e32 v10, 5, v9
	v_ashrrev_i32_e32 v11, 31, v10
	v_lshl_add_u64 v[12:13], s[46:47], 0, v[10:11]
	v_lshl_or_b32 v9, v10, 9, v152
	v_mad_u64_u32 v[10:11], s[48:49], v12, s22, v[6:7]
	v_mad_i32_i24 v11, v13, s22, v11
	v_lshl_add_u64 v[10:11], v[10:11], 0, v[4:5]
	v_add_co_u32_e32 v10, vcc, s21, v10
	s_nop 1
	v_addc_co_u32_e32 v11, vcc, 0, v11, vcc
	v_mov_b32_e32 v10, v216
	v_mov_b32_e32 v11, v217
	v_lshlrev_b32_e32 v14, 16, v10
	v_and_b32_e32 v10, 0xffff0000, v10
	v_lshlrev_b32_e32 v16, 16, v11
	v_mul_f32_e32 v10, 0xbfb8aa3b, v10
	v_and_b32_e32 v11, 0xffff0000, v11
	v_exp_f32_e32 v15, v10
	v_mul_f32_e32 v10, 0xbfb8aa3b, v16
	v_exp_f32_e32 v16, v10
	v_mul_f32_e32 v10, 0xbfb8aa3b, v11
	v_exp_f32_e32 v17, v10
	v_lshlrev_b64 v[10:11], 11, v[12:13]
	v_lshl_add_u64 v[10:11], v[0:1], 0, v[10:11]
	v_mov_b32_e32 v10, v218
	v_mov_b32_e32 v11, v219
	v_mul_f32_e32 v14, 0xbfb8aa3b, v14
	v_exp_f32_e32 v14, v14
	v_lshlrev_b32_e32 v18, 16, v10
	v_and_b32_e32 v19, 0xffff0000, v10
	v_lshlrev_b32_e32 v20, 16, v11
	v_and_b32_e32 v21, 0xffff0000, v11
	v_lshlrev_b64 v[10:11], 12, v[12:13]
	v_pk_add_f32 v[14:15], v[14:15], 1.0 op_sel_hi:[1,0]
	v_lshl_add_u64 v[22:23], v[2:3], 0, v[10:11]
	ds_read_b128 v[10:13], v9
	v_div_scale_f32 v9, s[48:49], v15, v15, 1.0
	v_rcp_f32_e32 v24, v9
	s_nop 0
	v_fma_f32 v25, -v9, v24, 1.0
	v_fmac_f32_e32 v24, v25, v24
	v_div_scale_f32 v25, vcc, 1.0, v15, 1.0
	v_mul_f32_e32 v26, v25, v24
	v_fma_f32 v27, -v9, v26, v25
	v_fmac_f32_e32 v26, v27, v24
	v_fma_f32 v9, -v9, v26, v25
	v_div_fmas_f32 v9, v9, v24, v26
	v_div_fixup_f32 v15, v9, v15, 1.0
	v_div_scale_f32 v9, s[48:49], v14, v14, 1.0
	v_rcp_f32_e32 v24, v9
	s_nop 0
	v_fma_f32 v25, -v9, v24, 1.0
	v_fmac_f32_e32 v24, v25, v24
	v_div_scale_f32 v25, vcc, 1.0, v14, 1.0
	v_mul_f32_e32 v26, v25, v24
	v_fma_f32 v27, -v9, v26, v25
	v_fmac_f32_e32 v26, v27, v24
	v_fma_f32 v9, -v9, v26, v25
	v_div_fmas_f32 v9, v9, v24, v26
	v_div_fixup_f32 v14, v9, v14, 1.0
	s_waitcnt lgkmcnt(0)
; DEVI float sigmoidf_(float x) { return 1.f / (1.f + __expf(-x)); }
; template <int BR, int IN, int OUT>
; DEVI void p6_branch(const Params& P, int pm, int pn, float* macc, char* smem, int tid) {
;     ...
; #pragma unroll 8
;   for (int q = 0; q < 16; ++q) {
;     const int id = tid + 256 * q, row = id >> 5, c4 = id & 31;
;     const long grow = (long)pm * 128 + row;
;     const int gcol = pn * 128 + c4 * 4;
;     float4 a = *reinterpret_cast<const float4*>(T + row * 128 + c4 * 4);
;     float g[4];
;     load4bf(Z + grow * NCOL + (9 + BR) * 1024 + gcol, g);
;     float v[4] = {sigmoidf_(g[0]) * a.x, sigmoidf_(g[1]) * a.y, sigmoidf_(g[2]) * a.z, sigmoidf_(g[3]) * a.w};
;     if (IN == 1) {
;       float mo[4]; load4bf(M + grow * 1024 + gcol, mo);
;       v[0] += mo[0]; v[1] += mo[1]; v[2] += mo[2]; v[3] += mo[3];
;     }
;     if (IN == 2) {
;       float4 mo = *reinterpret_cast<const float4*>(macc + grow * 1024 + gcol);
;       v[0] += mo.x; v[1] += mo.y; v[2] += mo.z; v[3] += mo.w;
;     }
;     if (OUT == 1) *reinterpret_cast<float4*>(macc + grow * 1024 + gcol) = make_float4(v[0], v[1], v[2], v[3]);
;     else store4bf(M + grow * 1024 + gcol, v);
;   }
	v_pk_fma_f32 v[10:11], v[10:11], v[14:15], v[18:19]
	v_pk_add_f32 v[14:15], v[16:17], 1.0 op_sel_hi:[1,0]
	s_nop 0
	v_div_scale_f32 v9, s[48:49], v15, v15, 1.0
	v_rcp_f32_e32 v16, v9
	s_nop 0
	v_fma_f32 v17, -v9, v16, 1.0
	v_fmac_f32_e32 v16, v17, v16
	v_div_scale_f32 v17, vcc, 1.0, v15, 1.0
	v_mul_f32_e32 v18, v17, v16
	v_fma_f32 v19, -v9, v18, v17
	v_fmac_f32_e32 v18, v19, v16
	v_fma_f32 v9, -v9, v18, v17
	v_div_fmas_f32 v9, v9, v16, v18
	v_div_fixup_f32 v15, v9, v15, 1.0
	v_div_scale_f32 v9, s[48:49], v14, v14, 1.0
	v_rcp_f32_e32 v16, v9
	s_nop 0
	v_fma_f32 v17, -v9, v16, 1.0
	v_fmac_f32_e32 v16, v17, v16
	v_div_scale_f32 v17, vcc, 1.0, v14, 1.0
	v_mul_f32_e32 v18, v17, v16
	v_fma_f32 v19, -v9, v18, v17
	v_fmac_f32_e32 v18, v19, v16
	v_fma_f32 v9, -v9, v18, v17
	v_div_fmas_f32 v9, v9, v16, v18
	v_div_fixup_f32 v14, v9, v14, 1.0
	v_pk_fma_f32 v[12:13], v[12:13], v[14:15], v[20:21]
	v_add_u32_e32 v9, 0x300, v8
	global_store_dwordx4 v[22:23], v[10:13], off
	s_nop 1
	v_ashrrev_i32_e32 v10, 5, v9
	v_ashrrev_i32_e32 v11, 31, v10
	v_lshl_add_u64 v[12:13], s[46:47], 0, v[10:11]
	v_lshl_or_b32 v9, v10, 9, v152
	v_mad_u64_u32 v[10:11], s[48:49], v12, s22, v[6:7]
	v_mad_i32_i24 v11, v13, s22, v11
	v_lshl_add_u64 v[10:11], v[10:11], 0, v[4:5]
	v_add_co_u32_e32 v10, vcc, s21, v10
	s_nop 1
	v_addc_co_u32_e32 v11, vcc, 0, v11, vcc
	v_mov_b32_e32 v10, v220
	v_mov_b32_e32 v11, v221
	v_lshlrev_b32_e32 v14, 16, v10
	v_and_b32_e32 v10, 0xffff0000, v10
	v_lshlrev_b32_e32 v16, 16, v11
	v_mul_f32_e32 v10, 0xbfb8aa3b, v10
	v_and_b32_e32 v11, 0xffff0000, v11
	v_exp_f32_e32 v15, v10
	v_mul_f32_e32 v10, 0xbfb8aa3b, v16
	v_exp_f32_e32 v16, v10
	v_mul_f32_e32 v10, 0xbfb8aa3b, v11
	v_exp_f32_e32 v17, v10
	v_lshlrev_b64 v[10:11], 11, v[12:13]
	v_lshl_add_u64 v[10:11], v[0:1], 0, v[10:11]
	v_mov_b32_e32 v10, v222
	v_mov_b32_e32 v11, v223
	v_mul_f32_e32 v14, 0xbfb8aa3b, v14
	v_exp_f32_e32 v14, v14
	v_lshlrev_b32_e32 v18, 16, v10
	v_and_b32_e32 v19, 0xffff0000, v10
	v_lshlrev_b32_e32 v20, 16, v11
	v_and_b32_e32 v21, 0xffff0000, v11
	v_lshlrev_b64 v[10:11], 12, v[12:13]
	v_pk_add_f32 v[14:15], v[14:15], 1.0 op_sel_hi:[1,0]
	v_lshl_add_u64 v[22:23], v[2:3], 0, v[10:11]
	ds_read_b128 v[10:13], v9
	v_div_scale_f32 v9, s[48:49], v15, v15, 1.0
	v_rcp_f32_e32 v24, v9
	s_nop 0
	v_fma_f32 v25, -v9, v24, 1.0
	v_fmac_f32_e32 v24, v25, v24
	v_div_scale_f32 v25, vcc, 1.0, v15, 1.0
	v_mul_f32_e32 v26, v25, v24
	v_fma_f32 v27, -v9, v26, v25
	v_fmac_f32_e32 v26, v27, v24
	v_fma_f32 v9, -v9, v26, v25
	v_div_fmas_f32 v9, v9, v24, v26
	v_div_fixup_f32 v15, v9, v15, 1.0
	v_div_scale_f32 v9, s[48:49], v14, v14, 1.0
	v_rcp_f32_e32 v24, v9
	s_nop 0
	v_fma_f32 v25, -v9, v24, 1.0
	v_fmac_f32_e32 v24, v25, v24
	v_div_scale_f32 v25, vcc, 1.0, v14, 1.0
	v_mul_f32_e32 v26, v25, v24
	v_fma_f32 v27, -v9, v26, v25
	v_fmac_f32_e32 v26, v27, v24
	v_fma_f32 v9, -v9, v26, v25
	v_div_fmas_f32 v9, v9, v24, v26
	v_div_fixup_f32 v14, v9, v14, 1.0
	s_waitcnt lgkmcnt(0)
	v_pk_fma_f32 v[10:11], v[10:11], v[14:15], v[18:19]
	v_pk_add_f32 v[14:15], v[16:17], 1.0 op_sel_hi:[1,0]
	s_nop 0
	v_div_scale_f32 v9, s[48:49], v15, v15, 1.0
	v_rcp_f32_e32 v16, v9
	s_nop 0
	v_fma_f32 v17, -v9, v16, 1.0
	v_fmac_f32_e32 v16, v17, v16
	v_div_scale_f32 v17, vcc, 1.0, v15, 1.0
	v_mul_f32_e32 v18, v17, v16
	v_fma_f32 v19, -v9, v18, v17
	v_fmac_f32_e32 v18, v19, v16
	v_fma_f32 v9, -v9, v18, v17
	v_div_fmas_f32 v9, v9, v16, v18
	v_div_fixup_f32 v15, v9, v15, 1.0
	v_div_scale_f32 v9, s[48:49], v14, v14, 1.0
	v_rcp_f32_e32 v16, v9
	s_nop 0
	v_fma_f32 v17, -v9, v16, 1.0
	v_fmac_f32_e32 v16, v17, v16
	v_div_scale_f32 v17, vcc, 1.0, v14, 1.0
	v_mul_f32_e32 v18, v17, v16
	v_fma_f32 v19, -v9, v18, v17
	v_fmac_f32_e32 v18, v19, v16
	v_fma_f32 v9, -v9, v18, v17
	v_div_fmas_f32 v9, v9, v16, v18
	v_div_fixup_f32 v14, v9, v14, 1.0
	v_pk_fma_f32 v[12:13], v[12:13], v[14:15], v[20:21]
	v_add_u32_e32 v9, 0x400, v8
	global_store_dwordx4 v[22:23], v[10:13], off
	s_nop 1
	v_ashrrev_i32_e32 v10, 5, v9
	v_ashrrev_i32_e32 v11, 31, v10
	v_lshl_add_u64 v[12:13], s[46:47], 0, v[10:11]
	v_lshl_or_b32 v9, v10, 9, v152
	v_mad_u64_u32 v[10:11], s[48:49], v12, s22, v[6:7]
	v_mad_i32_i24 v11, v13, s22, v11
	v_lshl_add_u64 v[10:11], v[10:11], 0, v[4:5]
	v_add_co_u32_e32 v10, vcc, s21, v10
	s_nop 1
	v_addc_co_u32_e32 v11, vcc, 0, v11, vcc
	v_mov_b32_e32 v10, v224
	v_mov_b32_e32 v11, v225
	v_lshlrev_b32_e32 v14, 16, v10
	v_and_b32_e32 v10, 0xffff0000, v10
	v_lshlrev_b32_e32 v16, 16, v11
	v_mul_f32_e32 v10, 0xbfb8aa3b, v10
	v_and_b32_e32 v11, 0xffff0000, v11
	v_exp_f32_e32 v15, v10
	v_mul_f32_e32 v10, 0xbfb8aa3b, v16
	v_exp_f32_e32 v16, v10
	v_mul_f32_e32 v10, 0xbfb8aa3b, v11
	v_exp_f32_e32 v17, v10
	v_lshlrev_b64 v[10:11], 11, v[12:13]
	v_lshl_add_u64 v[10:11], v[0:1], 0, v[10:11]
	v_mov_b32_e32 v10, v226
	v_mov_b32_e32 v11, v227
	v_mul_f32_e32 v14, 0xbfb8aa3b, v14
	v_exp_f32_e32 v14, v14
	v_lshlrev_b32_e32 v18, 16, v10
	v_and_b32_e32 v19, 0xffff0000, v10
	v_lshlrev_b32_e32 v20, 16, v11
	v_and_b32_e32 v21, 0xffff0000, v11
	v_lshlrev_b64 v[10:11], 12, v[12:13]
	v_pk_add_f32 v[14:15], v[14:15], 1.0 op_sel_hi:[1,0]
	v_lshl_add_u64 v[22:23], v[2:3], 0, v[10:11]
	ds_read_b128 v[10:13], v9
	v_div_scale_f32 v9, s[48:49], v15, v15, 1.0
	v_rcp_f32_e32 v24, v9
	s_nop 0
	v_fma_f32 v25, -v9, v24, 1.0
	v_fmac_f32_e32 v24, v25, v24
	v_div_scale_f32 v25, vcc, 1.0, v15, 1.0
	v_mul_f32_e32 v26, v25, v24
	v_fma_f32 v27, -v9, v26, v25
	v_fmac_f32_e32 v26, v27, v24
	v_fma_f32 v9, -v9, v26, v25
	v_div_fmas_f32 v9, v9, v24, v26
	v_div_fixup_f32 v15, v9, v15, 1.0
	v_div_scale_f32 v9, s[48:49], v14, v14, 1.0
	v_rcp_f32_e32 v24, v9
	s_nop 0
	v_fma_f32 v25, -v9, v24, 1.0
	v_fmac_f32_e32 v24, v25, v24
	v_div_scale_f32 v25, vcc, 1.0, v14, 1.0
	v_mul_f32_e32 v26, v25, v24
	v_fma_f32 v27, -v9, v26, v25
	v_fmac_f32_e32 v26, v27, v24
	v_fma_f32 v9, -v9, v26, v25
	v_div_fmas_f32 v9, v9, v24, v26
	v_div_fixup_f32 v14, v9, v14, 1.0
	s_waitcnt lgkmcnt(0)
; DEVI float sigmoidf_(float x) { return 1.f / (1.f + __expf(-x)); }
; template <int BR, int IN, int OUT>
; DEVI void p6_branch(const Params& P, int pm, int pn, float* macc, char* smem, int tid) {
;     ...
; #pragma unroll 8
;   for (int q = 0; q < 16; ++q) {
;     const int id = tid + 256 * q, row = id >> 5, c4 = id & 31;
;     const long grow = (long)pm * 128 + row;
;     const int gcol = pn * 128 + c4 * 4;
;     float4 a = *reinterpret_cast<const float4*>(T + row * 128 + c4 * 4);
;     float g[4];
;     load4bf(Z + grow * NCOL + (9 + BR) * 1024 + gcol, g);
;     float v[4] = {sigmoidf_(g[0]) * a.x, sigmoidf_(g[1]) * a.y, sigmoidf_(g[2]) * a.z, sigmoidf_(g[3]) * a.w};
;     if (IN == 1) {
;       float mo[4]; load4bf(M + grow * 1024 + gcol, mo);
;       v[0] += mo[0]; v[1] += mo[1]; v[2] += mo[2]; v[3] += mo[3];
;     }
;     if (IN == 2) {
;       float4 mo = *reinterpret_cast<const float4*>(macc + grow * 1024 + gcol);
;       v[0] += mo.x; v[1] += mo.y; v[2] += mo.z; v[3] += mo.w;
;     }
;     if (OUT == 1) *reinterpret_cast<float4*>(macc + grow * 1024 + gcol) = make_float4(v[0], v[1], v[2], v[3]);
;     else store4bf(M + grow * 1024 + gcol, v);
;   }
	v_pk_fma_f32 v[10:11], v[10:11], v[14:15], v[18:19]
	v_pk_add_f32 v[14:15], v[16:17], 1.0 op_sel_hi:[1,0]
	s_nop 0
	v_div_scale_f32 v9, s[48:49], v15, v15, 1.0
	v_rcp_f32_e32 v16, v9
	s_nop 0
	v_fma_f32 v17, -v9, v16, 1.0
	v_fmac_f32_e32 v16, v17, v16
	v_div_scale_f32 v17, vcc, 1.0, v15, 1.0
	v_mul_f32_e32 v18, v17, v16
	v_fma_f32 v19, -v9, v18, v17
	v_fmac_f32_e32 v18, v19, v16
	v_fma_f32 v9, -v9, v18, v17
	v_div_fmas_f32 v9, v9, v16, v18
	v_div_fixup_f32 v15, v9, v15, 1.0
	v_div_scale_f32 v9, s[48:49], v14, v14, 1.0
	v_rcp_f32_e32 v16, v9
	s_nop 0
	v_fma_f32 v17, -v9, v16, 1.0
	v_fmac_f32_e32 v16, v17, v16
	v_div_scale_f32 v17, vcc, 1.0, v14, 1.0
	v_mul_f32_e32 v18, v17, v16
	v_fma_f32 v19, -v9, v18, v17
	v_fmac_f32_e32 v18, v19, v16
	v_fma_f32 v9, -v9, v18, v17
	v_div_fmas_f32 v9, v9, v16, v18
	v_div_fixup_f32 v14, v9, v14, 1.0
	v_pk_fma_f32 v[12:13], v[12:13], v[14:15], v[20:21]
	v_add_u32_e32 v9, 0x500, v8
	global_store_dwordx4 v[22:23], v[10:13], off
	s_nop 1
	v_ashrrev_i32_e32 v10, 5, v9
	v_ashrrev_i32_e32 v11, 31, v10
	v_lshl_add_u64 v[12:13], s[46:47], 0, v[10:11]
	v_lshl_or_b32 v9, v10, 9, v152
	v_mad_u64_u32 v[10:11], s[48:49], v12, s22, v[6:7]
	v_mad_i32_i24 v11, v13, s22, v11
	v_lshl_add_u64 v[10:11], v[10:11], 0, v[4:5]
	v_add_co_u32_e32 v10, vcc, s21, v10
	s_nop 1
	v_addc_co_u32_e32 v11, vcc, 0, v11, vcc
	v_mov_b32_e32 v10, v228
	v_mov_b32_e32 v11, v229
	v_lshlrev_b32_e32 v14, 16, v10
	v_and_b32_e32 v10, 0xffff0000, v10
	v_lshlrev_b32_e32 v16, 16, v11
	v_mul_f32_e32 v10, 0xbfb8aa3b, v10
	v_and_b32_e32 v11, 0xffff0000, v11
	v_exp_f32_e32 v15, v10
	v_mul_f32_e32 v10, 0xbfb8aa3b, v16
	v_exp_f32_e32 v16, v10
	v_mul_f32_e32 v10, 0xbfb8aa3b, v11
	v_exp_f32_e32 v17, v10
	v_lshlrev_b64 v[10:11], 11, v[12:13]
	v_lshl_add_u64 v[10:11], v[0:1], 0, v[10:11]
	v_mov_b32_e32 v10, v230
	v_mov_b32_e32 v11, v231
	v_mul_f32_e32 v14, 0xbfb8aa3b, v14
	v_exp_f32_e32 v14, v14
	v_lshlrev_b32_e32 v18, 16, v10
	v_and_b32_e32 v19, 0xffff0000, v10
	v_lshlrev_b32_e32 v20, 16, v11
	v_and_b32_e32 v21, 0xffff0000, v11
	v_lshlrev_b64 v[10:11], 12, v[12:13]
	v_pk_add_f32 v[14:15], v[14:15], 1.0 op_sel_hi:[1,0]
	v_lshl_add_u64 v[22:23], v[2:3], 0, v[10:11]
	ds_read_b128 v[10:13], v9
	v_div_scale_f32 v9, s[48:49], v15, v15, 1.0
	v_rcp_f32_e32 v24, v9
	s_nop 0
	v_fma_f32 v25, -v9, v24, 1.0
	v_fmac_f32_e32 v24, v25, v24
	v_div_scale_f32 v25, vcc, 1.0, v15, 1.0
	v_mul_f32_e32 v26, v25, v24
	v_fma_f32 v27, -v9, v26, v25
	v_fmac_f32_e32 v26, v27, v24
	v_fma_f32 v9, -v9, v26, v25
	v_div_fmas_f32 v9, v9, v24, v26
	v_div_fixup_f32 v15, v9, v15, 1.0
	v_div_scale_f32 v9, s[48:49], v14, v14, 1.0
	v_rcp_f32_e32 v24, v9
	s_nop 0
	v_fma_f32 v25, -v9, v24, 1.0
	v_fmac_f32_e32 v24, v25, v24
	v_div_scale_f32 v25, vcc, 1.0, v14, 1.0
	v_mul_f32_e32 v26, v25, v24
	v_fma_f32 v27, -v9, v26, v25
	v_fmac_f32_e32 v26, v27, v24
	v_fma_f32 v9, -v9, v26, v25
	v_div_fmas_f32 v9, v9, v24, v26
	v_div_fixup_f32 v14, v9, v14, 1.0
	s_waitcnt lgkmcnt(0)
	v_pk_fma_f32 v[10:11], v[10:11], v[14:15], v[18:19]
	v_pk_add_f32 v[14:15], v[16:17], 1.0 op_sel_hi:[1,0]
	s_nop 0
	v_div_scale_f32 v9, s[48:49], v15, v15, 1.0
	v_rcp_f32_e32 v16, v9
	s_nop 0
	v_fma_f32 v17, -v9, v16, 1.0
	v_fmac_f32_e32 v16, v17, v16
	v_div_scale_f32 v17, vcc, 1.0, v15, 1.0
	v_mul_f32_e32 v18, v17, v16
	v_fma_f32 v19, -v9, v18, v17
	v_fmac_f32_e32 v18, v19, v16
	v_fma_f32 v9, -v9, v18, v17
	v_div_fmas_f32 v9, v9, v16, v18
	v_div_fixup_f32 v15, v9, v15, 1.0
	v_div_scale_f32 v9, s[48:49], v14, v14, 1.0
	v_rcp_f32_e32 v16, v9
	s_nop 0
	v_fma_f32 v17, -v9, v16, 1.0
	v_fmac_f32_e32 v16, v17, v16
	v_div_scale_f32 v17, vcc, 1.0, v14, 1.0
	v_mul_f32_e32 v18, v17, v16
	v_fma_f32 v19, -v9, v18, v17
	v_fmac_f32_e32 v18, v19, v16
	v_fma_f32 v9, -v9, v18, v17
	v_div_fmas_f32 v9, v9, v16, v18
	v_div_fixup_f32 v14, v9, v14, 1.0
	v_pk_fma_f32 v[12:13], v[12:13], v[14:15], v[20:21]
	v_add_u32_e32 v9, 0x600, v8
	global_store_dwordx4 v[22:23], v[10:13], off
	v_add_u32_e32 v8, 0x700, v8
	v_ashrrev_i32_e32 v8, 5, v8
	v_ashrrev_i32_e32 v10, 5, v9
	v_ashrrev_i32_e32 v11, 31, v10
	v_lshl_add_u64 v[12:13], s[46:47], 0, v[10:11]
	v_lshl_or_b32 v9, v10, 9, v152
	v_mad_u64_u32 v[10:11], s[48:49], v12, s22, v[6:7]
	v_mad_i32_i24 v11, v13, s22, v11
	v_lshl_add_u64 v[10:11], v[10:11], 0, v[4:5]
	v_add_co_u32_e32 v10, vcc, s21, v10
	s_nop 1
	v_addc_co_u32_e32 v11, vcc, 0, v11, vcc
	v_mov_b32_e32 v10, v232
	v_mov_b32_e32 v11, v233
	v_lshlrev_b32_e32 v14, 16, v10
	v_and_b32_e32 v10, 0xffff0000, v10
	v_lshlrev_b32_e32 v16, 16, v11
	v_mul_f32_e32 v10, 0xbfb8aa3b, v10
	v_and_b32_e32 v11, 0xffff0000, v11
	v_exp_f32_e32 v15, v10
	v_mul_f32_e32 v10, 0xbfb8aa3b, v16
	v_exp_f32_e32 v16, v10
	v_mul_f32_e32 v10, 0xbfb8aa3b, v11
	v_exp_f32_e32 v17, v10
	v_lshlrev_b64 v[10:11], 11, v[12:13]
	v_lshl_add_u64 v[10:11], v[0:1], 0, v[10:11]
	v_mov_b32_e32 v10, v234
	v_mov_b32_e32 v11, v235
	v_mul_f32_e32 v14, 0xbfb8aa3b, v14
	v_exp_f32_e32 v14, v14
	v_lshlrev_b32_e32 v18, 16, v10
	v_and_b32_e32 v19, 0xffff0000, v10
	v_lshlrev_b32_e32 v20, 16, v11
	v_and_b32_e32 v21, 0xffff0000, v11
	v_lshlrev_b64 v[10:11], 12, v[12:13]
	v_pk_add_f32 v[14:15], v[14:15], 1.0 op_sel_hi:[1,0]
	v_lshl_add_u64 v[22:23], v[2:3], 0, v[10:11]
	ds_read_b128 v[10:13], v9
	v_div_scale_f32 v9, s[48:49], v15, v15, 1.0
	v_rcp_f32_e32 v24, v9
	s_nop 0
	v_fma_f32 v25, -v9, v24, 1.0
	v_fmac_f32_e32 v24, v25, v24
	v_div_scale_f32 v25, vcc, 1.0, v15, 1.0
	v_mul_f32_e32 v26, v25, v24
	v_fma_f32 v27, -v9, v26, v25
	v_fmac_f32_e32 v26, v27, v24
	v_fma_f32 v9, -v9, v26, v25
	v_div_fmas_f32 v9, v9, v24, v26
	v_div_fixup_f32 v15, v9, v15, 1.0
	v_div_scale_f32 v9, s[48:49], v14, v14, 1.0
	v_rcp_f32_e32 v24, v9
	s_nop 0
	v_fma_f32 v25, -v9, v24, 1.0
	v_fmac_f32_e32 v24, v25, v24
	v_div_scale_f32 v25, vcc, 1.0, v14, 1.0
	v_mul_f32_e32 v26, v25, v24
	v_fma_f32 v27, -v9, v26, v25
	v_fmac_f32_e32 v26, v27, v24
	v_fma_f32 v9, -v9, v26, v25
	v_div_fmas_f32 v9, v9, v24, v26
	v_div_fixup_f32 v14, v9, v14, 1.0
	s_waitcnt lgkmcnt(0)
; DEVI float sigmoidf_(float x) { return 1.f / (1.f + __expf(-x)); }
; template <int BR, int IN, int OUT>
; DEVI void p6_branch(const Params& P, int pm, int pn, float* macc, char* smem, int tid) {
;     ...
; #pragma unroll 8
;   for (int q = 0; q < 16; ++q) {
;     const int id = tid + 256 * q, row = id >> 5, c4 = id & 31;
;     const long grow = (long)pm * 128 + row;
;     const int gcol = pn * 128 + c4 * 4;
;     float4 a = *reinterpret_cast<const float4*>(T + row * 128 + c4 * 4);
;     float g[4];
;     load4bf(Z + grow * NCOL + (9 + BR) * 1024 + gcol, g);
;     float v[4] = {sigmoidf_(g[0]) * a.x, sigmoidf_(g[1]) * a.y, sigmoidf_(g[2]) * a.z, sigmoidf_(g[3]) * a.w};
;     if (IN == 1) {
;       float mo[4]; load4bf(M + grow * 1024 + gcol, mo);
;       v[0] += mo[0]; v[1] += mo[1]; v[2] += mo[2]; v[3] += mo[3];
;     }
;     if (IN == 2) {
;       float4 mo = *reinterpret_cast<const float4*>(macc + grow * 1024 + gcol);
;       v[0] += mo.x; v[1] += mo.y; v[2] += mo.z; v[3] += mo.w;
;     }
;     if (OUT == 1) *reinterpret_cast<float4*>(macc + grow * 1024 + gcol) = make_float4(v[0], v[1], v[2], v[3]);
;     else store4bf(M + grow * 1024 + gcol, v);
;   }
	v_pk_fma_f32 v[10:11], v[10:11], v[14:15], v[18:19]
	v_pk_add_f32 v[14:15], v[16:17], 1.0 op_sel_hi:[1,0]
	s_nop 0
	v_div_scale_f32 v9, s[48:49], v15, v15, 1.0
	v_rcp_f32_e32 v16, v9
	s_nop 0
	v_fma_f32 v17, -v9, v16, 1.0
	v_fmac_f32_e32 v16, v17, v16
	v_div_scale_f32 v17, vcc, 1.0, v15, 1.0
	v_mul_f32_e32 v18, v17, v16
	v_fma_f32 v19, -v9, v18, v17
	v_fmac_f32_e32 v18, v19, v16
	v_fma_f32 v9, -v9, v18, v17
	v_div_fmas_f32 v9, v9, v16, v18
	v_div_fixup_f32 v15, v9, v15, 1.0
	v_div_scale_f32 v9, s[48:49], v14, v14, 1.0
	v_rcp_f32_e32 v16, v9
	s_nop 0
	v_fma_f32 v17, -v9, v16, 1.0
	v_fmac_f32_e32 v16, v17, v16
	v_div_scale_f32 v17, vcc, 1.0, v14, 1.0
	v_mul_f32_e32 v18, v17, v16
	v_fma_f32 v19, -v9, v18, v17
	v_fmac_f32_e32 v18, v19, v16
	v_fma_f32 v9, -v9, v18, v17
	v_div_fmas_f32 v9, v9, v16, v18
	v_div_fixup_f32 v14, v9, v14, 1.0
	v_pk_fma_f32 v[12:13], v[12:13], v[14:15], v[20:21]
	v_ashrrev_i32_e32 v9, 31, v8
	global_store_dwordx4 v[22:23], v[10:13], off
	s_nop 1
	v_lshl_add_u64 v[10:11], s[46:47], 0, v[8:9]
	v_mad_u64_u32 v[6:7], s[48:49], v10, s22, v[6:7]
	v_mad_i32_i24 v7, v11, s22, v7
	v_lshl_add_u64 v[6:7], v[6:7], 0, v[4:5]
	v_add_co_u32_e32 v6, vcc, s21, v6
	v_lshl_or_b32 v8, v8, 9, v152
	s_nop 0
	v_addc_co_u32_e32 v7, vcc, 0, v7, vcc
	v_mov_b32_e32 v6, v236
	v_mov_b32_e32 v7, v237
	v_lshlrev_b32_e32 v9, 16, v6
	v_and_b32_e32 v6, 0xffff0000, v6
	v_lshlrev_b32_e32 v14, 16, v7
	v_mul_f32_e32 v6, 0xbfb8aa3b, v6
	v_and_b32_e32 v7, 0xffff0000, v7
	v_exp_f32_e32 v13, v6
	v_mul_f32_e32 v6, 0xbfb8aa3b, v14
	v_exp_f32_e32 v14, v6
	v_mul_f32_e32 v6, 0xbfb8aa3b, v7
	v_exp_f32_e32 v15, v6
	v_lshlrev_b64 v[6:7], 11, v[10:11]
	v_lshl_add_u64 v[6:7], v[0:1], 0, v[6:7]
	v_mov_b32_e32 v6, v238
	v_mov_b32_e32 v7, v239
	v_mul_f32_e32 v9, 0xbfb8aa3b, v9
	v_exp_f32_e32 v12, v9
	v_lshlrev_b32_e32 v16, 16, v6
	v_pk_add_f32 v[12:13], v[12:13], 1.0 op_sel_hi:[1,0]
	v_and_b32_e32 v17, 0xffff0000, v6
	v_div_scale_f32 v20, s[48:49], v13, v13, 1.0
	v_rcp_f32_e32 v21, v20
	v_lshlrev_b32_e32 v18, 16, v7
	v_and_b32_e32 v19, 0xffff0000, v7
	v_lshlrev_b64 v[6:7], 12, v[10:11]
	v_fma_f32 v22, -v20, v21, 1.0
	v_fmac_f32_e32 v21, v22, v21
	v_div_scale_f32 v22, vcc, 1.0, v13, 1.0
	v_mul_f32_e32 v23, v22, v21
	v_fma_f32 v24, -v20, v23, v22
	v_fmac_f32_e32 v23, v24, v21
	v_fma_f32 v20, -v20, v23, v22
	v_div_fmas_f32 v20, v20, v21, v23
	v_div_fixup_f32 v13, v20, v13, 1.0
	v_div_scale_f32 v20, s[48:49], v12, v12, 1.0
	v_rcp_f32_e32 v21, v20
	v_lshl_add_u64 v[10:11], v[2:3], 0, v[6:7]
	ds_read_b128 v[6:9], v8
	v_fma_f32 v22, -v20, v21, 1.0
	v_fmac_f32_e32 v21, v22, v21
	v_div_scale_f32 v22, vcc, 1.0, v12, 1.0
	v_mul_f32_e32 v23, v22, v21
	v_fma_f32 v24, -v20, v23, v22
	v_fmac_f32_e32 v23, v24, v21
	v_fma_f32 v20, -v20, v23, v22
	v_div_fmas_f32 v20, v20, v21, v23
	v_div_fixup_f32 v12, v20, v12, 1.0
	s_waitcnt lgkmcnt(0)
	v_pk_fma_f32 v[6:7], v[6:7], v[12:13], v[16:17]
	v_pk_add_f32 v[12:13], v[14:15], 1.0 op_sel_hi:[1,0]
	s_nop 0
	v_div_scale_f32 v14, s[48:49], v13, v13, 1.0
	v_rcp_f32_e32 v15, v14
	s_nop 0
	v_fma_f32 v16, -v14, v15, 1.0
	v_fmac_f32_e32 v15, v16, v15
	v_div_scale_f32 v16, vcc, 1.0, v13, 1.0
	v_mul_f32_e32 v17, v16, v15
	v_fma_f32 v20, -v14, v17, v16
	v_fmac_f32_e32 v17, v20, v15
	v_fma_f32 v14, -v14, v17, v16
	v_div_fmas_f32 v14, v14, v15, v17
	v_div_fixup_f32 v13, v14, v13, 1.0
	v_div_scale_f32 v14, s[48:49], v12, v12, 1.0
	v_rcp_f32_e32 v15, v14
	s_nop 0
	v_fma_f32 v16, -v14, v15, 1.0
	v_fmac_f32_e32 v15, v16, v15
	v_div_scale_f32 v16, vcc, 1.0, v12, 1.0
	v_mul_f32_e32 v17, v16, v15
	v_fma_f32 v20, -v14, v17, v16
	v_fmac_f32_e32 v17, v20, v15
	v_fma_f32 v14, -v14, v17, v16
	v_div_fmas_f32 v14, v14, v15, v17
	v_div_fixup_f32 v12, v14, v12, 1.0
	v_pk_fma_f32 v[8:9], v[8:9], v[12:13], v[18:19]
	global_store_dwordx4 v[10:11], v[6:9], off
	s_cbranch_scc1 .LBB0_737
; DEVI char* wsp(const Params& P, size_t off) { asm volatile("" : "+s"(off)); return P.ws + off; }
; #define ZERO_ACC(a) _Pragma("unroll") for (int m_ = 0; m_ < 4; ++m_) _Pragma("unroll") for (int n_ = 0; n_ < 4; ++n_) a[m_][n_] = f32x4{0.f, 0.f, 0.f, 0.f}
; template <int GATE>
; DEVI void gemm_core_t(f32x4 (&acc)[4][4], const bfu* __restrict__ A, int lda,
;                     const bfu* __restrict__ B, int ldb, int K, char* smem, int tid, const bfu* __restrict__ B2 = nullptr) {
;   const int wid = tid >> 6, lane = tid & 63;
;   const int wr = wid >> 1, wc = wid & 1, fr = lane & 15, fq = lane >> 4;
;   const int nt = K >> 6;
;   __syncthreads();
;   stage_tile(A, lda, 0, smem, tid);
;   if (GATE) stage_tile_gate(B, B2, 0, smem + 16384, tid); else stage_tile(B, ldb, 0, smem + 16384, tid);
; template <int BR, int IN, int OUT>
; DEVI void p6_branch(const Params& P, int pm, int pn, float* macc, char* smem, int tid) {
;     ...
;   const bfu* Z = (const bfu*)wsp(P, O_Z);
;   bfu* M = (bfu*)wsp(P, O_CB);
;   const bfu* A = (const bfu*)wsp(P, BR == 0 ? O_UA : BR == 1 ? O_UB : O_UC) + (long)pm * 128 * 1024;
;   const bfu* B = (const bfu*)wsp(P, BR == 0 ? O_WOA : BR == 1 ? O_WOB : O_WOC) + (long)pn * 128 * 1024;
;   f32x4 acc[4][4]; ZERO_ACC(acc);
;   gemm_core(acc, A, 1024, B, 1024, 1024, smem, tid);
	s_ashr_i32 s41, s40, 31
	s_ashr_i32 s27, s26, 31
	s_mov_b64 s[44:45], 0x8582000
	s_mov_b64 s[46:47], 0x17d02000
	s_mov_b64 s[48:49], 0x15c02000
	s_lshl_b64 s[50:51], s[40:41], 18
	s_lshl_b64 s[54:55], s[26:27], 18
	s_add_u32 s24, s30, s48
	s_addc_u32 s27, s31, s49
	s_add_u32 s56, s24, s50
	s_mov_b64 s[52:53], 0x1a00000
	s_addc_u32 s57, s27, s51
	s_add_u32 s24, s30, s52
	s_addc_u32 s27, s31, s53
	s_add_u32 s58, s24, s54
	v_lshl_add_u64 v[0:1], s[56:57], 0, v[116:117]
	v_readfirstlane_b32 s24, v101
	v_lshl_add_u64 v[0:1], v[0:1], 0, v[88:89]
	s_mov_b32 m0, s24
	s_barrier
	global_load_lds_dwordx4 v[0:1], off
	v_lshl_add_u64 v[0:1], s[56:57], 0, v[118:119]
	v_mov_b32_e32 v125, v89
	v_readfirstlane_b32 s24, v103
	v_lshl_add_u64 v[0:1], v[0:1], 0, v[124:125]
	s_mov_b32 m0, s24
	v_mov_b32_e32 v127, v89
	global_load_lds_dwordx4 v[0:1], off
	v_lshl_add_u64 v[0:1], s[56:57], 0, v[120:121]
	v_readfirstlane_b32 s24, v105
	v_lshl_add_u64 v[0:1], v[0:1], 0, v[126:127]
	s_mov_b32 m0, s24
	v_mov_b32_e32 v129, v89
	global_load_lds_dwordx4 v[0:1], off
	v_lshl_add_u64 v[0:1], s[56:57], 0, v[122:123]
	v_readfirstlane_b32 s24, v107
	s_addc_u32 s59, s27, s55
	v_lshl_add_u64 v[0:1], v[0:1], 0, v[128:129]
	s_mov_b32 m0, s24
	v_readfirstlane_b32 s24, v153
	global_load_lds_dwordx4 v[0:1], off
	v_lshl_add_u64 v[0:1], s[58:59], 0, v[116:117]
	v_lshl_add_u64 v[0:1], v[0:1], 0, v[88:89]
	s_mov_b32 m0, s24
	v_readfirstlane_b32 s24, v154
	global_load_lds_dwordx4 v[0:1], off
	v_lshl_add_u64 v[0:1], s[58:59], 0, v[118:119]
	v_lshl_add_u64 v[0:1], v[0:1], 0, v[124:125]
	s_mov_b32 m0, s24
	v_readfirstlane_b32 s24, v155
	global_load_lds_dwordx4 v[0:1], off
	v_lshl_add_u64 v[0:1], s[58:59], 0, v[120:121]
	v_lshl_add_u64 v[0:1], v[0:1], 0, v[126:127]
	s_mov_b32 m0, s24
	v_readfirstlane_b32 s24, v156
	global_load_lds_dwordx4 v[0:1], off
	v_lshl_add_u64 v[0:1], s[58:59], 0, v[122:123]
	v_lshl_add_u64 v[0:1], v[0:1], 0, v[128:129]
	s_mov_b32 m0, s24
	s_add_u32 s48, s48, s50
	global_load_lds_dwordx4 v[0:1], off
	s_addc_u32 s49, s49, s51
	v_lshl_add_u64 v[124:125], v[108:109], 0, s[48:49]
	v_lshl_add_u64 v[126:127], v[110:111], 0, s[48:49]
	v_lshl_add_u64 v[128:129], v[112:113], 0, s[48:49]
	v_lshl_add_u64 v[130:131], v[114:115], 0, s[48:49]
	s_add_u32 s48, s52, s54
	s_addc_u32 s49, s53, s55
	v_mov_b32_e32 v0, 0
	v_lshl_add_u64 v[132:133], v[108:109], 0, s[48:49]
	v_lshl_add_u64 v[134:135], v[110:111], 0, s[48:49]
	v_lshl_add_u64 v[136:137], v[112:113], 0, s[48:49]
	v_lshl_add_u64 v[138:139], v[114:115], 0, s[48:49]
	s_mov_b64 s[48:49], 0
	s_mov_b32 s24, 0x8000
	v_mov_b32_e32 v1, v0
	v_mov_b32_e32 v2, v0
	v_mov_b32_e32 v3, v0
	v_mov_b32_e32 v4, v0
	v_mov_b32_e32 v5, v0
	v_mov_b32_e32 v6, v0
	v_mov_b32_e32 v7, v0
	v_mov_b32_e32 v8, v0
	v_mov_b32_e32 v9, v0
	v_mov_b32_e32 v10, v0
	v_mov_b32_e32 v11, v0
	v_mov_b32_e32 v12, v0
	v_mov_b32_e32 v13, v0
	v_mov_b32_e32 v14, v0
	v_mov_b32_e32 v15, v0
	v_mov_b32_e32 v16, v0
	v_mov_b32_e32 v17, v0
	v_mov_b32_e32 v18, v0
	v_mov_b32_e32 v19, v0
	v_mov_b32_e32 v20, v0
	v_mov_b32_e32 v21, v0
	v_mov_b32_e32 v22, v0
	v_mov_b32_e32 v23, v0
	v_mov_b32_e32 v24, v0
	v_mov_b32_e32 v25, v0
	v_mov_b32_e32 v26, v0
	v_mov_b32_e32 v27, v0
	v_mov_b32_e32 v28, v0
	v_mov_b32_e32 v29, v0
	v_mov_b32_e32 v30, v0
	v_mov_b32_e32 v31, v0
	v_mov_b32_e32 v32, v0
	v_mov_b32_e32 v33, v0
	v_mov_b32_e32 v34, v0
	v_mov_b32_e32 v35, v0
	v_mov_b32_e32 v36, v0
	v_mov_b32_e32 v37, v0
	v_mov_b32_e32 v38, v0
	v_mov_b32_e32 v39, v0
	v_mov_b32_e32 v40, v0
	v_mov_b32_e32 v41, v0
	v_mov_b32_e32 v42, v0
	v_mov_b32_e32 v43, v0
	v_mov_b32_e32 v44, v0
	v_mov_b32_e32 v45, v0
	v_mov_b32_e32 v46, v0
	v_mov_b32_e32 v47, v0
	v_mov_b32_e32 v48, v0
	v_mov_b32_e32 v49, v0
	v_mov_b32_e32 v50, v0
	v_mov_b32_e32 v51, v0
	v_mov_b32_e32 v52, v0
	v_mov_b32_e32 v53, v0
	v_mov_b32_e32 v54, v0
	v_mov_b32_e32 v55, v0
	v_mov_b32_e32 v56, v0
	v_mov_b32_e32 v57, v0
	v_mov_b32_e32 v58, v0
	v_mov_b32_e32 v59, v0
	v_mov_b32_e32 v60, v0
	v_mov_b32_e32 v61, v0
	v_mov_b32_e32 v62, v0
	v_mov_b32_e32 v63, v0

; DEVI float sigmoidf_(float x) { return 1.f / (1.f + __expf(-x)); }
; template <int BR, int IN, int OUT>
; DEVI void p6_branch(const Params& P, int pm, int pn, float* macc, char* smem, int tid) {
;     ...
; #pragma unroll 8
;   for (int q = 0; q < 16; ++q) {
;     const int id = tid + 256 * q, row = id >> 5, c4 = id & 31;
;     const long grow = (long)pm * 128 + row;
;     const int gcol = pn * 128 + c4 * 4;
;     float4 a = *reinterpret_cast<const float4*>(T + row * 128 + c4 * 4);
;     float g[4];
;     load4bf(Z + grow * NCOL + (9 + BR) * 1024 + gcol, g);
;     float v[4] = {sigmoidf_(g[0]) * a.x, sigmoidf_(g[1]) * a.y, sigmoidf_(g[2]) * a.z, sigmoidf_(g[3]) * a.w};
;     if (IN == 1) {
;       float mo[4]; load4bf(M + grow * 1024 + gcol, mo);
;       v[0] += mo[0]; v[1] += mo[1]; v[2] += mo[2]; v[3] += mo[3];
;     }
;     if (IN == 2) {
;       float4 mo = *reinterpret_cast<const float4*>(macc + grow * 1024 + gcol);
;       v[0] += mo.x; v[1] += mo.y; v[2] += mo.z; v[3] += mo.w;
;     }
;     if (OUT == 1) *reinterpret_cast<float4*>(macc + grow * 1024 + gcol) = make_float4(v[0], v[1], v[2], v[3]);
;     else store4bf(M + grow * 1024 + gcol, v);
;   }
.LBB0_741:
	s_cmp_lg_u32 s24, 0
	s_cbranch_scc1 .Leh2LBB0741b
	v_add_u32_e32 v238, s24, v91
	v_ashrrev_i32_e32 v236, 5, v238
	v_ashrrev_i32_e32 v237, 31, v236
	v_lshl_add_u64 v[240:241], s[40:41], 0, v[236:237]
	v_mov_b64_e32 v[236:237], s[44:45]
	v_mad_u64_u32 v[242:243], s[26:27], v240, s22, v[236:237]
	v_mad_i32_i24 v243, v241, s22, v243
	v_lshl_add_u64 v[242:243], v[242:243], 0, v[4:5]
	v_add_co_u32_e32 v242, vcc, 0x5000, v242
	s_nop 1
	v_addc_co_u32_e32 v243, vcc, 0, v243, vcc
	global_load_dwordx2 v[50:51], v[242:243], off
	v_add_u32_e32 v238, s24, v91
	v_ashrrev_i32_e32 v236, 5, v238
	v_ashrrev_i32_e32 v237, 31, v236
	v_lshl_add_u64 v[240:241], s[40:41], 0, v[236:237]
	v_lshlrev_b64 v[242:243], 12, v[240:241]
	v_lshl_add_u64 v[244:245], v[0:1], 0, v[242:243]
	global_load_dwordx4 v[28:31], v[244:245], off
	v_add_u32_e32 v238, s24, v91
	v_mov_b64_e32 v[236:237], s[44:45]
	v_add_u32_e32 v239, 0x100, v238
	v_ashrrev_i32_e32 v240, 5, v239
	v_ashrrev_i32_e32 v241, 31, v240
	v_lshl_add_u64 v[242:243], s[40:41], 0, v[240:241]
	v_mad_u64_u32 v[240:241], s[26:27], v242, s22, v[236:237]
	v_mad_i32_i24 v241, v243, s22, v241
	v_lshl_add_u64 v[240:241], v[240:241], 0, v[4:5]
	v_add_co_u32_e32 v240, vcc, s21, v240
	s_nop 1
	v_addc_co_u32_e32 v241, vcc, 0, v241, vcc
	global_load_dwordx2 v[52:53], v[240:241], off
	v_add_u32_e32 v236, s24, v91
	v_add_u32_e32 v237, 0x100, v236
	v_ashrrev_i32_e32 v238, 5, v237
	v_ashrrev_i32_e32 v239, 31, v238
	v_lshl_add_u64 v[240:241], s[40:41], 0, v[238:239]
	v_lshlrev_b64 v[238:239], 12, v[240:241]
	v_lshl_add_u64 v[242:243], v[0:1], 0, v[238:239]
	global_load_dwordx4 v[32:35], v[242:243], off
	v_add_u32_e32 v238, s24, v91
	v_mov_b64_e32 v[236:237], s[44:45]
	v_add_u32_e32 v239, 0x200, v238
	v_ashrrev_i32_e32 v240, 5, v239
	v_ashrrev_i32_e32 v241, 31, v240
	v_lshl_add_u64 v[242:243], s[40:41], 0, v[240:241]
	v_mad_u64_u32 v[240:241], s[26:27], v242, s22, v[236:237]
	v_mad_i32_i24 v241, v243, s22, v241
	v_lshl_add_u64 v[240:241], v[240:241], 0, v[4:5]
	v_add_co_u32_e32 v240, vcc, s21, v240
	s_nop 1
	v_addc_co_u32_e32 v241, vcc, 0, v241, vcc
	global_load_dwordx2 v[202:203], v[240:241], off
	v_add_u32_e32 v236, s24, v91
	v_add_u32_e32 v237, 0x200, v236
	v_ashrrev_i32_e32 v238, 5, v237
	v_ashrrev_i32_e32 v239, 31, v238
	v_lshl_add_u64 v[240:241], s[40:41], 0, v[238:239]
	v_lshlrev_b64 v[238:239], 12, v[240:241]
	v_lshl_add_u64 v[242:243], v[0:1], 0, v[238:239]
	global_load_dwordx4 v[36:39], v[242:243], off
	v_add_u32_e32 v238, s24, v91
	v_mov_b64_e32 v[236:237], s[44:45]
	v_add_u32_e32 v239, 0x300, v238
	v_ashrrev_i32_e32 v240, 5, v239
	v_ashrrev_i32_e32 v241, 31, v240
	v_lshl_add_u64 v[242:243], s[40:41], 0, v[240:241]
	v_mad_u64_u32 v[240:241], s[26:27], v242, s22, v[236:237]
	v_mad_i32_i24 v241, v243, s22, v241
	v_lshl_add_u64 v[240:241], v[240:241], 0, v[4:5]
	v_add_co_u32_e32 v240, vcc, s21, v240
	s_nop 1
	v_addc_co_u32_e32 v241, vcc, 0, v241, vcc
	global_load_dwordx2 v[204:205], v[240:241], off
	v_add_u32_e32 v236, s24, v91
	v_add_u32_e32 v237, 0x300, v236
	v_ashrrev_i32_e32 v238, 5, v237
	v_ashrrev_i32_e32 v239, 31, v238
	v_lshl_add_u64 v[240:241], s[40:41], 0, v[238:239]
	v_lshlrev_b64 v[238:239], 12, v[240:241]
	v_lshl_add_u64 v[242:243], v[0:1], 0, v[238:239]
	global_load_dwordx4 v[40:43], v[242:243], off
	v_add_u32_e32 v238, s24, v91
	v_mov_b64_e32 v[236:237], s[44:45]
	v_add_u32_e32 v239, 0x400, v238
	v_ashrrev_i32_e32 v240, 5, v239
	v_ashrrev_i32_e32 v241, 31, v240
	v_lshl_add_u64 v[242:243], s[40:41], 0, v[240:241]
	v_mad_u64_u32 v[240:241], s[26:27], v242, s22, v[236:237]
	v_mad_i32_i24 v241, v243, s22, v241
	v_lshl_add_u64 v[240:241], v[240:241], 0, v[4:5]
	v_add_co_u32_e32 v240, vcc, s21, v240
	s_nop 1
	v_addc_co_u32_e32 v241, vcc, 0, v241, vcc
	global_load_dwordx2 v[142:143], v[240:241], off
	v_add_u32_e32 v236, s24, v91
	v_add_u32_e32 v237, 0x400, v236
	v_ashrrev_i32_e32 v238, 5, v237
	v_ashrrev_i32_e32 v239, 31, v238
	v_lshl_add_u64 v[240:241], s[40:41], 0, v[238:239]
	v_lshlrev_b64 v[238:239], 12, v[240:241]
	v_lshl_add_u64 v[242:243], v[0:1], 0, v[238:239]
	global_load_dwordx4 v[44:47], v[242:243], off
	v_add_u32_e32 v238, s24, v91
	v_mov_b64_e32 v[236:237], s[44:45]
	v_add_u32_e32 v239, 0x500, v238
	v_ashrrev_i32_e32 v240, 5, v239
	v_ashrrev_i32_e32 v241, 31, v240
	v_lshl_add_u64 v[242:243], s[40:41], 0, v[240:241]
	v_mad_u64_u32 v[240:241], s[26:27], v242, s22, v[236:237]
	v_mad_i32_i24 v241, v243, s22, v241
	v_lshl_add_u64 v[240:241], v[240:241], 0, v[4:5]
	v_add_co_u32_e32 v240, vcc, s21, v240
	s_nop 1
	v_addc_co_u32_e32 v241, vcc, 0, v241, vcc
	global_load_dwordx2 v[144:145], v[240:241], off
	v_add_u32_e32 v236, s24, v91
	v_add_u32_e32 v237, 0x500, v236
	v_ashrrev_i32_e32 v238, 5, v237
	v_ashrrev_i32_e32 v239, 31, v238
	v_lshl_add_u64 v[240:241], s[40:41], 0, v[238:239]
	v_lshlrev_b64 v[238:239], 12, v[240:241]
	v_lshl_add_u64 v[242:243], v[0:1], 0, v[238:239]
	global_load_dwordx4 v[60:63], v[242:243], off
	v_add_u32_e32 v238, s24, v91
	v_mov_b64_e32 v[236:237], s[44:45]
	v_add_u32_e32 v239, 0x600, v238
	v_ashrrev_i32_e32 v240, 5, v239
	v_ashrrev_i32_e32 v241, 31, v240
	v_lshl_add_u64 v[242:243], s[40:41], 0, v[240:241]
	v_mad_u64_u32 v[240:241], s[26:27], v242, s22, v[236:237]
	v_mad_i32_i24 v241, v243, s22, v241
	v_lshl_add_u64 v[240:241], v[240:241], 0, v[4:5]
	v_add_co_u32_e32 v240, vcc, s21, v240
	s_nop 1
	v_addc_co_u32_e32 v241, vcc, 0, v241, vcc
	global_load_dwordx2 v[134:135], v[240:241], off
	v_add_u32_e32 v236, s24, v91
	v_add_u32_e32 v237, 0x600, v236
	v_ashrrev_i32_e32 v238, 5, v237
	v_ashrrev_i32_e32 v239, 31, v238
	v_lshl_add_u64 v[240:241], s[40:41], 0, v[238:239]
; DEVI float sigmoidf_(float x) { return 1.f / (1.f + __expf(-x)); }
; template <int BR, int IN, int OUT>
; DEVI void p6_branch(const Params& P, int pm, int pn, float* macc, char* smem, int tid) {
;     ...
; #pragma unroll 8
;   for (int q = 0; q < 16; ++q) {
;     const int id = tid + 256 * q, row = id >> 5, c4 = id & 31;
;     const long grow = (long)pm * 128 + row;
;     const int gcol = pn * 128 + c4 * 4;
;     float4 a = *reinterpret_cast<const float4*>(T + row * 128 + c4 * 4);
;     float g[4];
;     load4bf(Z + grow * NCOL + (9 + BR) * 1024 + gcol, g);
;     float v[4] = {sigmoidf_(g[0]) * a.x, sigmoidf_(g[1]) * a.y, sigmoidf_(g[2]) * a.z, sigmoidf_(g[3]) * a.w};
;     if (IN == 1) {
;       float mo[4]; load4bf(M + grow * 1024 + gcol, mo);
;       v[0] += mo[0]; v[1] += mo[1]; v[2] += mo[2]; v[3] += mo[3];
;     }
;     if (IN == 2) {
;       float4 mo = *reinterpret_cast<const float4*>(macc + grow * 1024 + gcol);
;       v[0] += mo.x; v[1] += mo.y; v[2] += mo.z; v[3] += mo.w;
;     }
;     if (OUT == 1) *reinterpret_cast<float4*>(macc + grow * 1024 + gcol) = make_float4(v[0], v[1], v[2], v[3]);
;     else store4bf(M + grow * 1024 + gcol, v);
;   }
	v_lshlrev_b64 v[238:239], 12, v[240:241]
	v_lshl_add_u64 v[242:243], v[0:1], 0, v[238:239]
	global_load_dwordx4 v[124:127], v[242:243], off
	v_add_u32_e32 v238, s24, v91
	v_mov_b64_e32 v[236:237], s[44:45]
	v_add_u32_e32 v238, 0x700, v238
	v_ashrrev_i32_e32 v238, 5, v238
	v_ashrrev_i32_e32 v239, 31, v238
	v_lshl_add_u64 v[240:241], s[40:41], 0, v[238:239]
	v_mad_u64_u32 v[236:237], s[26:27], v240, s22, v[236:237]
	v_mad_i32_i24 v237, v241, s22, v237
	v_lshl_add_u64 v[236:237], v[236:237], 0, v[4:5]
	v_add_co_u32_e32 v236, vcc, s21, v236
	s_nop 1
	v_addc_co_u32_e32 v237, vcc, 0, v237, vcc
	global_load_dwordx2 v[138:139], v[236:237], off
	v_add_u32_e32 v238, s24, v91
	v_add_u32_e32 v238, 0x700, v238
	v_ashrrev_i32_e32 v238, 5, v238
	v_ashrrev_i32_e32 v239, 31, v238
	v_lshl_add_u64 v[240:241], s[40:41], 0, v[238:239]
	v_lshlrev_b64 v[236:237], 12, v[240:241]
	v_lshl_add_u64 v[242:243], v[0:1], 0, v[236:237]
	global_load_dwordx4 v[128:131], v[242:243], off
	v_add_u32_e32 v238, s24, v91
	v_add_u32_e32 v238, 0x800, v238
	v_ashrrev_i32_e32 v236, 5, v238
	v_ashrrev_i32_e32 v237, 31, v236
	v_lshl_add_u64 v[240:241], s[40:41], 0, v[236:237]
	v_mov_b64_e32 v[236:237], s[44:45]
	v_mad_u64_u32 v[242:243], s[26:27], v240, s22, v[236:237]
	v_mad_i32_i24 v243, v241, s22, v243
	v_lshl_add_u64 v[242:243], v[242:243], 0, v[4:5]
	v_add_co_u32_e32 v242, vcc, 0x5000, v242
	s_nop 1
	v_addc_co_u32_e32 v243, vcc, 0, v243, vcc
	global_load_dwordx2 v[154:155], v[242:243], off
	v_add_u32_e32 v238, s24, v91
	v_add_u32_e32 v238, 0x800, v238
	v_ashrrev_i32_e32 v236, 5, v238
	v_ashrrev_i32_e32 v237, 31, v236
	v_lshl_add_u64 v[240:241], s[40:41], 0, v[236:237]
	v_lshlrev_b64 v[242:243], 12, v[240:241]
	v_lshl_add_u64 v[244:245], v[0:1], 0, v[242:243]
	global_load_dwordx4 v[156:159], v[244:245], off
	v_add_u32_e32 v238, s24, v91
	v_add_u32_e32 v238, 0x800, v238
	v_mov_b64_e32 v[236:237], s[44:45]
	v_add_u32_e32 v239, 0x100, v238
	v_ashrrev_i32_e32 v240, 5, v239
	v_ashrrev_i32_e32 v241, 31, v240
	v_lshl_add_u64 v[242:243], s[40:41], 0, v[240:241]
	v_mad_u64_u32 v[240:241], s[26:27], v242, s22, v[236:237]
	v_mad_i32_i24 v241, v243, s22, v241
	v_lshl_add_u64 v[240:241], v[240:241], 0, v[4:5]
	v_add_co_u32_e32 v240, vcc, s21, v240
	s_nop 1
	v_addc_co_u32_e32 v241, vcc, 0, v241, vcc
	global_load_dwordx2 v[160:161], v[240:241], off
	v_add_u32_e32 v236, s24, v91
	v_add_u32_e32 v236, 0x800, v236
	v_add_u32_e32 v237, 0x100, v236
	v_ashrrev_i32_e32 v238, 5, v237
	v_ashrrev_i32_e32 v239, 31, v238
	v_lshl_add_u64 v[240:241], s[40:41], 0, v[238:239]
	v_lshlrev_b64 v[238:239], 12, v[240:241]
	v_lshl_add_u64 v[242:243], v[0:1], 0, v[238:239]
	global_load_dwordx4 v[164:167], v[242:243], off
	v_add_u32_e32 v238, s24, v91
	v_add_u32_e32 v238, 0x800, v238
	v_mov_b64_e32 v[236:237], s[44:45]
	v_add_u32_e32 v239, 0x200, v238
	v_ashrrev_i32_e32 v240, 5, v239
	v_ashrrev_i32_e32 v241, 31, v240
	v_lshl_add_u64 v[242:243], s[40:41], 0, v[240:241]
	v_mad_u64_u32 v[240:241], s[26:27], v242, s22, v[236:237]
	v_mad_i32_i24 v241, v243, s22, v241
	v_lshl_add_u64 v[240:241], v[240:241], 0, v[4:5]
	v_add_co_u32_e32 v240, vcc, s21, v240
	s_nop 1
	v_addc_co_u32_e32 v241, vcc, 0, v241, vcc
	global_load_dwordx2 v[162:163], v[240:241], off
	v_add_u32_e32 v236, s24, v91
	v_add_u32_e32 v236, 0x800, v236
	v_add_u32_e32 v237, 0x200, v236
	v_ashrrev_i32_e32 v238, 5, v237
	v_ashrrev_i32_e32 v239, 31, v238
	v_lshl_add_u64 v[240:241], s[40:41], 0, v[238:239]
	v_lshlrev_b64 v[238:239], 12, v[240:241]
	v_lshl_add_u64 v[242:243], v[0:1], 0, v[238:239]
	global_load_dwordx4 v[168:171], v[242:243], off
	v_add_u32_e32 v238, s24, v91
	v_add_u32_e32 v238, 0x800, v238
	v_mov_b64_e32 v[236:237], s[44:45]
	v_add_u32_e32 v239, 0x300, v238
	v_ashrrev_i32_e32 v240, 5, v239
	v_ashrrev_i32_e32 v241, 31, v240
	v_lshl_add_u64 v[242:243], s[40:41], 0, v[240:241]
	v_mad_u64_u32 v[240:241], s[26:27], v242, s22, v[236:237]
	v_mad_i32_i24 v241, v243, s22, v241
	v_lshl_add_u64 v[240:241], v[240:241], 0, v[4:5]
	v_add_co_u32_e32 v240, vcc, s21, v240
	s_nop 1
	v_addc_co_u32_e32 v241, vcc, 0, v241, vcc
	global_load_dwordx2 v[172:173], v[240:241], off
	v_add_u32_e32 v236, s24, v91
	v_add_u32_e32 v236, 0x800, v236
	v_add_u32_e32 v237, 0x300, v236
	v_ashrrev_i32_e32 v238, 5, v237
	v_ashrrev_i32_e32 v239, 31, v238
	v_lshl_add_u64 v[240:241], s[40:41], 0, v[238:239]
	v_lshlrev_b64 v[238:239], 12, v[240:241]
	v_lshl_add_u64 v[242:243], v[0:1], 0, v[238:239]
	global_load_dwordx4 v[176:179], v[242:243], off
	v_add_u32_e32 v238, s24, v91
	v_add_u32_e32 v238, 0x800, v238
	v_mov_b64_e32 v[236:237], s[44:45]
	v_add_u32_e32 v239, 0x400, v238
	v_ashrrev_i32_e32 v240, 5, v239
	v_ashrrev_i32_e32 v241, 31, v240
	v_lshl_add_u64 v[242:243], s[40:41], 0, v[240:241]
	v_mad_u64_u32 v[240:241], s[26:27], v242, s22, v[236:237]
	v_mad_i32_i24 v241, v243, s22, v241
	v_lshl_add_u64 v[240:241], v[240:241], 0, v[4:5]
	v_add_co_u32_e32 v240, vcc, s21, v240
	s_nop 1
	v_addc_co_u32_e32 v241, vcc, 0, v241, vcc
	global_load_dwordx2 v[174:175], v[240:241], off
	v_add_u32_e32 v236, s24, v91
	v_add_u32_e32 v236, 0x800, v236
	v_add_u32_e32 v237, 0x400, v236
	v_ashrrev_i32_e32 v238, 5, v237
	v_ashrrev_i32_e32 v239, 31, v238
	v_lshl_add_u64 v[240:241], s[40:41], 0, v[238:239]
	v_lshlrev_b64 v[238:239], 12, v[240:241]
	v_lshl_add_u64 v[242:243], v[0:1], 0, v[238:239]
	global_load_dwordx4 v[180:183], v[242:243], off
	v_add_u32_e32 v238, s24, v91
	v_add_u32_e32 v238, 0x800, v238
	v_mov_b64_e32 v[236:237], s[44:45]
	v_add_u32_e32 v239, 0x500, v238
	v_ashrrev_i32_e32 v240, 5, v239
	v_ashrrev_i32_e32 v241, 31, v240
	v_lshl_add_u64 v[242:243], s[40:41], 0, v[240:241]
; DEVI float sigmoidf_(float x) { return 1.f / (1.f + __expf(-x)); }
; template <int BR, int IN, int OUT>
; DEVI void p6_branch(const Params& P, int pm, int pn, float* macc, char* smem, int tid) {
;     ...
; #pragma unroll 8
;   for (int q = 0; q < 16; ++q) {
;     const int id = tid + 256 * q, row = id >> 5, c4 = id & 31;
;     const long grow = (long)pm * 128 + row;
;     const int gcol = pn * 128 + c4 * 4;
;     float4 a = *reinterpret_cast<const float4*>(T + row * 128 + c4 * 4);
;     float g[4];
;     load4bf(Z + grow * NCOL + (9 + BR) * 1024 + gcol, g);
;     float v[4] = {sigmoidf_(g[0]) * a.x, sigmoidf_(g[1]) * a.y, sigmoidf_(g[2]) * a.z, sigmoidf_(g[3]) * a.w};
;     if (IN == 1) {
;       float mo[4]; load4bf(M + grow * 1024 + gcol, mo);
;       v[0] += mo[0]; v[1] += mo[1]; v[2] += mo[2]; v[3] += mo[3];
;     }
;     if (IN == 2) {
;       float4 mo = *reinterpret_cast<const float4*>(macc + grow * 1024 + gcol);
;       v[0] += mo.x; v[1] += mo.y; v[2] += mo.z; v[3] += mo.w;
;     }
;     if (OUT == 1) *reinterpret_cast<float4*>(macc + grow * 1024 + gcol) = make_float4(v[0], v[1], v[2], v[3]);
;     else store4bf(M + grow * 1024 + gcol, v);
;   }
	v_mad_u64_u32 v[240:241], s[26:27], v242, s22, v[236:237]
	v_mad_i32_i24 v241, v243, s22, v241
	v_lshl_add_u64 v[240:241], v[240:241], 0, v[4:5]
	v_add_co_u32_e32 v240, vcc, s21, v240
	s_nop 1
	v_addc_co_u32_e32 v241, vcc, 0, v241, vcc
	global_load_dwordx2 v[196:197], v[240:241], off
	v_add_u32_e32 v236, s24, v91
	v_add_u32_e32 v236, 0x800, v236
	v_add_u32_e32 v237, 0x500, v236
	v_ashrrev_i32_e32 v238, 5, v237
	v_ashrrev_i32_e32 v239, 31, v238
	v_lshl_add_u64 v[240:241], s[40:41], 0, v[238:239]
	v_lshlrev_b64 v[238:239], 12, v[240:241]
	v_lshl_add_u64 v[242:243], v[0:1], 0, v[238:239]
	global_load_dwordx4 v[208:211], v[242:243], off
	v_add_u32_e32 v238, s24, v91
	v_add_u32_e32 v238, 0x800, v238
	v_mov_b64_e32 v[236:237], s[44:45]
	v_add_u32_e32 v239, 0x600, v238
	v_ashrrev_i32_e32 v240, 5, v239
	v_ashrrev_i32_e32 v241, 31, v240
	v_lshl_add_u64 v[242:243], s[40:41], 0, v[240:241]
	v_mad_u64_u32 v[240:241], s[26:27], v242, s22, v[236:237]
	v_mad_i32_i24 v241, v243, s22, v241
	v_lshl_add_u64 v[240:241], v[240:241], 0, v[4:5]
	v_add_co_u32_e32 v240, vcc, s21, v240
	s_nop 1
	v_addc_co_u32_e32 v241, vcc, 0, v241, vcc
	global_load_dwordx2 v[198:199], v[240:241], off
	v_add_u32_e32 v236, s24, v91
	v_add_u32_e32 v236, 0x800, v236
	v_add_u32_e32 v237, 0x600, v236
	v_ashrrev_i32_e32 v238, 5, v237
	v_ashrrev_i32_e32 v239, 31, v238
	v_lshl_add_u64 v[240:241], s[40:41], 0, v[238:239]
	v_lshlrev_b64 v[238:239], 12, v[240:241]
	v_lshl_add_u64 v[242:243], v[0:1], 0, v[238:239]
	global_load_dwordx4 v[212:215], v[242:243], off
	v_add_u32_e32 v238, s24, v91
	v_add_u32_e32 v238, 0x800, v238
	v_mov_b64_e32 v[236:237], s[44:45]
	v_add_u32_e32 v238, 0x700, v238
	v_ashrrev_i32_e32 v238, 5, v238
	v_ashrrev_i32_e32 v239, 31, v238
	v_lshl_add_u64 v[240:241], s[40:41], 0, v[238:239]
	v_mad_u64_u32 v[236:237], s[26:27], v240, s22, v[236:237]
	v_mad_i32_i24 v237, v241, s22, v237
	v_lshl_add_u64 v[236:237], v[236:237], 0, v[4:5]
	v_add_co_u32_e32 v236, vcc, s21, v236
	s_nop 1
	v_addc_co_u32_e32 v237, vcc, 0, v237, vcc
	global_load_dwordx2 v[216:217], v[236:237], off
	v_add_u32_e32 v238, s24, v91
	v_add_u32_e32 v238, 0x800, v238
	v_add_u32_e32 v238, 0x700, v238
	v_ashrrev_i32_e32 v238, 5, v238
	v_ashrrev_i32_e32 v239, 31, v238
	v_lshl_add_u64 v[240:241], s[40:41], 0, v[238:239]
	v_lshlrev_b64 v[236:237], 12, v[240:241]
	v_lshl_add_u64 v[242:243], v[0:1], 0, v[236:237]
	global_load_dwordx4 v[220:223], v[242:243], off
	s_waitcnt vmcnt(0)
	s_branch .Leh2LBB0741c
.Leh2LBB0741b:
	v_mov_b32_e32 v50, v154
	v_mov_b32_e32 v51, v155
	v_mov_b32_e32 v28, v156
	v_mov_b32_e32 v29, v157
	v_mov_b32_e32 v30, v158
	v_mov_b32_e32 v31, v159
	v_mov_b32_e32 v52, v160
	v_mov_b32_e32 v53, v161
	v_mov_b32_e32 v32, v164
	v_mov_b32_e32 v33, v165
	v_mov_b32_e32 v34, v166
	v_mov_b32_e32 v35, v167
	v_mov_b32_e32 v202, v162
	v_mov_b32_e32 v203, v163
	v_mov_b32_e32 v36, v168
	v_mov_b32_e32 v37, v169
	v_mov_b32_e32 v38, v170
	v_mov_b32_e32 v39, v171
	v_mov_b32_e32 v204, v172
	v_mov_b32_e32 v205, v173
	v_mov_b32_e32 v40, v176
	v_mov_b32_e32 v41, v177
	v_mov_b32_e32 v42, v178
	v_mov_b32_e32 v43, v179
	v_mov_b32_e32 v142, v174
	v_mov_b32_e32 v143, v175
	v_mov_b32_e32 v44, v180
	v_mov_b32_e32 v45, v181
	v_mov_b32_e32 v46, v182
	v_mov_b32_e32 v47, v183
	v_mov_b32_e32 v144, v196
	v_mov_b32_e32 v145, v197
	v_mov_b32_e32 v60, v208
	v_mov_b32_e32 v61, v209
	v_mov_b32_e32 v62, v210
	v_mov_b32_e32 v63, v211
	v_mov_b32_e32 v134, v198
	v_mov_b32_e32 v135, v199
	v_mov_b32_e32 v124, v212
	v_mov_b32_e32 v125, v213
	v_mov_b32_e32 v126, v214
	v_mov_b32_e32 v127, v215
	v_mov_b32_e32 v138, v216
	v_mov_b32_e32 v139, v217
	v_mov_b32_e32 v128, v220
	v_mov_b32_e32 v129, v221
	v_mov_b32_e32 v130, v222
	v_mov_b32_e32 v131, v223
.Leh2LBB0741c:
	v_add_u32_e32 v8, s24, v91
	v_ashrrev_i32_e32 v6, 5, v8
	v_ashrrev_i32_e32 v7, 31, v6
	v_lshl_add_u64 v[10:11], s[40:41], 0, v[6:7]
	v_lshl_or_b32 v9, v6, 9, v152
	v_mov_b64_e32 v[6:7], s[44:45]
	v_mad_u64_u32 v[12:13], s[26:27], v10, s22, v[6:7]
	v_mad_i32_i24 v13, v11, s22, v13
	v_lshl_add_u64 v[12:13], v[12:13], 0, v[4:5]
	v_add_co_u32_e32 v12, vcc, 0x5000, v12
	s_addk_i32 s24, 0x800
	s_nop 0
	v_addc_co_u32_e32 v13, vcc, 0, v13, vcc
	v_mov_b32_e32 v12, v50
	v_mov_b32_e32 v13, v51
	s_cmpk_lg_i32 s24, 0x1000
	v_lshlrev_b32_e32 v14, 16, v12
	v_and_b32_e32 v12, 0xffff0000, v12
	v_lshlrev_b32_e32 v15, 16, v13
	v_mul_f32_e32 v12, 0xbfb8aa3b, v12
	v_mul_f32_e32 v14, 0xbfb8aa3b, v14
	v_exp_f32_e32 v16, v12
	v_mul_f32_e32 v12, 0xbfb8aa3b, v15
	v_exp_f32_e32 v14, v14
	v_exp_f32_e32 v15, v12
	v_and_b32_e32 v13, 0xffff0000, v13
	v_mul_f32_e32 v12, 0xbfb8aa3b, v13
	v_exp_f32_e32 v17, v12
	v_lshlrev_b64 v[12:13], 12, v[10:11]
	v_lshlrev_b64 v[10:11], 11, v[10:11]
	v_pk_add_f32 v[14:15], v[14:15], 1.0 op_sel_hi:[1,0]
	v_lshl_add_u64 v[18:19], v[0:1], 0, v[12:13]
	v_lshl_add_u64 v[20:21], v[2:3], 0, v[10:11]
	ds_read_b128 v[10:13], v9
	v_div_scale_f32 v9, s[26:27], v15, v15, 1.0
	v_rcp_f32_e32 v22, v9
	s_nop 0
	v_fma_f32 v23, -v9, v22, 1.0
	v_fmac_f32_e32 v22, v23, v22
	v_div_scale_f32 v23, vcc, 1.0, v15, 1.0
	v_mul_f32_e32 v24, v23, v22
	v_fma_f32 v25, -v9, v24, v23
	v_fmac_f32_e32 v24, v25, v22
	v_fma_f32 v9, -v9, v24, v23
	v_div_fmas_f32 v9, v9, v22, v24
	v_div_fixup_f32 v23, v9, v15, 1.0
	v_div_scale_f32 v9, s[26:27], v14, v14, 1.0
	v_rcp_f32_e32 v15, v9
	s_nop 0
	v_fma_f32 v22, -v9, v15, 1.0
	v_fmac_f32_e32 v15, v22, v15
	v_div_scale_f32 v22, vcc, 1.0, v14, 1.0
	v_mul_f32_e32 v24, v22, v15
	v_fma_f32 v25, -v9, v24, v22
	v_fmac_f32_e32 v24, v25, v15
	v_fma_f32 v9, -v9, v24, v22
	v_div_fmas_f32 v9, v9, v15, v24
	v_div_fixup_f32 v22, v9, v14, 1.0
	v_pk_add_f32 v[14:15], v[16:17], 1.0 op_sel_hi:[1,0]
	s_waitcnt lgkmcnt(0)
; DEVI float sigmoidf_(float x) { return 1.f / (1.f + __expf(-x)); }
; template <int BR, int IN, int OUT>
; DEVI void p6_branch(const Params& P, int pm, int pn, float* macc, char* smem, int tid) {
;     ...
; #pragma unroll 8
;   for (int q = 0; q < 16; ++q) {
;     const int id = tid + 256 * q, row = id >> 5, c4 = id & 31;
;     const long grow = (long)pm * 128 + row;
;     const int gcol = pn * 128 + c4 * 4;
;     float4 a = *reinterpret_cast<const float4*>(T + row * 128 + c4 * 4);
;     float g[4];
;     load4bf(Z + grow * NCOL + (9 + BR) * 1024 + gcol, g);
;     float v[4] = {sigmoidf_(g[0]) * a.x, sigmoidf_(g[1]) * a.y, sigmoidf_(g[2]) * a.z, sigmoidf_(g[3]) * a.w};
;     if (IN == 1) {
;       float mo[4]; load4bf(M + grow * 1024 + gcol, mo);
;       v[0] += mo[0]; v[1] += mo[1]; v[2] += mo[2]; v[3] += mo[3];
;     }
;     if (IN == 2) {
;       float4 mo = *reinterpret_cast<const float4*>(macc + grow * 1024 + gcol);
;       v[0] += mo.x; v[1] += mo.y; v[2] += mo.z; v[3] += mo.w;
;     }
;     if (OUT == 1) *reinterpret_cast<float4*>(macc + grow * 1024 + gcol) = make_float4(v[0], v[1], v[2], v[3]);
;     else store4bf(M + grow * 1024 + gcol, v);
;   }
	v_mov_b32_e32 v24, v10
	v_div_scale_f32 v9, s[26:27], v15, v15, 1.0
	v_rcp_f32_e32 v10, v9
	v_mov_b32_e32 v25, v12
	v_fma_f32 v12, -v9, v10, 1.0
	v_fmac_f32_e32 v10, v12, v10
	v_div_scale_f32 v12, vcc, 1.0, v15, 1.0
	v_mul_f32_e32 v16, v12, v10
	v_fma_f32 v17, -v9, v16, v12
	v_fmac_f32_e32 v16, v17, v10
	v_fma_f32 v9, -v9, v16, v12
	v_div_fmas_f32 v9, v9, v10, v16
	v_div_fixup_f32 v27, v9, v15, 1.0
	v_div_scale_f32 v9, s[26:27], v14, v14, 1.0
	v_rcp_f32_e32 v10, v9
	s_nop 0
	v_fma_f32 v12, -v9, v10, 1.0
	v_fmac_f32_e32 v10, v12, v10
	v_div_scale_f32 v12, vcc, 1.0, v14, 1.0
	v_mul_f32_e32 v15, v12, v10
	v_fma_f32 v16, -v9, v15, v12
	v_fmac_f32_e32 v15, v16, v10
	v_fma_f32 v9, -v9, v15, v12
	v_div_fmas_f32 v9, v9, v10, v15
	v_div_fixup_f32 v26, v9, v14, 1.0
	v_mov_b32_e32 v14, v28
	v_mov_b32_e32 v15, v29
	v_mov_b32_e32 v16, v30
	v_mov_b32_e32 v17, v31
	v_mov_b32_e32 v12, v11
	v_mov_b32_e32 v10, v14
	v_mov_b32_e32 v11, v16
	v_pk_fma_f32 v[10:11], v[24:25], v[22:23], v[10:11]
	v_mov_b32_e32 v16, v15
	v_pk_fma_f32 v[12:13], v[12:13], v[26:27], v[16:17]
	v_and_b32_sdwa v9, v11, v95 dst_sel:DWORD dst_unused:UNUSED_PAD src0_sel:WORD_1 src1_sel:DWORD
	v_and_b32_sdwa v14, v10, v95 dst_sel:DWORD dst_unused:UNUSED_PAD src0_sel:WORD_1 src1_sel:DWORD
	v_add3_u32 v10, v10, v14, s39
	v_add3_u32 v9, v11, v9, s39
	v_and_b32_sdwa v11, v13, v95 dst_sel:DWORD dst_unused:UNUSED_PAD src0_sel:WORD_1 src1_sel:DWORD
	v_and_b32_sdwa v14, v12, v95 dst_sel:DWORD dst_unused:UNUSED_PAD src0_sel:WORD_1 src1_sel:DWORD
	v_add3_u32 v11, v13, v11, s39
	v_add3_u32 v12, v12, v14, s39
	v_and_b32_e32 v11, 0xffff0000, v11
	v_and_b32_e32 v12, 0xffff0000, v12
	v_or_b32_sdwa v11, v11, v9 dst_sel:DWORD dst_unused:UNUSED_PAD src0_sel:DWORD src1_sel:WORD_1
	v_or_b32_sdwa v10, v12, v10 dst_sel:DWORD dst_unused:UNUSED_PAD src0_sel:DWORD src1_sel:WORD_1
	v_add_u32_e32 v9, 0x100, v8
	global_store_dwordx2 v[20:21], v[10:11], off
	v_ashrrev_i32_e32 v10, 5, v9
	v_ashrrev_i32_e32 v11, 31, v10
	v_lshl_add_u64 v[12:13], s[40:41], 0, v[10:11]
	v_lshl_or_b32 v9, v10, 9, v152
	v_mad_u64_u32 v[10:11], s[26:27], v12, s22, v[6:7]
	v_mad_i32_i24 v11, v13, s22, v11
	v_lshl_add_u64 v[10:11], v[10:11], 0, v[4:5]
	v_add_co_u32_e32 v10, vcc, s21, v10
	s_nop 1
	v_addc_co_u32_e32 v11, vcc, 0, v11, vcc
	v_mov_b32_e32 v10, v52
	v_mov_b32_e32 v11, v53
	v_lshlrev_b32_e32 v14, 16, v10
	v_and_b32_e32 v10, 0xffff0000, v10
	v_lshlrev_b32_e32 v15, 16, v11
	v_mul_f32_e32 v10, 0xbfb8aa3b, v10
	v_mul_f32_e32 v14, 0xbfb8aa3b, v14
	v_exp_f32_e32 v16, v10
	v_mul_f32_e32 v10, 0xbfb8aa3b, v15
	v_exp_f32_e32 v14, v14
	v_exp_f32_e32 v15, v10
	v_and_b32_e32 v11, 0xffff0000, v11
	v_mul_f32_e32 v10, 0xbfb8aa3b, v11
	v_exp_f32_e32 v17, v10
	v_lshlrev_b64 v[10:11], 12, v[12:13]
	v_lshl_add_u64 v[18:19], v[0:1], 0, v[10:11]
	v_lshlrev_b64 v[10:11], 11, v[12:13]
	v_pk_add_f32 v[14:15], v[14:15], 1.0 op_sel_hi:[1,0]
	v_lshl_add_u64 v[20:21], v[2:3], 0, v[10:11]
	ds_read_b128 v[10:13], v9
	v_div_scale_f32 v9, s[26:27], v15, v15, 1.0
	v_rcp_f32_e32 v22, v9
	s_nop 0
	v_fma_f32 v23, -v9, v22, 1.0
	v_fmac_f32_e32 v22, v23, v22
	v_div_scale_f32 v23, vcc, 1.0, v15, 1.0
	v_mul_f32_e32 v24, v23, v22
	v_fma_f32 v25, -v9, v24, v23
	v_fmac_f32_e32 v24, v25, v22
	v_fma_f32 v9, -v9, v24, v23
	v_div_fmas_f32 v9, v9, v22, v24
	v_div_fixup_f32 v23, v9, v15, 1.0
	v_div_scale_f32 v9, s[26:27], v14, v14, 1.0
	v_rcp_f32_e32 v15, v9
	s_nop 0
	v_fma_f32 v22, -v9, v15, 1.0
	v_fmac_f32_e32 v15, v22, v15
	v_div_scale_f32 v22, vcc, 1.0, v14, 1.0
	v_mul_f32_e32 v24, v22, v15
	v_fma_f32 v25, -v9, v24, v22
	v_fmac_f32_e32 v24, v25, v15
	v_fma_f32 v9, -v9, v24, v22
	v_div_fmas_f32 v9, v9, v15, v24
	v_div_fixup_f32 v22, v9, v14, 1.0
	v_pk_add_f32 v[14:15], v[16:17], 1.0 op_sel_hi:[1,0]
	s_waitcnt lgkmcnt(0)
	v_mov_b32_e32 v24, v10
	v_div_scale_f32 v9, s[26:27], v15, v15, 1.0
	v_rcp_f32_e32 v10, v9
	v_mov_b32_e32 v25, v12
	v_fma_f32 v12, -v9, v10, 1.0
	v_fmac_f32_e32 v10, v12, v10
	v_div_scale_f32 v12, vcc, 1.0, v15, 1.0
	v_mul_f32_e32 v16, v12, v10
	v_fma_f32 v17, -v9, v16, v12
	v_fmac_f32_e32 v16, v17, v10
	v_fma_f32 v9, -v9, v16, v12
	v_div_fmas_f32 v9, v9, v10, v16
	v_div_fixup_f32 v27, v9, v15, 1.0
	v_div_scale_f32 v9, s[26:27], v14, v14, 1.0
	v_rcp_f32_e32 v10, v9
	s_nop 0
	v_fma_f32 v12, -v9, v10, 1.0
	v_fmac_f32_e32 v10, v12, v10
	v_div_scale_f32 v12, vcc, 1.0, v14, 1.0
	v_mul_f32_e32 v15, v12, v10
	v_fma_f32 v16, -v9, v15, v12
	v_fmac_f32_e32 v15, v16, v10
	v_fma_f32 v9, -v9, v15, v12
	v_div_fmas_f32 v9, v9, v10, v15
	v_div_fixup_f32 v26, v9, v14, 1.0
	v_mov_b32_e32 v14, v32
	v_mov_b32_e32 v15, v33
	v_mov_b32_e32 v16, v34
	v_mov_b32_e32 v17, v35
	v_mov_b32_e32 v12, v11
	v_mov_b32_e32 v10, v14
	v_mov_b32_e32 v11, v16
	v_pk_fma_f32 v[10:11], v[24:25], v[22:23], v[10:11]
	v_mov_b32_e32 v16, v15
	v_pk_fma_f32 v[12:13], v[12:13], v[26:27], v[16:17]
	v_and_b32_sdwa v9, v11, v95 dst_sel:DWORD dst_unused:UNUSED_PAD src0_sel:WORD_1 src1_sel:DWORD
	v_and_b32_sdwa v14, v10, v95 dst_sel:DWORD dst_unused:UNUSED_PAD src0_sel:WORD_1 src1_sel:DWORD
	v_add3_u32 v10, v10, v14, s39
	v_add3_u32 v9, v11, v9, s39
	v_and_b32_sdwa v11, v13, v95 dst_sel:DWORD dst_unused:UNUSED_PAD src0_sel:WORD_1 src1_sel:DWORD
	v_and_b32_sdwa v14, v12, v95 dst_sel:DWORD dst_unused:UNUSED_PAD src0_sel:WORD_1 src1_sel:DWORD
	v_add3_u32 v11, v13, v11, s39
	v_add3_u32 v12, v12, v14, s39
	v_and_b32_e32 v11, 0xffff0000, v11
	v_and_b32_e32 v12, 0xffff0000, v12
	v_or_b32_sdwa v11, v11, v9 dst_sel:DWORD dst_unused:UNUSED_PAD src0_sel:DWORD src1_sel:WORD_1
	v_or_b32_sdwa v10, v12, v10 dst_sel:DWORD dst_unused:UNUSED_PAD src0_sel:DWORD src1_sel:WORD_1
	v_add_u32_e32 v9, 0x200, v8
	global_store_dwordx2 v[20:21], v[10:11], off
; DEVI float sigmoidf_(float x) { return 1.f / (1.f + __expf(-x)); }
; template <int BR, int IN, int OUT>
; DEVI void p6_branch(const Params& P, int pm, int pn, float* macc, char* smem, int tid) {
;     ...
; #pragma unroll 8
;   for (int q = 0; q < 16; ++q) {
;     const int id = tid + 256 * q, row = id >> 5, c4 = id & 31;
;     const long grow = (long)pm * 128 + row;
;     const int gcol = pn * 128 + c4 * 4;
;     float4 a = *reinterpret_cast<const float4*>(T + row * 128 + c4 * 4);
;     float g[4];
;     load4bf(Z + grow * NCOL + (9 + BR) * 1024 + gcol, g);
;     float v[4] = {sigmoidf_(g[0]) * a.x, sigmoidf_(g[1]) * a.y, sigmoidf_(g[2]) * a.z, sigmoidf_(g[3]) * a.w};
;     if (IN == 1) {
;       float mo[4]; load4bf(M + grow * 1024 + gcol, mo);
;       v[0] += mo[0]; v[1] += mo[1]; v[2] += mo[2]; v[3] += mo[3];
;     }
;     if (IN == 2) {
;       float4 mo = *reinterpret_cast<const float4*>(macc + grow * 1024 + gcol);
;       v[0] += mo.x; v[1] += mo.y; v[2] += mo.z; v[3] += mo.w;
;     }
;     if (OUT == 1) *reinterpret_cast<float4*>(macc + grow * 1024 + gcol) = make_float4(v[0], v[1], v[2], v[3]);
;     else store4bf(M + grow * 1024 + gcol, v);
;   }
	v_ashrrev_i32_e32 v10, 5, v9
	v_ashrrev_i32_e32 v11, 31, v10
	v_lshl_add_u64 v[12:13], s[40:41], 0, v[10:11]
	v_lshl_or_b32 v9, v10, 9, v152
	v_mad_u64_u32 v[10:11], s[26:27], v12, s22, v[6:7]
	v_mad_i32_i24 v11, v13, s22, v11
	v_lshl_add_u64 v[10:11], v[10:11], 0, v[4:5]
	v_add_co_u32_e32 v10, vcc, s21, v10
	s_nop 1
	v_addc_co_u32_e32 v11, vcc, 0, v11, vcc
	v_mov_b32_e32 v10, v202
	v_mov_b32_e32 v11, v203
	v_lshlrev_b32_e32 v14, 16, v10
	v_and_b32_e32 v10, 0xffff0000, v10
	v_lshlrev_b32_e32 v15, 16, v11
	v_mul_f32_e32 v10, 0xbfb8aa3b, v10
	v_mul_f32_e32 v14, 0xbfb8aa3b, v14
	v_exp_f32_e32 v16, v10
	v_mul_f32_e32 v10, 0xbfb8aa3b, v15
	v_exp_f32_e32 v14, v14
	v_exp_f32_e32 v15, v10
	v_and_b32_e32 v11, 0xffff0000, v11
	v_mul_f32_e32 v10, 0xbfb8aa3b, v11
	v_exp_f32_e32 v17, v10
	v_lshlrev_b64 v[10:11], 12, v[12:13]
	v_lshl_add_u64 v[18:19], v[0:1], 0, v[10:11]
	v_lshlrev_b64 v[10:11], 11, v[12:13]
	v_pk_add_f32 v[14:15], v[14:15], 1.0 op_sel_hi:[1,0]
	v_lshl_add_u64 v[20:21], v[2:3], 0, v[10:11]
	ds_read_b128 v[10:13], v9
	v_div_scale_f32 v9, s[26:27], v15, v15, 1.0
	v_rcp_f32_e32 v22, v9
	s_nop 0
	v_fma_f32 v23, -v9, v22, 1.0
	v_fmac_f32_e32 v22, v23, v22
	v_div_scale_f32 v23, vcc, 1.0, v15, 1.0
	v_mul_f32_e32 v24, v23, v22
	v_fma_f32 v25, -v9, v24, v23
	v_fmac_f32_e32 v24, v25, v22
	v_fma_f32 v9, -v9, v24, v23
	v_div_fmas_f32 v9, v9, v22, v24
	v_div_fixup_f32 v23, v9, v15, 1.0
	v_div_scale_f32 v9, s[26:27], v14, v14, 1.0
	v_rcp_f32_e32 v15, v9
	s_nop 0
	v_fma_f32 v22, -v9, v15, 1.0
	v_fmac_f32_e32 v15, v22, v15
	v_div_scale_f32 v22, vcc, 1.0, v14, 1.0
	v_mul_f32_e32 v24, v22, v15
	v_fma_f32 v25, -v9, v24, v22
	v_fmac_f32_e32 v24, v25, v15
	v_fma_f32 v9, -v9, v24, v22
	v_div_fmas_f32 v9, v9, v15, v24
	v_div_fixup_f32 v22, v9, v14, 1.0
	v_pk_add_f32 v[14:15], v[16:17], 1.0 op_sel_hi:[1,0]
	s_waitcnt lgkmcnt(0)
	v_mov_b32_e32 v24, v10
	v_div_scale_f32 v9, s[26:27], v15, v15, 1.0
	v_rcp_f32_e32 v10, v9
	v_mov_b32_e32 v25, v12
	v_fma_f32 v12, -v9, v10, 1.0
	v_fmac_f32_e32 v10, v12, v10
	v_div_scale_f32 v12, vcc, 1.0, v15, 1.0
	v_mul_f32_e32 v16, v12, v10
	v_fma_f32 v17, -v9, v16, v12
	v_fmac_f32_e32 v16, v17, v10
	v_fma_f32 v9, -v9, v16, v12
	v_div_fmas_f32 v9, v9, v10, v16
	v_div_fixup_f32 v27, v9, v15, 1.0
	v_div_scale_f32 v9, s[26:27], v14, v14, 1.0
	v_rcp_f32_e32 v10, v9
	s_nop 0
	v_fma_f32 v12, -v9, v10, 1.0
	v_fmac_f32_e32 v10, v12, v10
	v_div_scale_f32 v12, vcc, 1.0, v14, 1.0
	v_mul_f32_e32 v15, v12, v10
	v_fma_f32 v16, -v9, v15, v12
	v_fmac_f32_e32 v15, v16, v10
	v_fma_f32 v9, -v9, v15, v12
	v_div_fmas_f32 v9, v9, v10, v15
	v_div_fixup_f32 v26, v9, v14, 1.0
	v_mov_b32_e32 v14, v36
	v_mov_b32_e32 v15, v37
	v_mov_b32_e32 v16, v38
	v_mov_b32_e32 v17, v39
	v_mov_b32_e32 v12, v11
	v_mov_b32_e32 v10, v14
	v_mov_b32_e32 v11, v16
	v_pk_fma_f32 v[10:11], v[24:25], v[22:23], v[10:11]
	v_mov_b32_e32 v16, v15
	v_pk_fma_f32 v[12:13], v[12:13], v[26:27], v[16:17]
	v_and_b32_sdwa v9, v11, v95 dst_sel:DWORD dst_unused:UNUSED_PAD src0_sel:WORD_1 src1_sel:DWORD
	v_and_b32_sdwa v14, v10, v95 dst_sel:DWORD dst_unused:UNUSED_PAD src0_sel:WORD_1 src1_sel:DWORD
	v_add3_u32 v10, v10, v14, s39
	v_add3_u32 v9, v11, v9, s39
	v_and_b32_sdwa v11, v13, v95 dst_sel:DWORD dst_unused:UNUSED_PAD src0_sel:WORD_1 src1_sel:DWORD
	v_and_b32_sdwa v14, v12, v95 dst_sel:DWORD dst_unused:UNUSED_PAD src0_sel:WORD_1 src1_sel:DWORD
	v_add3_u32 v11, v13, v11, s39
	v_add3_u32 v12, v12, v14, s39
	v_and_b32_e32 v11, 0xffff0000, v11
	v_and_b32_e32 v12, 0xffff0000, v12
	v_or_b32_sdwa v11, v11, v9 dst_sel:DWORD dst_unused:UNUSED_PAD src0_sel:DWORD src1_sel:WORD_1
	v_or_b32_sdwa v10, v12, v10 dst_sel:DWORD dst_unused:UNUSED_PAD src0_sel:DWORD src1_sel:WORD_1
	v_add_u32_e32 v9, 0x300, v8
	global_store_dwordx2 v[20:21], v[10:11], off
	v_ashrrev_i32_e32 v10, 5, v9
	v_ashrrev_i32_e32 v11, 31, v10
	v_lshl_add_u64 v[12:13], s[40:41], 0, v[10:11]
	v_lshl_or_b32 v9, v10, 9, v152
	v_mad_u64_u32 v[10:11], s[26:27], v12, s22, v[6:7]
	v_mad_i32_i24 v11, v13, s22, v11
	v_lshl_add_u64 v[10:11], v[10:11], 0, v[4:5]
	v_add_co_u32_e32 v10, vcc, s21, v10
	s_nop 1
	v_addc_co_u32_e32 v11, vcc, 0, v11, vcc
	v_mov_b32_e32 v10, v204
	v_mov_b32_e32 v11, v205
	v_lshlrev_b32_e32 v14, 16, v10
	v_and_b32_e32 v10, 0xffff0000, v10
	v_lshlrev_b32_e32 v15, 16, v11
	v_mul_f32_e32 v10, 0xbfb8aa3b, v10
	v_mul_f32_e32 v14, 0xbfb8aa3b, v14
	v_exp_f32_e32 v16, v10
	v_mul_f32_e32 v10, 0xbfb8aa3b, v15
	v_exp_f32_e32 v14, v14
	v_exp_f32_e32 v15, v10
	v_and_b32_e32 v11, 0xffff0000, v11
	v_mul_f32_e32 v10, 0xbfb8aa3b, v11
	v_exp_f32_e32 v17, v10
	v_lshlrev_b64 v[10:11], 12, v[12:13]
	v_lshl_add_u64 v[18:19], v[0:1], 0, v[10:11]
	v_lshlrev_b64 v[10:11], 11, v[12:13]
	v_pk_add_f32 v[14:15], v[14:15], 1.0 op_sel_hi:[1,0]
	v_lshl_add_u64 v[20:21], v[2:3], 0, v[10:11]
	ds_read_b128 v[10:13], v9
	v_div_scale_f32 v9, s[26:27], v15, v15, 1.0
	v_rcp_f32_e32 v22, v9
	s_nop 0
	v_fma_f32 v23, -v9, v22, 1.0
	v_fmac_f32_e32 v22, v23, v22
	v_div_scale_f32 v23, vcc, 1.0, v15, 1.0
	v_mul_f32_e32 v24, v23, v22
	v_fma_f32 v25, -v9, v24, v23
	v_fmac_f32_e32 v24, v25, v22
	v_fma_f32 v9, -v9, v24, v23
	v_div_fmas_f32 v9, v9, v22, v24
	v_div_fixup_f32 v23, v9, v15, 1.0
	v_div_scale_f32 v9, s[26:27], v14, v14, 1.0
	v_rcp_f32_e32 v15, v9
	s_nop 0
	v_fma_f32 v22, -v9, v15, 1.0
	v_fmac_f32_e32 v15, v22, v15
	v_div_scale_f32 v22, vcc, 1.0, v14, 1.0
	v_mul_f32_e32 v24, v22, v15
	v_fma_f32 v25, -v9, v24, v22
	v_fmac_f32_e32 v24, v25, v15
	v_fma_f32 v9, -v9, v24, v22
	v_div_fmas_f32 v9, v9, v15, v24
	v_div_fixup_f32 v22, v9, v14, 1.0
	v_pk_add_f32 v[14:15], v[16:17], 1.0 op_sel_hi:[1,0]
	s_waitcnt lgkmcnt(0)
; DEVI float sigmoidf_(float x) { return 1.f / (1.f + __expf(-x)); }
; template <int BR, int IN, int OUT>
; DEVI void p6_branch(const Params& P, int pm, int pn, float* macc, char* smem, int tid) {
;     ...
; #pragma unroll 8
;   for (int q = 0; q < 16; ++q) {
;     const int id = tid + 256 * q, row = id >> 5, c4 = id & 31;
;     const long grow = (long)pm * 128 + row;
;     const int gcol = pn * 128 + c4 * 4;
;     float4 a = *reinterpret_cast<const float4*>(T + row * 128 + c4 * 4);
;     float g[4];
;     load4bf(Z + grow * NCOL + (9 + BR) * 1024 + gcol, g);
;     float v[4] = {sigmoidf_(g[0]) * a.x, sigmoidf_(g[1]) * a.y, sigmoidf_(g[2]) * a.z, sigmoidf_(g[3]) * a.w};
;     if (IN == 1) {
;       float mo[4]; load4bf(M + grow * 1024 + gcol, mo);
;       v[0] += mo[0]; v[1] += mo[1]; v[2] += mo[2]; v[3] += mo[3];
;     }
;     if (IN == 2) {
;       float4 mo = *reinterpret_cast<const float4*>(macc + grow * 1024 + gcol);
;       v[0] += mo.x; v[1] += mo.y; v[2] += mo.z; v[3] += mo.w;
;     }
;     if (OUT == 1) *reinterpret_cast<float4*>(macc + grow * 1024 + gcol) = make_float4(v[0], v[1], v[2], v[3]);
;     else store4bf(M + grow * 1024 + gcol, v);
;   }
	v_mov_b32_e32 v24, v10
	v_div_scale_f32 v9, s[26:27], v15, v15, 1.0
	v_rcp_f32_e32 v10, v9
	v_mov_b32_e32 v25, v12
	v_fma_f32 v12, -v9, v10, 1.0
	v_fmac_f32_e32 v10, v12, v10
	v_div_scale_f32 v12, vcc, 1.0, v15, 1.0
	v_mul_f32_e32 v16, v12, v10
	v_fma_f32 v17, -v9, v16, v12
	v_fmac_f32_e32 v16, v17, v10
	v_fma_f32 v9, -v9, v16, v12
	v_div_fmas_f32 v9, v9, v10, v16
	v_div_fixup_f32 v27, v9, v15, 1.0
	v_div_scale_f32 v9, s[26:27], v14, v14, 1.0
	v_rcp_f32_e32 v10, v9
	s_nop 0
	v_fma_f32 v12, -v9, v10, 1.0
	v_fmac_f32_e32 v10, v12, v10
	v_div_scale_f32 v12, vcc, 1.0, v14, 1.0
	v_mul_f32_e32 v15, v12, v10
	v_fma_f32 v16, -v9, v15, v12
	v_fmac_f32_e32 v15, v16, v10
	v_fma_f32 v9, -v9, v15, v12
	v_div_fmas_f32 v9, v9, v10, v15
	v_div_fixup_f32 v26, v9, v14, 1.0
	v_mov_b32_e32 v14, v40
	v_mov_b32_e32 v15, v41
	v_mov_b32_e32 v16, v42
	v_mov_b32_e32 v17, v43
	v_mov_b32_e32 v12, v11
	v_mov_b32_e32 v10, v14
	v_mov_b32_e32 v11, v16
	v_pk_fma_f32 v[10:11], v[24:25], v[22:23], v[10:11]
	v_mov_b32_e32 v16, v15
	v_pk_fma_f32 v[12:13], v[12:13], v[26:27], v[16:17]
	v_and_b32_sdwa v9, v11, v95 dst_sel:DWORD dst_unused:UNUSED_PAD src0_sel:WORD_1 src1_sel:DWORD
	v_and_b32_sdwa v14, v10, v95 dst_sel:DWORD dst_unused:UNUSED_PAD src0_sel:WORD_1 src1_sel:DWORD
	v_add3_u32 v10, v10, v14, s39
	v_add3_u32 v9, v11, v9, s39
	v_and_b32_sdwa v11, v13, v95 dst_sel:DWORD dst_unused:UNUSED_PAD src0_sel:WORD_1 src1_sel:DWORD
	v_and_b32_sdwa v14, v12, v95 dst_sel:DWORD dst_unused:UNUSED_PAD src0_sel:WORD_1 src1_sel:DWORD
	v_add3_u32 v11, v13, v11, s39
	v_add3_u32 v12, v12, v14, s39
	v_and_b32_e32 v11, 0xffff0000, v11
	v_and_b32_e32 v12, 0xffff0000, v12
	v_or_b32_sdwa v11, v11, v9 dst_sel:DWORD dst_unused:UNUSED_PAD src0_sel:DWORD src1_sel:WORD_1
	v_or_b32_sdwa v10, v12, v10 dst_sel:DWORD dst_unused:UNUSED_PAD src0_sel:DWORD src1_sel:WORD_1
	v_add_u32_e32 v9, 0x400, v8
	global_store_dwordx2 v[20:21], v[10:11], off
	v_ashrrev_i32_e32 v10, 5, v9
	v_ashrrev_i32_e32 v11, 31, v10
	v_lshl_add_u64 v[12:13], s[40:41], 0, v[10:11]
	v_lshl_or_b32 v9, v10, 9, v152
	v_mad_u64_u32 v[10:11], s[26:27], v12, s22, v[6:7]
	v_mad_i32_i24 v11, v13, s22, v11
	v_lshl_add_u64 v[10:11], v[10:11], 0, v[4:5]
	v_add_co_u32_e32 v10, vcc, s21, v10
	s_nop 1
	v_addc_co_u32_e32 v11, vcc, 0, v11, vcc
	v_mov_b32_e32 v10, v142
	v_mov_b32_e32 v11, v143
	v_lshlrev_b32_e32 v14, 16, v10
	v_and_b32_e32 v10, 0xffff0000, v10
	v_lshlrev_b32_e32 v15, 16, v11
	v_mul_f32_e32 v10, 0xbfb8aa3b, v10
	v_mul_f32_e32 v14, 0xbfb8aa3b, v14
	v_exp_f32_e32 v16, v10
	v_mul_f32_e32 v10, 0xbfb8aa3b, v15
	v_exp_f32_e32 v14, v14
	v_exp_f32_e32 v15, v10
	v_and_b32_e32 v11, 0xffff0000, v11
	v_mul_f32_e32 v10, 0xbfb8aa3b, v11
	v_exp_f32_e32 v17, v10
	v_lshlrev_b64 v[10:11], 12, v[12:13]
	v_lshl_add_u64 v[18:19], v[0:1], 0, v[10:11]
	v_lshlrev_b64 v[10:11], 11, v[12:13]
	v_pk_add_f32 v[14:15], v[14:15], 1.0 op_sel_hi:[1,0]
	v_lshl_add_u64 v[20:21], v[2:3], 0, v[10:11]
	ds_read_b128 v[10:13], v9
	v_div_scale_f32 v9, s[26:27], v15, v15, 1.0
	v_rcp_f32_e32 v22, v9
	s_nop 0
	v_fma_f32 v23, -v9, v22, 1.0
	v_fmac_f32_e32 v22, v23, v22
	v_div_scale_f32 v23, vcc, 1.0, v15, 1.0
	v_mul_f32_e32 v24, v23, v22
	v_fma_f32 v25, -v9, v24, v23
	v_fmac_f32_e32 v24, v25, v22
	v_fma_f32 v9, -v9, v24, v23
	v_div_fmas_f32 v9, v9, v22, v24
	v_div_fixup_f32 v23, v9, v15, 1.0
	v_div_scale_f32 v9, s[26:27], v14, v14, 1.0
	v_rcp_f32_e32 v15, v9
	s_nop 0
	v_fma_f32 v22, -v9, v15, 1.0
	v_fmac_f32_e32 v15, v22, v15
	v_div_scale_f32 v22, vcc, 1.0, v14, 1.0
	v_mul_f32_e32 v24, v22, v15
	v_fma_f32 v25, -v9, v24, v22
	v_fmac_f32_e32 v24, v25, v15
	v_fma_f32 v9, -v9, v24, v22
	v_div_fmas_f32 v9, v9, v15, v24
	v_div_fixup_f32 v22, v9, v14, 1.0
	v_pk_add_f32 v[14:15], v[16:17], 1.0 op_sel_hi:[1,0]
	s_waitcnt lgkmcnt(0)
	v_mov_b32_e32 v24, v10
	v_div_scale_f32 v9, s[26:27], v15, v15, 1.0
	v_rcp_f32_e32 v10, v9
	v_mov_b32_e32 v25, v12
	v_fma_f32 v12, -v9, v10, 1.0
	v_fmac_f32_e32 v10, v12, v10
	v_div_scale_f32 v12, vcc, 1.0, v15, 1.0
	v_mul_f32_e32 v16, v12, v10
	v_fma_f32 v17, -v9, v16, v12
	v_fmac_f32_e32 v16, v17, v10
	v_fma_f32 v9, -v9, v16, v12
	v_div_fmas_f32 v9, v9, v10, v16
	v_div_fixup_f32 v27, v9, v15, 1.0
	v_div_scale_f32 v9, s[26:27], v14, v14, 1.0
	v_rcp_f32_e32 v10, v9
	s_nop 0
	v_fma_f32 v12, -v9, v10, 1.0
	v_fmac_f32_e32 v10, v12, v10
	v_div_scale_f32 v12, vcc, 1.0, v14, 1.0
	v_mul_f32_e32 v15, v12, v10
	v_fma_f32 v16, -v9, v15, v12
	v_fmac_f32_e32 v15, v16, v10
	v_fma_f32 v9, -v9, v15, v12
	v_div_fmas_f32 v9, v9, v10, v15
	v_div_fixup_f32 v26, v9, v14, 1.0
	v_mov_b32_e32 v14, v44
	v_mov_b32_e32 v15, v45
	v_mov_b32_e32 v16, v46
	v_mov_b32_e32 v17, v47
	v_mov_b32_e32 v12, v11
	v_mov_b32_e32 v10, v14
	v_mov_b32_e32 v11, v16
	v_pk_fma_f32 v[10:11], v[24:25], v[22:23], v[10:11]
	v_mov_b32_e32 v16, v15
	v_pk_fma_f32 v[12:13], v[12:13], v[26:27], v[16:17]
	v_and_b32_sdwa v9, v11, v95 dst_sel:DWORD dst_unused:UNUSED_PAD src0_sel:WORD_1 src1_sel:DWORD
	v_and_b32_sdwa v14, v10, v95 dst_sel:DWORD dst_unused:UNUSED_PAD src0_sel:WORD_1 src1_sel:DWORD
	v_add3_u32 v10, v10, v14, s39
	v_add3_u32 v9, v11, v9, s39
	v_and_b32_sdwa v11, v13, v95 dst_sel:DWORD dst_unused:UNUSED_PAD src0_sel:WORD_1 src1_sel:DWORD
	v_and_b32_sdwa v14, v12, v95 dst_sel:DWORD dst_unused:UNUSED_PAD src0_sel:WORD_1 src1_sel:DWORD
	v_add3_u32 v11, v13, v11, s39
	v_add3_u32 v12, v12, v14, s39
	v_and_b32_e32 v11, 0xffff0000, v11
	v_and_b32_e32 v12, 0xffff0000, v12
	v_or_b32_sdwa v11, v11, v9 dst_sel:DWORD dst_unused:UNUSED_PAD src0_sel:DWORD src1_sel:WORD_1
	v_or_b32_sdwa v10, v12, v10 dst_sel:DWORD dst_unused:UNUSED_PAD src0_sel:DWORD src1_sel:WORD_1
	v_add_u32_e32 v9, 0x500, v8
; DEVI float sigmoidf_(float x) { return 1.f / (1.f + __expf(-x)); }
; template <int BR, int IN, int OUT>
; DEVI void p6_branch(const Params& P, int pm, int pn, float* macc, char* smem, int tid) {
;     ...
; #pragma unroll 8
;   for (int q = 0; q < 16; ++q) {
;     const int id = tid + 256 * q, row = id >> 5, c4 = id & 31;
;     const long grow = (long)pm * 128 + row;
;     const int gcol = pn * 128 + c4 * 4;
;     float4 a = *reinterpret_cast<const float4*>(T + row * 128 + c4 * 4);
;     float g[4];
;     load4bf(Z + grow * NCOL + (9 + BR) * 1024 + gcol, g);
;     float v[4] = {sigmoidf_(g[0]) * a.x, sigmoidf_(g[1]) * a.y, sigmoidf_(g[2]) * a.z, sigmoidf_(g[3]) * a.w};
;     if (IN == 1) {
;       float mo[4]; load4bf(M + grow * 1024 + gcol, mo);
;       v[0] += mo[0]; v[1] += mo[1]; v[2] += mo[2]; v[3] += mo[3];
;     }
;     if (IN == 2) {
;       float4 mo = *reinterpret_cast<const float4*>(macc + grow * 1024 + gcol);
;       v[0] += mo.x; v[1] += mo.y; v[2] += mo.z; v[3] += mo.w;
;     }
;     if (OUT == 1) *reinterpret_cast<float4*>(macc + grow * 1024 + gcol) = make_float4(v[0], v[1], v[2], v[3]);
;     else store4bf(M + grow * 1024 + gcol, v);
;   }
	global_store_dwordx2 v[20:21], v[10:11], off
	v_ashrrev_i32_e32 v10, 5, v9
	v_ashrrev_i32_e32 v11, 31, v10
	v_lshl_add_u64 v[12:13], s[40:41], 0, v[10:11]
	v_lshl_or_b32 v9, v10, 9, v152
	v_mad_u64_u32 v[10:11], s[26:27], v12, s22, v[6:7]
	v_mad_i32_i24 v11, v13, s22, v11
	v_lshl_add_u64 v[10:11], v[10:11], 0, v[4:5]
	v_add_co_u32_e32 v10, vcc, s21, v10
	s_nop 1
	v_addc_co_u32_e32 v11, vcc, 0, v11, vcc
	v_mov_b32_e32 v10, v144
	v_mov_b32_e32 v11, v145
	v_lshlrev_b32_e32 v14, 16, v10
	v_and_b32_e32 v10, 0xffff0000, v10
	v_lshlrev_b32_e32 v15, 16, v11
	v_mul_f32_e32 v10, 0xbfb8aa3b, v10
	v_mul_f32_e32 v14, 0xbfb8aa3b, v14
	v_exp_f32_e32 v16, v10
	v_mul_f32_e32 v10, 0xbfb8aa3b, v15
	v_exp_f32_e32 v14, v14
	v_exp_f32_e32 v15, v10
	v_and_b32_e32 v11, 0xffff0000, v11
	v_mul_f32_e32 v10, 0xbfb8aa3b, v11
	v_exp_f32_e32 v17, v10
	v_lshlrev_b64 v[10:11], 12, v[12:13]
	v_lshl_add_u64 v[18:19], v[0:1], 0, v[10:11]
	v_lshlrev_b64 v[10:11], 11, v[12:13]
	v_pk_add_f32 v[14:15], v[14:15], 1.0 op_sel_hi:[1,0]
	v_lshl_add_u64 v[20:21], v[2:3], 0, v[10:11]
	ds_read_b128 v[10:13], v9
	v_div_scale_f32 v9, s[26:27], v15, v15, 1.0
	v_rcp_f32_e32 v22, v9
	s_nop 0
	v_fma_f32 v23, -v9, v22, 1.0
	v_fmac_f32_e32 v22, v23, v22
	v_div_scale_f32 v23, vcc, 1.0, v15, 1.0
	v_mul_f32_e32 v24, v23, v22
	v_fma_f32 v25, -v9, v24, v23
	v_fmac_f32_e32 v24, v25, v22
	v_fma_f32 v9, -v9, v24, v23
	v_div_fmas_f32 v9, v9, v22, v24
	v_div_fixup_f32 v23, v9, v15, 1.0
	v_div_scale_f32 v9, s[26:27], v14, v14, 1.0
	v_rcp_f32_e32 v15, v9
	s_nop 0
	v_fma_f32 v22, -v9, v15, 1.0
	v_fmac_f32_e32 v15, v22, v15
	v_div_scale_f32 v22, vcc, 1.0, v14, 1.0
	v_mul_f32_e32 v24, v22, v15
	v_fma_f32 v25, -v9, v24, v22
	v_fmac_f32_e32 v24, v25, v15
	v_fma_f32 v9, -v9, v24, v22
	v_div_fmas_f32 v9, v9, v15, v24
	v_div_fixup_f32 v22, v9, v14, 1.0
	v_pk_add_f32 v[14:15], v[16:17], 1.0 op_sel_hi:[1,0]
	s_waitcnt lgkmcnt(0)
	v_mov_b32_e32 v24, v10
	v_div_scale_f32 v9, s[26:27], v15, v15, 1.0
	v_rcp_f32_e32 v10, v9
	v_mov_b32_e32 v25, v12
	v_fma_f32 v12, -v9, v10, 1.0
	v_fmac_f32_e32 v10, v12, v10
	v_div_scale_f32 v12, vcc, 1.0, v15, 1.0
	v_mul_f32_e32 v16, v12, v10
	v_fma_f32 v17, -v9, v16, v12
	v_fmac_f32_e32 v16, v17, v10
	v_fma_f32 v9, -v9, v16, v12
	v_div_fmas_f32 v9, v9, v10, v16
	v_div_fixup_f32 v27, v9, v15, 1.0
	v_div_scale_f32 v9, s[26:27], v14, v14, 1.0
	v_rcp_f32_e32 v10, v9
	s_nop 0
	v_fma_f32 v12, -v9, v10, 1.0
	v_fmac_f32_e32 v10, v12, v10
	v_div_scale_f32 v12, vcc, 1.0, v14, 1.0
	v_mul_f32_e32 v15, v12, v10
	v_fma_f32 v16, -v9, v15, v12
	v_fmac_f32_e32 v15, v16, v10
	v_fma_f32 v9, -v9, v15, v12
	v_div_fmas_f32 v9, v9, v10, v15
	v_div_fixup_f32 v26, v9, v14, 1.0
	v_mov_b32_e32 v14, v60
	v_mov_b32_e32 v15, v61
	v_mov_b32_e32 v16, v62
	v_mov_b32_e32 v17, v63
	v_mov_b32_e32 v12, v11
	v_mov_b32_e32 v10, v14
	v_mov_b32_e32 v11, v16
	v_pk_fma_f32 v[10:11], v[24:25], v[22:23], v[10:11]
	v_mov_b32_e32 v16, v15
	v_pk_fma_f32 v[12:13], v[12:13], v[26:27], v[16:17]
	v_and_b32_sdwa v9, v11, v95 dst_sel:DWORD dst_unused:UNUSED_PAD src0_sel:WORD_1 src1_sel:DWORD
	v_and_b32_sdwa v14, v10, v95 dst_sel:DWORD dst_unused:UNUSED_PAD src0_sel:WORD_1 src1_sel:DWORD
	v_add3_u32 v10, v10, v14, s39
	v_add3_u32 v9, v11, v9, s39
	v_and_b32_sdwa v11, v13, v95 dst_sel:DWORD dst_unused:UNUSED_PAD src0_sel:WORD_1 src1_sel:DWORD
	v_and_b32_sdwa v14, v12, v95 dst_sel:DWORD dst_unused:UNUSED_PAD src0_sel:WORD_1 src1_sel:DWORD
	v_add3_u32 v11, v13, v11, s39
	v_add3_u32 v12, v12, v14, s39
	v_and_b32_e32 v11, 0xffff0000, v11
	v_and_b32_e32 v12, 0xffff0000, v12
	v_or_b32_sdwa v11, v11, v9 dst_sel:DWORD dst_unused:UNUSED_PAD src0_sel:DWORD src1_sel:WORD_1
	v_or_b32_sdwa v10, v12, v10 dst_sel:DWORD dst_unused:UNUSED_PAD src0_sel:DWORD src1_sel:WORD_1
	v_add_u32_e32 v9, 0x600, v8
	global_store_dwordx2 v[20:21], v[10:11], off
	v_ashrrev_i32_e32 v10, 5, v9
	v_ashrrev_i32_e32 v11, 31, v10
	v_lshl_add_u64 v[12:13], s[40:41], 0, v[10:11]
	v_lshl_or_b32 v9, v10, 9, v152
	v_mad_u64_u32 v[10:11], s[26:27], v12, s22, v[6:7]
	v_mad_i32_i24 v11, v13, s22, v11
	v_lshl_add_u64 v[10:11], v[10:11], 0, v[4:5]
	v_add_co_u32_e32 v10, vcc, s21, v10
	v_add_u32_e32 v8, 0x700, v8
	s_nop 0
	v_addc_co_u32_e32 v11, vcc, 0, v11, vcc
	v_mov_b32_e32 v10, v134
	v_mov_b32_e32 v11, v135
	v_ashrrev_i32_e32 v8, 5, v8
	v_lshlrev_b32_e32 v14, 16, v10
	v_and_b32_e32 v10, 0xffff0000, v10
	v_lshlrev_b32_e32 v15, 16, v11
	v_mul_f32_e32 v10, 0xbfb8aa3b, v10
	v_mul_f32_e32 v14, 0xbfb8aa3b, v14
	v_exp_f32_e32 v16, v10
	v_mul_f32_e32 v10, 0xbfb8aa3b, v15
	v_exp_f32_e32 v14, v14
	v_exp_f32_e32 v15, v10
	v_and_b32_e32 v11, 0xffff0000, v11
	v_mul_f32_e32 v10, 0xbfb8aa3b, v11
	v_exp_f32_e32 v17, v10
	v_lshlrev_b64 v[10:11], 12, v[12:13]
	v_lshl_add_u64 v[18:19], v[0:1], 0, v[10:11]
	v_lshlrev_b64 v[10:11], 11, v[12:13]
	v_pk_add_f32 v[14:15], v[14:15], 1.0 op_sel_hi:[1,0]
	v_lshl_add_u64 v[20:21], v[2:3], 0, v[10:11]
	ds_read_b128 v[10:13], v9
	v_div_scale_f32 v9, s[26:27], v15, v15, 1.0
	v_rcp_f32_e32 v22, v9
	s_nop 0
	v_fma_f32 v23, -v9, v22, 1.0
	v_fmac_f32_e32 v22, v23, v22
	v_div_scale_f32 v23, vcc, 1.0, v15, 1.0
	v_mul_f32_e32 v24, v23, v22
	v_fma_f32 v25, -v9, v24, v23
	v_fmac_f32_e32 v24, v25, v22
	v_fma_f32 v9, -v9, v24, v23
	v_div_fmas_f32 v9, v9, v22, v24
	v_div_fixup_f32 v23, v9, v15, 1.0
	v_div_scale_f32 v9, s[26:27], v14, v14, 1.0
	v_rcp_f32_e32 v15, v9
	s_nop 0
	v_fma_f32 v22, -v9, v15, 1.0
	v_fmac_f32_e32 v15, v22, v15
	v_div_scale_f32 v22, vcc, 1.0, v14, 1.0
	v_mul_f32_e32 v24, v22, v15
	v_fma_f32 v25, -v9, v24, v22
	v_fmac_f32_e32 v24, v25, v15
	v_fma_f32 v9, -v9, v24, v22
	v_div_fmas_f32 v9, v9, v15, v24
	v_div_fixup_f32 v22, v9, v14, 1.0
	v_pk_add_f32 v[14:15], v[16:17], 1.0 op_sel_hi:[1,0]
	s_waitcnt lgkmcnt(0)
; DEVI float sigmoidf_(float x) { return 1.f / (1.f + __expf(-x)); }
; DEVI char* wsp(const Params& P, size_t off) { asm volatile("" : "+s"(off)); return P.ws + off; }
; template <int BR, int IN, int OUT>
; DEVI void p6_branch(const Params& P, int pm, int pn, float* macc, char* smem, int tid) {
;     ...
; #pragma unroll 8
;   for (int q = 0; q < 16; ++q) {
;     const int id = tid + 256 * q, row = id >> 5, c4 = id & 31;
;     const long grow = (long)pm * 128 + row;
;     const int gcol = pn * 128 + c4 * 4;
;     float4 a = *reinterpret_cast<const float4*>(T + row * 128 + c4 * 4);
;     float g[4];
;     load4bf(Z + grow * NCOL + (9 + BR) * 1024 + gcol, g);
;     float v[4] = {sigmoidf_(g[0]) * a.x, sigmoidf_(g[1]) * a.y, sigmoidf_(g[2]) * a.z, sigmoidf_(g[3]) * a.w};
;     if (IN == 1) {
;       float mo[4]; load4bf(M + grow * 1024 + gcol, mo);
;       v[0] += mo[0]; v[1] += mo[1]; v[2] += mo[2]; v[3] += mo[3];
;     }
;     if (IN == 2) {
;       float4 mo = *reinterpret_cast<const float4*>(macc + grow * 1024 + gcol);
;       v[0] += mo.x; v[1] += mo.y; v[2] += mo.z; v[3] += mo.w;
;     }
;     if (OUT == 1) *reinterpret_cast<float4*>(macc + grow * 1024 + gcol) = make_float4(v[0], v[1], v[2], v[3]);
;     else store4bf(M + grow * 1024 + gcol, v);
;   }
; DEVI void phase6(const Params& P, int l, int pass, char* smem) {
;     ...
;   for (int id = blockIdx.x; id < nM * nN; id += gridDim.x) {
;     int pm, pn; tile_rc_m(id, nM, nN, pm, pn);
;     float* macc = (float*)wsp(P, O_AU);
;     p6_branch<2, 1, 1>(P, pm, pn, macc, smem, tid);
;     p6_branch<1, 2, 0>(P, pm, pn, macc, smem, tid);
	v_mov_b32_e32 v24, v10
	v_div_scale_f32 v9, s[26:27], v15, v15, 1.0
	v_rcp_f32_e32 v10, v9
	v_mov_b32_e32 v25, v12
	v_fma_f32 v12, -v9, v10, 1.0
	v_fmac_f32_e32 v10, v12, v10
	v_div_scale_f32 v12, vcc, 1.0, v15, 1.0
	v_mul_f32_e32 v16, v12, v10
	v_fma_f32 v17, -v9, v16, v12
	v_fmac_f32_e32 v16, v17, v10
	v_fma_f32 v9, -v9, v16, v12
	v_div_fmas_f32 v9, v9, v10, v16
	v_div_fixup_f32 v27, v9, v15, 1.0
	v_div_scale_f32 v9, s[26:27], v14, v14, 1.0
	v_rcp_f32_e32 v10, v9
	s_nop 0
	v_fma_f32 v12, -v9, v10, 1.0
	v_fmac_f32_e32 v10, v12, v10
	v_div_scale_f32 v12, vcc, 1.0, v14, 1.0
	v_mul_f32_e32 v15, v12, v10
	v_fma_f32 v16, -v9, v15, v12
	v_fmac_f32_e32 v15, v16, v10
	v_fma_f32 v9, -v9, v15, v12
	v_div_fmas_f32 v9, v9, v10, v15
	v_div_fixup_f32 v26, v9, v14, 1.0
	v_mov_b32_e32 v14, v124
	v_mov_b32_e32 v15, v125
	v_mov_b32_e32 v16, v126
	v_mov_b32_e32 v17, v127
	v_mov_b32_e32 v12, v11
	v_mov_b32_e32 v10, v14
	v_mov_b32_e32 v11, v16
	v_pk_fma_f32 v[10:11], v[24:25], v[22:23], v[10:11]
	v_mov_b32_e32 v16, v15
	v_pk_fma_f32 v[12:13], v[12:13], v[26:27], v[16:17]
	v_and_b32_sdwa v9, v11, v95 dst_sel:DWORD dst_unused:UNUSED_PAD src0_sel:WORD_1 src1_sel:DWORD
	v_and_b32_sdwa v14, v10, v95 dst_sel:DWORD dst_unused:UNUSED_PAD src0_sel:WORD_1 src1_sel:DWORD
	v_add3_u32 v10, v10, v14, s39
	v_add3_u32 v9, v11, v9, s39
	v_and_b32_sdwa v11, v13, v95 dst_sel:DWORD dst_unused:UNUSED_PAD src0_sel:WORD_1 src1_sel:DWORD
	v_and_b32_sdwa v14, v12, v95 dst_sel:DWORD dst_unused:UNUSED_PAD src0_sel:WORD_1 src1_sel:DWORD
	v_add3_u32 v11, v13, v11, s39
	v_add3_u32 v12, v12, v14, s39
	v_and_b32_e32 v11, 0xffff0000, v11
	v_and_b32_e32 v12, 0xffff0000, v12
	v_or_b32_sdwa v11, v11, v9 dst_sel:DWORD dst_unused:UNUSED_PAD src0_sel:DWORD src1_sel:WORD_1
	v_or_b32_sdwa v10, v12, v10 dst_sel:DWORD dst_unused:UNUSED_PAD src0_sel:DWORD src1_sel:WORD_1
	v_ashrrev_i32_e32 v9, 31, v8
	global_store_dwordx2 v[20:21], v[10:11], off
	v_lshl_add_u64 v[10:11], s[40:41], 0, v[8:9]
	v_mad_u64_u32 v[6:7], s[26:27], v10, s22, v[6:7]
	v_mad_i32_i24 v7, v11, s22, v7
	v_lshl_add_u64 v[6:7], v[6:7], 0, v[4:5]
	v_add_co_u32_e32 v6, vcc, s21, v6
	v_lshl_or_b32 v8, v8, 9, v152
	s_nop 0
	v_addc_co_u32_e32 v7, vcc, 0, v7, vcc
	v_mov_b32_e32 v6, v138
	v_mov_b32_e32 v7, v139
	v_lshlrev_b32_e32 v9, 16, v6
	v_and_b32_e32 v6, 0xffff0000, v6
	v_lshlrev_b32_e32 v13, 16, v7
	v_mul_f32_e32 v6, 0xbfb8aa3b, v6
	v_mul_f32_e32 v9, 0xbfb8aa3b, v9
	v_exp_f32_e32 v14, v6
	v_mul_f32_e32 v6, 0xbfb8aa3b, v13
	v_exp_f32_e32 v12, v9
	v_exp_f32_e32 v13, v6
	v_and_b32_e32 v7, 0xffff0000, v7
	v_mul_f32_e32 v6, 0xbfb8aa3b, v7
	v_exp_f32_e32 v15, v6
	v_lshlrev_b64 v[6:7], 12, v[10:11]
	v_lshl_add_u64 v[16:17], v[0:1], 0, v[6:7]
	v_lshlrev_b64 v[6:7], 11, v[10:11]
	v_pk_add_f32 v[10:11], v[12:13], 1.0 op_sel_hi:[1,0]
	v_lshl_add_u64 v[18:19], v[2:3], 0, v[6:7]
	v_div_scale_f32 v12, s[26:27], v11, v11, 1.0
	v_rcp_f32_e32 v13, v12
	ds_read_b128 v[6:9], v8
	v_fma_f32 v20, -v12, v13, 1.0
	v_fmac_f32_e32 v13, v20, v13
	v_div_scale_f32 v20, vcc, 1.0, v11, 1.0
	v_mul_f32_e32 v21, v20, v13
	v_fma_f32 v22, -v12, v21, v20
	v_fmac_f32_e32 v21, v22, v13
	v_fma_f32 v12, -v12, v21, v20
	v_div_fmas_f32 v12, v12, v13, v21
	v_div_fixup_f32 v21, v12, v11, 1.0
	v_div_scale_f32 v11, s[26:27], v10, v10, 1.0
	v_rcp_f32_e32 v12, v11
	s_waitcnt lgkmcnt(0)
	v_mov_b32_e32 v23, v8
	v_fma_f32 v13, -v11, v12, 1.0
	v_fmac_f32_e32 v12, v13, v12
	v_div_scale_f32 v13, vcc, 1.0, v10, 1.0
	v_mul_f32_e32 v20, v13, v12
	v_fma_f32 v22, -v11, v20, v13
	v_fmac_f32_e32 v20, v22, v12
	v_fma_f32 v11, -v11, v20, v13
	v_div_fmas_f32 v11, v11, v12, v20
	v_div_fixup_f32 v20, v11, v10, 1.0
	v_pk_add_f32 v[10:11], v[14:15], 1.0 op_sel_hi:[1,0]
	v_mov_b32_e32 v22, v6
	v_div_scale_f32 v6, s[26:27], v11, v11, 1.0
	v_rcp_f32_e32 v8, v6
	s_nop 0
	v_fma_f32 v12, -v6, v8, 1.0
	v_fmac_f32_e32 v8, v12, v8
	v_div_scale_f32 v12, vcc, 1.0, v11, 1.0
	v_mul_f32_e32 v13, v12, v8
	v_fma_f32 v14, -v6, v13, v12
	v_fmac_f32_e32 v13, v14, v8
	v_fma_f32 v6, -v6, v13, v12
	v_div_fmas_f32 v6, v6, v8, v13
	v_div_fixup_f32 v15, v6, v11, 1.0
	v_div_scale_f32 v6, s[26:27], v10, v10, 1.0
	v_rcp_f32_e32 v8, v6
	s_nop 0
	v_fma_f32 v11, -v6, v8, 1.0
	v_fmac_f32_e32 v8, v11, v8
	v_div_scale_f32 v11, vcc, 1.0, v10, 1.0
	v_mul_f32_e32 v12, v11, v8
	v_fma_f32 v13, -v6, v12, v11
	v_fmac_f32_e32 v12, v13, v8
	v_fma_f32 v6, -v6, v12, v11
	v_div_fmas_f32 v6, v6, v8, v12
	v_div_fixup_f32 v14, v6, v10, 1.0
	v_mov_b32_e32 v10, v128
	v_mov_b32_e32 v11, v129
	v_mov_b32_e32 v12, v130
	v_mov_b32_e32 v13, v131
	v_mov_b32_e32 v8, v7
	v_mov_b32_e32 v6, v10
	v_mov_b32_e32 v7, v12
	v_pk_fma_f32 v[6:7], v[22:23], v[20:21], v[6:7]
	v_mov_b32_e32 v12, v11
	v_pk_fma_f32 v[8:9], v[8:9], v[14:15], v[12:13]
	v_and_b32_sdwa v10, v7, v95 dst_sel:DWORD dst_unused:UNUSED_PAD src0_sel:WORD_1 src1_sel:DWORD
	v_and_b32_sdwa v11, v6, v95 dst_sel:DWORD dst_unused:UNUSED_PAD src0_sel:WORD_1 src1_sel:DWORD
	v_add3_u32 v6, v6, v11, s39
	v_add3_u32 v7, v7, v10, s39
	v_and_b32_sdwa v10, v9, v95 dst_sel:DWORD dst_unused:UNUSED_PAD src0_sel:WORD_1 src1_sel:DWORD
	v_and_b32_sdwa v11, v8, v95 dst_sel:DWORD dst_unused:UNUSED_PAD src0_sel:WORD_1 src1_sel:DWORD
	v_add3_u32 v9, v9, v10, s39
	v_add3_u32 v8, v8, v11, s39
	v_and_b32_e32 v9, 0xffff0000, v9
	v_and_b32_e32 v8, 0xffff0000, v8
	v_or_b32_sdwa v7, v9, v7 dst_sel:DWORD dst_unused:UNUSED_PAD src0_sel:DWORD src1_sel:WORD_1
	v_or_b32_sdwa v6, v8, v6 dst_sel:DWORD dst_unused:UNUSED_PAD src0_sel:DWORD src1_sel:WORD_1
	global_store_dwordx2 v[18:19], v[6:7], off
	s_cbranch_scc1 .LBB0_741
	s_add_i32 s2, s2, s23
	s_cmp_lt_i32 s2, s1
	s_cbranch_scc1 .LBB0_730
